# P2 conv: tap weights staged once per workgroup in LDS (ds_read_b128, counted lgkmcnt), task-range guard
# baseline (speedup 1.0000x reference)
.Lcv_pre_skip2:
	s_waitcnt lgkmcnt(0)
	s_barrier
	v_readlane_b32 s0, v254, 41
	s_cmpk_gt_i32 s0, 0xfff
	s_cbranch_scc1 .LBB0_280
	v_mov_b32_e32 v86, 0
	v_readlane_b32 s4, v254, 23
	v_lshlrev_b32_e32 v2, 4, v199
	v_mov_b32_e32 v3, v86
	v_readlane_b32 s5, v254, 24
	v_mbcnt_lo_u32_b32 v1, -1, 0
	v_lshl_add_u64 v[88:89], s[64:65], 0, v[2:3]
	v_lshl_add_u64 v[92:93], s[62:63], 0, v[2:3]
	v_lshl_add_u64 v[94:95], s[66:67], 0, v[2:3]
	v_lshl_add_u64 v[96:97], s[4:5], 0, v[2:3]
	v_mbcnt_hi_u32_b32 v2, -1, v1
	v_and_b32_e32 v1, 64, v2
	v_add_u32_e32 v3, 64, v1
	v_xor_b32_e32 v1, 1, v2
	v_cmp_lt_i32_e32 vcc, v1, v3
	v_xor_b32_e32 v6, 2, v2
	v_readlane_b32 s1, v254, 40
	v_cndmask_b32_e32 v1, v2, v1, vcc
	v_cmp_lt_i32_e32 vcc, v6, v3
	s_lshl_b32 s0, s80, 5
	s_lshl_b32 s1, s1, 2
	v_cndmask_b32_e32 v6, v2, v6, vcc
	v_lshlrev_b32_e32 v162, 2, v6
	v_xor_b32_e32 v6, 4, v2
	v_cmp_lt_i32_e32 vcc, v6, v3
	v_lshlrev_b32_e32 v4, 3, v199
	v_mov_b32_e32 v5, v86
	v_cndmask_b32_e32 v6, v2, v6, vcc
	v_lshlrev_b32_e32 v163, 2, v6
	v_xor_b32_e32 v6, 8, v2
	v_cmp_lt_i32_e32 vcc, v6, v3
	v_readlane_b32 s8, v254, 27
	v_readlane_b32 s9, v254, 28
	v_cndmask_b32_e32 v6, v2, v6, vcc
	v_lshlrev_b32_e32 v164, 2, v6
	v_xor_b32_e32 v6, 16, v2
	v_cmp_lt_i32_e32 vcc, v6, v3
	v_readlane_b32 s10, v254, 29
	v_readlane_b32 s11, v254, 30
	v_cndmask_b32_e32 v6, v2, v6, vcc
	v_lshlrev_b32_e32 v165, 2, v6
	v_xor_b32_e32 v6, 32, v2
	v_cmp_lt_i32_e32 vcc, v6, v3
	v_readlane_b32 s12, v254, 31
	v_readlane_b32 s13, v254, 32
	v_readlane_b32 s14, v254, 33
	v_readlane_b32 s15, v254, 34
	v_cndmask_b32_e32 v2, v2, v6, vcc
	s_add_i32 s0, s0, s1
	v_lshl_add_u64 v[90:91], s[38:39], 0, v[4:5]
	v_lshlrev_b32_e32 v1, 2, v1
	v_lshlrev_b32_e32 v166, 2, v2
	v_lshl_add_u64 v[98:99], s[44:45], 0, v[4:5]
	s_sub_i32 s8, s0, 27
	s_lshl_b32 s9, s33, 5
	v_mov_b32_e32 v167, 0x600
	s_movk_i32 s10, 0x1000
	s_movk_i32 s11, 0x2000
	s_movk_i32 s12, 0x3000
	s_movk_i32 s13, 0x4000
	s_movk_i32 s14, 0x5000
	v_mov_b32_e32 v168, 0x3727c5ac
	v_readlane_b32 s15, v254, 41
	v_readlane_b32 s6, v254, 25
	v_readlane_b32 s7, v254, 26
	v_readlane_b32 s16, v254, 35
	v_readlane_b32 s17, v254, 36
	v_readlane_b32 s18, v254, 37
	v_readlane_b32 s19, v254, 38
	v_readlane_b32 s40, v254, 41
	v_readlane_b32 s42, v254, 23
	v_readlane_b32 s43, v254, 24
	v_lshlrev_b32_e32 v2, 4, v199
	v_lshlrev_b32_e32 v3, 3, v199
	s_cmpk_gt_u32 s40, 0x7ff
	s_cbranch_scc1 .LBB0_280
	s_lshl_b32 s41, s40, 3
	s_mov_b64 s[50:51], s[62:63]
	v_add_u32_e32 v208, 0x10000, v2
	global_load_dwordx4 v[222:225], v2, s[64:65]
	global_load_dwordx4 v[226:229], v2, s[64:65] offset:1024
	global_load_dwordx4 v[230:233], v2, s[64:65] offset:2048
	s_add_i32 s52, s41, -30
	s_max_i32 s52, s52, 0
	s_mulk_i32 s52, 0x600
	v_add_u32_e32 v196, s52, v3
	global_load_dwordx2 v[234:235], v196, s[38:39]
	global_load_dwordx2 v[236:237], v196, s[38:39] offset:512
	global_load_dwordx2 v[238:239], v196, s[38:39] offset:1024
	s_add_i32 s52, s41, -29
	s_max_i32 s52, s52, 0
	s_mulk_i32 s52, 0x600
	v_add_u32_e32 v196, s52, v3
	global_load_dwordx2 v[240:241], v196, s[38:39]
	global_load_dwordx2 v[242:243], v196, s[38:39] offset:512
	global_load_dwordx2 v[244:245], v196, s[38:39] offset:1024
	s_add_i32 s52, s41, -28
	s_max_i32 s52, s52, 0
	s_mulk_i32 s52, 0x600
	v_add_u32_e32 v196, s52, v3
	global_load_dwordx2 v[246:247], v196, s[38:39]
	global_load_dwordx2 v[248:249], v196, s[38:39] offset:512
	global_load_dwordx2 v[250:251], v196, s[38:39] offset:1024
	s_add_i32 s52, s41, -27
	s_max_i32 s52, s52, 0
	s_mulk_i32 s52, 0x600
	v_add_u32_e32 v196, s52, v3
	global_load_dwordx2 v[204:205], v196, s[38:39]
	global_load_dwordx2 v[206:207], v196, s[38:39] offset:512
	global_load_dwordx2 v[252:253], v196, s[38:39] offset:1024
	s_add_i32 s52, s41, -26
	s_max_i32 s52, s52, 0
	s_mulk_i32 s52, 0x600
	v_add_u32_e32 v196, s52, v3
	global_load_dwordx2 v[154:155], v196, s[38:39]
	global_load_dwordx2 v[156:157], v196, s[38:39] offset:512
	global_load_dwordx2 v[158:159], v196, s[38:39] offset:1024
	s_add_i32 s52, s41, -25
	s_max_i32 s52, s52, 0
	s_mulk_i32 s52, 0x600
	v_add_u32_e32 v196, s52, v3
	global_load_dwordx2 v[166:167], v196, s[38:39]
	global_load_dwordx2 v[168:169], v196, s[38:39] offset:512
	global_load_dwordx2 v[170:171], v196, s[38:39] offset:1024
	s_add_i32 s52, s41, -24
	s_max_i32 s52, s52, 0
	s_mulk_i32 s52, 0x600
	v_add_u32_e32 v196, s52, v3
	global_load_dwordx2 v[178:179], v196, s[38:39]
	global_load_dwordx2 v[180:181], v196, s[38:39] offset:512
	global_load_dwordx2 v[182:183], v196, s[38:39] offset:1024
	s_add_i32 s52, s41, -23
	s_max_i32 s52, s52, 0
	s_mulk_i32 s52, 0x600
	v_add_u32_e32 v196, s52, v3
	global_load_dwordx2 v[190:191], v196, s[38:39]
	global_load_dwordx2 v[192:193], v196, s[38:39] offset:512
	global_load_dwordx2 v[194:195], v196, s[38:39] offset:1024
	ds_read_b128 v[210:213], v2
	ds_read_b128 v[214:217], v2 offset:1024
	ds_read_b128 v[218:221], v2 offset:2048
	s_waitcnt vmcnt(24)
	v_mov_b32_e32 v4, v222
	v_mov_b32_e32 v5, v223
	v_mov_b32_e32 v6, v224
	v_mov_b32_e32 v7, v225
	v_mov_b32_e32 v8, v226
	v_mov_b32_e32 v9, v227
	v_mov_b32_e32 v10, v228
	v_mov_b32_e32 v11, v229
	v_mov_b32_e32 v12, v230
	v_mov_b32_e32 v13, v231
	v_mov_b32_e32 v14, v232
	v_mov_b32_e32 v15, v233
	v_mov_b32_e32 v16, v222
	v_mov_b32_e32 v17, v223
	v_mov_b32_e32 v18, v224
	v_mov_b32_e32 v19, v225
	v_mov_b32_e32 v20, v226
	v_mov_b32_e32 v21, v227
	v_mov_b32_e32 v22, v228
	v_mov_b32_e32 v23, v229
	v_mov_b32_e32 v24, v230
	v_mov_b32_e32 v25, v231
	v_mov_b32_e32 v26, v232
	v_mov_b32_e32 v27, v233
	v_mov_b32_e32 v28, v222
	v_mov_b32_e32 v29, v223
	v_mov_b32_e32 v30, v224
	v_mov_b32_e32 v31, v225
	v_mov_b32_e32 v32, v226
	v_mov_b32_e32 v33, v227
	v_mov_b32_e32 v34, v228
	v_mov_b32_e32 v35, v229
	v_mov_b32_e32 v36, v230
	v_mov_b32_e32 v37, v231
	v_mov_b32_e32 v38, v232
	v_mov_b32_e32 v39, v233
	v_mov_b32_e32 v40, v222
	v_mov_b32_e32 v41, v223
	v_mov_b32_e32 v42, v224
	v_mov_b32_e32 v43, v225
	v_mov_b32_e32 v44, v226
	v_mov_b32_e32 v45, v227
	v_mov_b32_e32 v46, v228
	v_mov_b32_e32 v47, v229
	v_mov_b32_e32 v48, v230
	v_mov_b32_e32 v49, v231
	v_mov_b32_e32 v50, v232
	v_mov_b32_e32 v51, v233
	v_mov_b32_e32 v52, v222
	v_mov_b32_e32 v53, v223
	v_mov_b32_e32 v54, v224
	v_mov_b32_e32 v55, v225
	v_mov_b32_e32 v56, v226
	v_mov_b32_e32 v57, v227
	v_mov_b32_e32 v58, v228
	v_mov_b32_e32 v59, v229
	v_mov_b32_e32 v60, v230
	v_mov_b32_e32 v61, v231
	v_mov_b32_e32 v62, v232
	v_mov_b32_e32 v63, v233
	v_mov_b32_e32 v64, v222
	v_mov_b32_e32 v65, v223
	v_mov_b32_e32 v66, v224
	v_mov_b32_e32 v67, v225
	v_mov_b32_e32 v68, v226
	v_mov_b32_e32 v69, v227
	v_mov_b32_e32 v70, v228
	v_mov_b32_e32 v71, v229
	v_mov_b32_e32 v72, v230
	v_mov_b32_e32 v73, v231
	v_mov_b32_e32 v74, v232
	v_mov_b32_e32 v75, v233
	v_mov_b32_e32 v76, v222
	v_mov_b32_e32 v77, v223
	v_mov_b32_e32 v78, v224
	v_mov_b32_e32 v79, v225
	v_mov_b32_e32 v80, v226
	v_mov_b32_e32 v81, v227
	v_mov_b32_e32 v82, v228
	v_mov_b32_e32 v83, v229
	v_mov_b32_e32 v84, v230
	v_mov_b32_e32 v85, v231
	v_mov_b32_e32 v86, v232
	v_mov_b32_e32 v87, v233
	v_mov_b32_e32 v88, v222
	v_mov_b32_e32 v89, v223
	v_mov_b32_e32 v90, v224
	v_mov_b32_e32 v91, v225
	v_mov_b32_e32 v92, v226
	v_mov_b32_e32 v93, v227
	v_mov_b32_e32 v94, v228
	v_mov_b32_e32 v95, v229
	v_mov_b32_e32 v96, v230
	v_mov_b32_e32 v97, v231
	v_mov_b32_e32 v98, v232
	v_mov_b32_e32 v99, v233
	ds_read_b128 v[222:225], v2 offset:3072
	ds_read_b128 v[226:229], v2 offset:4096
	ds_read_b128 v[230:233], v2 offset:5120
	s_waitcnt vmcnt(21)
	s_add_i32 s52, s41, -30
	s_cmp_lt_i32 s52, 0
	s_cbranch_scc1 .Lcv_z0_zero
	v_lshlrev_b32_e32 v100, 16, v234
	v_and_b32_e32 v101, 0xffff0000, v234
	v_lshlrev_b32_e32 v102, 16, v235
	v_and_b32_e32 v103, 0xffff0000, v235
	v_lshlrev_b32_e32 v104, 16, v236
	v_and_b32_e32 v105, 0xffff0000, v236
	v_lshlrev_b32_e32 v106, 16, v237
	v_and_b32_e32 v107, 0xffff0000, v237
	v_lshlrev_b32_e32 v108, 16, v238
	v_and_b32_e32 v109, 0xffff0000, v238
	v_lshlrev_b32_e32 v110, 16, v239
	v_and_b32_e32 v111, 0xffff0000, v239
	s_branch .Lcv_z0_done

.Lcv_z0_done:
	s_add_i32 s52, s41, -22
	s_max_i32 s52, s52, 0
	s_mulk_i32 s52, 0x600
	v_add_u32_e32 v196, s52, v3
	global_load_dwordx2 v[234:235], v196, s[38:39]
	global_load_dwordx2 v[236:237], v196, s[38:39] offset:512
	global_load_dwordx2 v[238:239], v196, s[38:39] offset:1024
	s_waitcnt vmcnt(21)
	s_add_i32 s52, s41, -29
	s_cmp_lt_i32 s52, 0
	s_cbranch_scc1 .Lcv_z1_zero
	v_lshlrev_b32_e32 v112, 16, v240
	v_and_b32_e32 v113, 0xffff0000, v240
	v_lshlrev_b32_e32 v114, 16, v241
	v_and_b32_e32 v115, 0xffff0000, v241
	v_lshlrev_b32_e32 v116, 16, v242
	v_and_b32_e32 v117, 0xffff0000, v242
	v_lshlrev_b32_e32 v118, 16, v243
	v_and_b32_e32 v119, 0xffff0000, v243
	v_lshlrev_b32_e32 v120, 16, v244
	v_and_b32_e32 v121, 0xffff0000, v244
	v_lshlrev_b32_e32 v122, 16, v245
	v_and_b32_e32 v123, 0xffff0000, v245
	s_branch .Lcv_z1_done

.Lcv_z1_done:
	s_add_i32 s52, s41, -21
	s_max_i32 s52, s52, 0
	s_mulk_i32 s52, 0x600
	v_add_u32_e32 v196, s52, v3
	global_load_dwordx2 v[240:241], v196, s[38:39]
	global_load_dwordx2 v[242:243], v196, s[38:39] offset:512
	global_load_dwordx2 v[244:245], v196, s[38:39] offset:1024
	s_waitcnt vmcnt(21)
	s_add_i32 s52, s41, -28
	s_cmp_lt_i32 s52, 0
	s_cbranch_scc1 .Lcv_z2_zero
	v_lshlrev_b32_e32 v124, 16, v246
	v_and_b32_e32 v125, 0xffff0000, v246
	v_lshlrev_b32_e32 v126, 16, v247
	v_and_b32_e32 v127, 0xffff0000, v247
	v_lshlrev_b32_e32 v128, 16, v248
	v_and_b32_e32 v129, 0xffff0000, v248
	v_lshlrev_b32_e32 v130, 16, v249
	v_and_b32_e32 v131, 0xffff0000, v249
	v_lshlrev_b32_e32 v132, 16, v250
	v_and_b32_e32 v133, 0xffff0000, v250
	v_lshlrev_b32_e32 v134, 16, v251
	v_and_b32_e32 v135, 0xffff0000, v251
	s_branch .Lcv_z2_done

.Lcv_z2_done:
	s_add_i32 s52, s41, -20
	s_max_i32 s52, s52, 0
	s_mulk_i32 s52, 0x600
	v_add_u32_e32 v196, s52, v3
	global_load_dwordx2 v[246:247], v196, s[38:39]
	global_load_dwordx2 v[248:249], v196, s[38:39] offset:512
	global_load_dwordx2 v[250:251], v196, s[38:39] offset:1024
	s_waitcnt vmcnt(21)
	s_add_i32 s52, s41, -27
	s_cmp_lt_i32 s52, 0
	s_cbranch_scc1 .Lcv_z3_zero
	v_lshlrev_b32_e32 v136, 16, v204
	v_and_b32_e32 v137, 0xffff0000, v204
	v_lshlrev_b32_e32 v138, 16, v205
	v_and_b32_e32 v139, 0xffff0000, v205
	v_lshlrev_b32_e32 v140, 16, v206
	v_and_b32_e32 v141, 0xffff0000, v206
	v_lshlrev_b32_e32 v142, 16, v207
	v_and_b32_e32 v143, 0xffff0000, v207
	v_lshlrev_b32_e32 v144, 16, v252
	v_and_b32_e32 v145, 0xffff0000, v252
	v_lshlrev_b32_e32 v146, 16, v253
	v_and_b32_e32 v147, 0xffff0000, v253
	s_branch .Lcv_z3_done

.Lcv_z3_done:
	s_add_i32 s52, s41, -19
	s_max_i32 s52, s52, 0
	s_mulk_i32 s52, 0x600
	v_add_u32_e32 v196, s52, v3
	global_load_dwordx2 v[204:205], v196, s[38:39]
	global_load_dwordx2 v[206:207], v196, s[38:39] offset:512
	global_load_dwordx2 v[252:253], v196, s[38:39] offset:1024
	s_waitcnt vmcnt(21)
	s_add_i32 s52, s41, -26
	s_cmp_lt_i32 s52, 0
	s_cbranch_scc1 .Lcv_z4_zero
	v_lshlrev_b32_e32 v148, 16, v154
	v_and_b32_e32 v149, 0xffff0000, v154
	v_lshlrev_b32_e32 v150, 16, v155
	v_and_b32_e32 v151, 0xffff0000, v155
	v_lshlrev_b32_e32 v152, 16, v156
	v_and_b32_e32 v153, 0xffff0000, v156
	v_lshlrev_b32_e32 v154, 16, v157
	v_and_b32_e32 v155, 0xffff0000, v157
	v_lshlrev_b32_e32 v156, 16, v158
	v_and_b32_e32 v157, 0xffff0000, v158
	v_lshlrev_b32_e32 v158, 16, v159
	v_and_b32_e32 v159, 0xffff0000, v159
	s_branch .Lcv_z4_done

.Lcv_z4_done:
	s_waitcnt vmcnt(18)
	s_add_i32 s52, s41, -25
	s_cmp_lt_i32 s52, 0
	s_cbranch_scc1 .Lcv_z5_zero
	v_lshlrev_b32_e32 v160, 16, v166
	v_and_b32_e32 v161, 0xffff0000, v166
	v_lshlrev_b32_e32 v162, 16, v167
	v_and_b32_e32 v163, 0xffff0000, v167
	v_lshlrev_b32_e32 v164, 16, v168
	v_and_b32_e32 v165, 0xffff0000, v168
	v_lshlrev_b32_e32 v166, 16, v169
	v_and_b32_e32 v167, 0xffff0000, v169
	v_lshlrev_b32_e32 v168, 16, v170
	v_and_b32_e32 v169, 0xffff0000, v170
	v_lshlrev_b32_e32 v170, 16, v171
	v_and_b32_e32 v171, 0xffff0000, v171
	s_branch .Lcv_z5_done

.Lcv_z5_done:
	s_waitcnt vmcnt(15)
	s_add_i32 s52, s41, -24
	s_cmp_lt_i32 s52, 0
	s_cbranch_scc1 .Lcv_z6_zero
	v_lshlrev_b32_e32 v172, 16, v178
	v_and_b32_e32 v173, 0xffff0000, v178
	v_lshlrev_b32_e32 v174, 16, v179
	v_and_b32_e32 v175, 0xffff0000, v179
	v_lshlrev_b32_e32 v176, 16, v180
	v_and_b32_e32 v177, 0xffff0000, v180
	v_lshlrev_b32_e32 v178, 16, v181
	v_and_b32_e32 v179, 0xffff0000, v181
	v_lshlrev_b32_e32 v180, 16, v182
	v_and_b32_e32 v181, 0xffff0000, v182
	v_lshlrev_b32_e32 v182, 16, v183
	v_and_b32_e32 v183, 0xffff0000, v183
	s_branch .Lcv_z6_done

.Lcv_z6_done:
	s_waitcnt vmcnt(12)
	s_add_i32 s52, s41, -23
	s_cmp_lt_i32 s52, 0
	s_cbranch_scc1 .Lcv_z7_zero
	v_lshlrev_b32_e32 v184, 16, v190
	v_and_b32_e32 v185, 0xffff0000, v190
	v_lshlrev_b32_e32 v186, 16, v191
	v_and_b32_e32 v187, 0xffff0000, v191
	v_lshlrev_b32_e32 v188, 16, v192
	v_and_b32_e32 v189, 0xffff0000, v192
	v_lshlrev_b32_e32 v190, 16, v193
	v_and_b32_e32 v191, 0xffff0000, v193
	v_lshlrev_b32_e32 v192, 16, v194
	v_and_b32_e32 v193, 0xffff0000, v194
	v_lshlrev_b32_e32 v194, 16, v195
	v_and_b32_e32 v195, 0xffff0000, v195
	s_branch .Lcv_z7_done

.Lcv_z7_done:
	s_waitcnt lgkmcnt(3)
	v_pk_fma_f32 v[4:5], v[100:101], v[210:211], v[4:5]
	v_pk_fma_f32 v[6:7], v[102:103], v[212:213], v[6:7]
	v_pk_fma_f32 v[8:9], v[104:105], v[214:215], v[8:9]
	v_pk_fma_f32 v[10:11], v[106:107], v[216:217], v[10:11]
	v_pk_fma_f32 v[12:13], v[108:109], v[218:219], v[12:13]
	v_pk_fma_f32 v[14:15], v[110:111], v[220:221], v[14:15]
	v_pk_fma_f32 v[16:17], v[112:113], v[210:211], v[16:17]
	v_pk_fma_f32 v[18:19], v[114:115], v[212:213], v[18:19]
	v_pk_fma_f32 v[20:21], v[116:117], v[214:215], v[20:21]
	v_pk_fma_f32 v[22:23], v[118:119], v[216:217], v[22:23]
	v_pk_fma_f32 v[24:25], v[120:121], v[218:219], v[24:25]
	v_pk_fma_f32 v[26:27], v[122:123], v[220:221], v[26:27]
	v_pk_fma_f32 v[28:29], v[124:125], v[210:211], v[28:29]
	v_pk_fma_f32 v[30:31], v[126:127], v[212:213], v[30:31]
	v_pk_fma_f32 v[32:33], v[128:129], v[214:215], v[32:33]
	v_pk_fma_f32 v[34:35], v[130:131], v[216:217], v[34:35]
	v_pk_fma_f32 v[36:37], v[132:133], v[218:219], v[36:37]
	v_pk_fma_f32 v[38:39], v[134:135], v[220:221], v[38:39]
	v_pk_fma_f32 v[40:41], v[136:137], v[210:211], v[40:41]
	v_pk_fma_f32 v[42:43], v[138:139], v[212:213], v[42:43]
	v_pk_fma_f32 v[44:45], v[140:141], v[214:215], v[44:45]
	v_pk_fma_f32 v[46:47], v[142:143], v[216:217], v[46:47]
	v_pk_fma_f32 v[48:49], v[144:145], v[218:219], v[48:49]
	v_pk_fma_f32 v[50:51], v[146:147], v[220:221], v[50:51]
	v_pk_fma_f32 v[52:53], v[148:149], v[210:211], v[52:53]
	v_pk_fma_f32 v[54:55], v[150:151], v[212:213], v[54:55]
	v_pk_fma_f32 v[56:57], v[152:153], v[214:215], v[56:57]
	v_pk_fma_f32 v[58:59], v[154:155], v[216:217], v[58:59]
	v_pk_fma_f32 v[60:61], v[156:157], v[218:219], v[60:61]
	v_pk_fma_f32 v[62:63], v[158:159], v[220:221], v[62:63]
	v_pk_fma_f32 v[64:65], v[160:161], v[210:211], v[64:65]
	v_pk_fma_f32 v[66:67], v[162:163], v[212:213], v[66:67]
	v_pk_fma_f32 v[68:69], v[164:165], v[214:215], v[68:69]
	v_pk_fma_f32 v[70:71], v[166:167], v[216:217], v[70:71]
	v_pk_fma_f32 v[72:73], v[168:169], v[218:219], v[72:73]
	v_pk_fma_f32 v[74:75], v[170:171], v[220:221], v[74:75]
	v_pk_fma_f32 v[76:77], v[172:173], v[210:211], v[76:77]
	v_pk_fma_f32 v[78:79], v[174:175], v[212:213], v[78:79]
	v_pk_fma_f32 v[80:81], v[176:177], v[214:215], v[80:81]
	v_pk_fma_f32 v[82:83], v[178:179], v[216:217], v[82:83]
	v_pk_fma_f32 v[84:85], v[180:181], v[218:219], v[84:85]
	v_pk_fma_f32 v[86:87], v[182:183], v[220:221], v[86:87]
	v_pk_fma_f32 v[88:89], v[184:185], v[210:211], v[88:89]
	v_pk_fma_f32 v[90:91], v[186:187], v[212:213], v[90:91]
	v_pk_fma_f32 v[92:93], v[188:189], v[214:215], v[92:93]
	v_pk_fma_f32 v[94:95], v[190:191], v[216:217], v[94:95]
	v_pk_fma_f32 v[96:97], v[192:193], v[218:219], v[96:97]
	v_pk_fma_f32 v[98:99], v[194:195], v[220:221], v[98:99]
	ds_read_b128 v[210:213], v2 offset:6144
	ds_read_b128 v[214:217], v2 offset:7168
	ds_read_b128 v[218:221], v2 offset:8192
	s_waitcnt vmcnt(9)
	s_add_i32 s52, s41, -22
	s_cmp_lt_i32 s52, 0
	s_cbranch_scc1 .Lcv_z8_zero
	v_lshlrev_b32_e32 v100, 16, v234
	v_and_b32_e32 v101, 0xffff0000, v234
	v_lshlrev_b32_e32 v102, 16, v235
	v_and_b32_e32 v103, 0xffff0000, v235
	v_lshlrev_b32_e32 v104, 16, v236
	v_and_b32_e32 v105, 0xffff0000, v236
	v_lshlrev_b32_e32 v106, 16, v237
	v_and_b32_e32 v107, 0xffff0000, v237
	v_lshlrev_b32_e32 v108, 16, v238
	v_and_b32_e32 v109, 0xffff0000, v238
	v_lshlrev_b32_e32 v110, 16, v239
	v_and_b32_e32 v111, 0xffff0000, v239
	s_branch .Lcv_z8_done

.Lcv_z8_done:
	s_add_i32 s52, s41, -18
	s_max_i32 s52, s52, 0
	s_mulk_i32 s52, 0x600
	v_add_u32_e32 v196, s52, v3
	global_load_dwordx2 v[234:235], v196, s[38:39]
	global_load_dwordx2 v[236:237], v196, s[38:39] offset:512
	global_load_dwordx2 v[238:239], v196, s[38:39] offset:1024
	s_waitcnt lgkmcnt(3)
	v_pk_fma_f32 v[4:5], v[112:113], v[222:223], v[4:5]
	v_pk_fma_f32 v[6:7], v[114:115], v[224:225], v[6:7]
	v_pk_fma_f32 v[8:9], v[116:117], v[226:227], v[8:9]
	v_pk_fma_f32 v[10:11], v[118:119], v[228:229], v[10:11]
	v_pk_fma_f32 v[12:13], v[120:121], v[230:231], v[12:13]
	v_pk_fma_f32 v[14:15], v[122:123], v[232:233], v[14:15]
	v_pk_fma_f32 v[16:17], v[124:125], v[222:223], v[16:17]
	v_pk_fma_f32 v[18:19], v[126:127], v[224:225], v[18:19]
	v_pk_fma_f32 v[20:21], v[128:129], v[226:227], v[20:21]
	v_pk_fma_f32 v[22:23], v[130:131], v[228:229], v[22:23]
	v_pk_fma_f32 v[24:25], v[132:133], v[230:231], v[24:25]
	v_pk_fma_f32 v[26:27], v[134:135], v[232:233], v[26:27]
	v_pk_fma_f32 v[28:29], v[136:137], v[222:223], v[28:29]
	v_pk_fma_f32 v[30:31], v[138:139], v[224:225], v[30:31]
	v_pk_fma_f32 v[32:33], v[140:141], v[226:227], v[32:33]
	v_pk_fma_f32 v[34:35], v[142:143], v[228:229], v[34:35]
	v_pk_fma_f32 v[36:37], v[144:145], v[230:231], v[36:37]
	v_pk_fma_f32 v[38:39], v[146:147], v[232:233], v[38:39]
	v_pk_fma_f32 v[40:41], v[148:149], v[222:223], v[40:41]
	v_pk_fma_f32 v[42:43], v[150:151], v[224:225], v[42:43]
	v_pk_fma_f32 v[44:45], v[152:153], v[226:227], v[44:45]
	v_pk_fma_f32 v[46:47], v[154:155], v[228:229], v[46:47]
	v_pk_fma_f32 v[48:49], v[156:157], v[230:231], v[48:49]
	v_pk_fma_f32 v[50:51], v[158:159], v[232:233], v[50:51]
	v_pk_fma_f32 v[52:53], v[160:161], v[222:223], v[52:53]
	v_pk_fma_f32 v[54:55], v[162:163], v[224:225], v[54:55]
	v_pk_fma_f32 v[56:57], v[164:165], v[226:227], v[56:57]
	v_pk_fma_f32 v[58:59], v[166:167], v[228:229], v[58:59]
	v_pk_fma_f32 v[60:61], v[168:169], v[230:231], v[60:61]
	v_pk_fma_f32 v[62:63], v[170:171], v[232:233], v[62:63]
	v_pk_fma_f32 v[64:65], v[172:173], v[222:223], v[64:65]
	v_pk_fma_f32 v[66:67], v[174:175], v[224:225], v[66:67]
	v_pk_fma_f32 v[68:69], v[176:177], v[226:227], v[68:69]
	v_pk_fma_f32 v[70:71], v[178:179], v[228:229], v[70:71]
	v_pk_fma_f32 v[72:73], v[180:181], v[230:231], v[72:73]
	v_pk_fma_f32 v[74:75], v[182:183], v[232:233], v[74:75]
	v_pk_fma_f32 v[76:77], v[184:185], v[222:223], v[76:77]
	v_pk_fma_f32 v[78:79], v[186:187], v[224:225], v[78:79]
	v_pk_fma_f32 v[80:81], v[188:189], v[226:227], v[80:81]
	v_pk_fma_f32 v[82:83], v[190:191], v[228:229], v[82:83]
	v_pk_fma_f32 v[84:85], v[192:193], v[230:231], v[84:85]
	v_pk_fma_f32 v[86:87], v[194:195], v[232:233], v[86:87]
	v_pk_fma_f32 v[88:89], v[100:101], v[222:223], v[88:89]
	v_pk_fma_f32 v[90:91], v[102:103], v[224:225], v[90:91]
	v_pk_fma_f32 v[92:93], v[104:105], v[226:227], v[92:93]
	v_pk_fma_f32 v[94:95], v[106:107], v[228:229], v[94:95]
	v_pk_fma_f32 v[96:97], v[108:109], v[230:231], v[96:97]
	v_pk_fma_f32 v[98:99], v[110:111], v[232:233], v[98:99]
	ds_read_b128 v[222:225], v2 offset:9216
	ds_read_b128 v[226:229], v2 offset:10240
	ds_read_b128 v[230:233], v2 offset:11264
	s_waitcnt vmcnt(9)
	s_add_i32 s52, s41, -21
	s_cmp_lt_i32 s52, 0
	s_cbranch_scc1 .Lcv_z9_zero
	v_lshlrev_b32_e32 v112, 16, v240
	v_and_b32_e32 v113, 0xffff0000, v240
	v_lshlrev_b32_e32 v114, 16, v241
	v_and_b32_e32 v115, 0xffff0000, v241
	v_lshlrev_b32_e32 v116, 16, v242
	v_and_b32_e32 v117, 0xffff0000, v242
	v_lshlrev_b32_e32 v118, 16, v243
	v_and_b32_e32 v119, 0xffff0000, v243
	v_lshlrev_b32_e32 v120, 16, v244
	v_and_b32_e32 v121, 0xffff0000, v244
	v_lshlrev_b32_e32 v122, 16, v245
	v_and_b32_e32 v123, 0xffff0000, v245
	s_branch .Lcv_z9_done

.Lcv_z9_done:
	s_add_i32 s52, s41, -17
	s_max_i32 s52, s52, 0
	s_mulk_i32 s52, 0x600
	v_add_u32_e32 v196, s52, v3
	global_load_dwordx2 v[240:241], v196, s[38:39]
	global_load_dwordx2 v[242:243], v196, s[38:39] offset:512
	global_load_dwordx2 v[244:245], v196, s[38:39] offset:1024
	s_waitcnt lgkmcnt(3)
	v_pk_fma_f32 v[4:5], v[124:125], v[210:211], v[4:5]
	v_pk_fma_f32 v[6:7], v[126:127], v[212:213], v[6:7]
	v_pk_fma_f32 v[8:9], v[128:129], v[214:215], v[8:9]
	v_pk_fma_f32 v[10:11], v[130:131], v[216:217], v[10:11]
	v_pk_fma_f32 v[12:13], v[132:133], v[218:219], v[12:13]
	v_pk_fma_f32 v[14:15], v[134:135], v[220:221], v[14:15]
	v_pk_fma_f32 v[16:17], v[136:137], v[210:211], v[16:17]
	v_pk_fma_f32 v[18:19], v[138:139], v[212:213], v[18:19]
	v_pk_fma_f32 v[20:21], v[140:141], v[214:215], v[20:21]
	v_pk_fma_f32 v[22:23], v[142:143], v[216:217], v[22:23]
	v_pk_fma_f32 v[24:25], v[144:145], v[218:219], v[24:25]
	v_pk_fma_f32 v[26:27], v[146:147], v[220:221], v[26:27]
	v_pk_fma_f32 v[28:29], v[148:149], v[210:211], v[28:29]
	v_pk_fma_f32 v[30:31], v[150:151], v[212:213], v[30:31]
	v_pk_fma_f32 v[32:33], v[152:153], v[214:215], v[32:33]
	v_pk_fma_f32 v[34:35], v[154:155], v[216:217], v[34:35]
	v_pk_fma_f32 v[36:37], v[156:157], v[218:219], v[36:37]
	v_pk_fma_f32 v[38:39], v[158:159], v[220:221], v[38:39]
	v_pk_fma_f32 v[40:41], v[160:161], v[210:211], v[40:41]
	v_pk_fma_f32 v[42:43], v[162:163], v[212:213], v[42:43]
	v_pk_fma_f32 v[44:45], v[164:165], v[214:215], v[44:45]
	v_pk_fma_f32 v[46:47], v[166:167], v[216:217], v[46:47]
	v_pk_fma_f32 v[48:49], v[168:169], v[218:219], v[48:49]
	v_pk_fma_f32 v[50:51], v[170:171], v[220:221], v[50:51]
	v_pk_fma_f32 v[52:53], v[172:173], v[210:211], v[52:53]
	v_pk_fma_f32 v[54:55], v[174:175], v[212:213], v[54:55]
	v_pk_fma_f32 v[56:57], v[176:177], v[214:215], v[56:57]
	v_pk_fma_f32 v[58:59], v[178:179], v[216:217], v[58:59]
	v_pk_fma_f32 v[60:61], v[180:181], v[218:219], v[60:61]
	v_pk_fma_f32 v[62:63], v[182:183], v[220:221], v[62:63]
	v_pk_fma_f32 v[64:65], v[184:185], v[210:211], v[64:65]
	v_pk_fma_f32 v[66:67], v[186:187], v[212:213], v[66:67]
	v_pk_fma_f32 v[68:69], v[188:189], v[214:215], v[68:69]
	v_pk_fma_f32 v[70:71], v[190:191], v[216:217], v[70:71]
	v_pk_fma_f32 v[72:73], v[192:193], v[218:219], v[72:73]
	v_pk_fma_f32 v[74:75], v[194:195], v[220:221], v[74:75]
	v_pk_fma_f32 v[76:77], v[100:101], v[210:211], v[76:77]
	v_pk_fma_f32 v[78:79], v[102:103], v[212:213], v[78:79]
	v_pk_fma_f32 v[80:81], v[104:105], v[214:215], v[80:81]
	v_pk_fma_f32 v[82:83], v[106:107], v[216:217], v[82:83]
	v_pk_fma_f32 v[84:85], v[108:109], v[218:219], v[84:85]
	v_pk_fma_f32 v[86:87], v[110:111], v[220:221], v[86:87]
	v_pk_fma_f32 v[88:89], v[112:113], v[210:211], v[88:89]
	v_pk_fma_f32 v[90:91], v[114:115], v[212:213], v[90:91]
	v_pk_fma_f32 v[92:93], v[116:117], v[214:215], v[92:93]
	v_pk_fma_f32 v[94:95], v[118:119], v[216:217], v[94:95]
	v_pk_fma_f32 v[96:97], v[120:121], v[218:219], v[96:97]
	v_pk_fma_f32 v[98:99], v[122:123], v[220:221], v[98:99]
	ds_read_b128 v[210:213], v2 offset:12288
	ds_read_b128 v[214:217], v2 offset:13312
	ds_read_b128 v[218:221], v2 offset:14336
	s_waitcnt vmcnt(9)
	s_add_i32 s52, s41, -20
	s_cmp_lt_i32 s52, 0
	s_cbranch_scc1 .Lcv_z10_zero
	v_lshlrev_b32_e32 v124, 16, v246
	v_and_b32_e32 v125, 0xffff0000, v246
	v_lshlrev_b32_e32 v126, 16, v247
	v_and_b32_e32 v127, 0xffff0000, v247
	v_lshlrev_b32_e32 v128, 16, v248
	v_and_b32_e32 v129, 0xffff0000, v248
	v_lshlrev_b32_e32 v130, 16, v249
	v_and_b32_e32 v131, 0xffff0000, v249
	v_lshlrev_b32_e32 v132, 16, v250
	v_and_b32_e32 v133, 0xffff0000, v250
	v_lshlrev_b32_e32 v134, 16, v251
	v_and_b32_e32 v135, 0xffff0000, v251
	s_branch .Lcv_z10_done

.Lcv_z10_done:
	s_add_i32 s52, s41, -16
	s_max_i32 s52, s52, 0
	s_mulk_i32 s52, 0x600
	v_add_u32_e32 v196, s52, v3
	global_load_dwordx2 v[246:247], v196, s[38:39]
	global_load_dwordx2 v[248:249], v196, s[38:39] offset:512
	global_load_dwordx2 v[250:251], v196, s[38:39] offset:1024
	s_waitcnt lgkmcnt(3)
	v_pk_fma_f32 v[4:5], v[136:137], v[222:223], v[4:5]
	v_pk_fma_f32 v[6:7], v[138:139], v[224:225], v[6:7]
	v_pk_fma_f32 v[8:9], v[140:141], v[226:227], v[8:9]
	v_pk_fma_f32 v[10:11], v[142:143], v[228:229], v[10:11]
	v_pk_fma_f32 v[12:13], v[144:145], v[230:231], v[12:13]
	v_pk_fma_f32 v[14:15], v[146:147], v[232:233], v[14:15]
	v_pk_fma_f32 v[16:17], v[148:149], v[222:223], v[16:17]
	v_pk_fma_f32 v[18:19], v[150:151], v[224:225], v[18:19]
	v_pk_fma_f32 v[20:21], v[152:153], v[226:227], v[20:21]
	v_pk_fma_f32 v[22:23], v[154:155], v[228:229], v[22:23]
	v_pk_fma_f32 v[24:25], v[156:157], v[230:231], v[24:25]
	v_pk_fma_f32 v[26:27], v[158:159], v[232:233], v[26:27]
	v_pk_fma_f32 v[28:29], v[160:161], v[222:223], v[28:29]
	v_pk_fma_f32 v[30:31], v[162:163], v[224:225], v[30:31]
	v_pk_fma_f32 v[32:33], v[164:165], v[226:227], v[32:33]
	v_pk_fma_f32 v[34:35], v[166:167], v[228:229], v[34:35]
	v_pk_fma_f32 v[36:37], v[168:169], v[230:231], v[36:37]
	v_pk_fma_f32 v[38:39], v[170:171], v[232:233], v[38:39]
	v_pk_fma_f32 v[40:41], v[172:173], v[222:223], v[40:41]
	v_pk_fma_f32 v[42:43], v[174:175], v[224:225], v[42:43]
	v_pk_fma_f32 v[44:45], v[176:177], v[226:227], v[44:45]
	v_pk_fma_f32 v[46:47], v[178:179], v[228:229], v[46:47]
	v_pk_fma_f32 v[48:49], v[180:181], v[230:231], v[48:49]
	v_pk_fma_f32 v[50:51], v[182:183], v[232:233], v[50:51]
	v_pk_fma_f32 v[52:53], v[184:185], v[222:223], v[52:53]
	v_pk_fma_f32 v[54:55], v[186:187], v[224:225], v[54:55]
	v_pk_fma_f32 v[56:57], v[188:189], v[226:227], v[56:57]
	v_pk_fma_f32 v[58:59], v[190:191], v[228:229], v[58:59]
	v_pk_fma_f32 v[60:61], v[192:193], v[230:231], v[60:61]
	v_pk_fma_f32 v[62:63], v[194:195], v[232:233], v[62:63]
	v_pk_fma_f32 v[64:65], v[100:101], v[222:223], v[64:65]
	v_pk_fma_f32 v[66:67], v[102:103], v[224:225], v[66:67]
	v_pk_fma_f32 v[68:69], v[104:105], v[226:227], v[68:69]
	v_pk_fma_f32 v[70:71], v[106:107], v[228:229], v[70:71]
	v_pk_fma_f32 v[72:73], v[108:109], v[230:231], v[72:73]
	v_pk_fma_f32 v[74:75], v[110:111], v[232:233], v[74:75]
	v_pk_fma_f32 v[76:77], v[112:113], v[222:223], v[76:77]
	v_pk_fma_f32 v[78:79], v[114:115], v[224:225], v[78:79]
	v_pk_fma_f32 v[80:81], v[116:117], v[226:227], v[80:81]
	v_pk_fma_f32 v[82:83], v[118:119], v[228:229], v[82:83]
	v_pk_fma_f32 v[84:85], v[120:121], v[230:231], v[84:85]
	v_pk_fma_f32 v[86:87], v[122:123], v[232:233], v[86:87]
	v_pk_fma_f32 v[88:89], v[124:125], v[222:223], v[88:89]
	v_pk_fma_f32 v[90:91], v[126:127], v[224:225], v[90:91]
	v_pk_fma_f32 v[92:93], v[128:129], v[226:227], v[92:93]
	v_pk_fma_f32 v[94:95], v[130:131], v[228:229], v[94:95]
	v_pk_fma_f32 v[96:97], v[132:133], v[230:231], v[96:97]
	v_pk_fma_f32 v[98:99], v[134:135], v[232:233], v[98:99]
	ds_read_b128 v[222:225], v2 offset:15360
	ds_read_b128 v[226:229], v2 offset:16384
	ds_read_b128 v[230:233], v2 offset:17408
	s_waitcnt vmcnt(9)
	s_add_i32 s52, s41, -19
	s_cmp_lt_i32 s52, 0
	s_cbranch_scc1 .Lcv_z11_zero
	v_lshlrev_b32_e32 v136, 16, v204
	v_and_b32_e32 v137, 0xffff0000, v204
	v_lshlrev_b32_e32 v138, 16, v205
	v_and_b32_e32 v139, 0xffff0000, v205
	v_lshlrev_b32_e32 v140, 16, v206
	v_and_b32_e32 v141, 0xffff0000, v206
	v_lshlrev_b32_e32 v142, 16, v207
	v_and_b32_e32 v143, 0xffff0000, v207
	v_lshlrev_b32_e32 v144, 16, v252
	v_and_b32_e32 v145, 0xffff0000, v252
	v_lshlrev_b32_e32 v146, 16, v253
	v_and_b32_e32 v147, 0xffff0000, v253
	s_branch .Lcv_z11_done

.Lcv_z11_done:
	s_add_i32 s52, s41, -15
	s_max_i32 s52, s52, 0
	s_mulk_i32 s52, 0x600
	v_add_u32_e32 v196, s52, v3
	global_load_dwordx2 v[204:205], v196, s[38:39]
	global_load_dwordx2 v[206:207], v196, s[38:39] offset:512
	global_load_dwordx2 v[252:253], v196, s[38:39] offset:1024
	s_waitcnt lgkmcnt(3)
	v_pk_fma_f32 v[4:5], v[148:149], v[210:211], v[4:5]
	v_pk_fma_f32 v[6:7], v[150:151], v[212:213], v[6:7]
	v_pk_fma_f32 v[8:9], v[152:153], v[214:215], v[8:9]
	v_pk_fma_f32 v[10:11], v[154:155], v[216:217], v[10:11]
	v_pk_fma_f32 v[12:13], v[156:157], v[218:219], v[12:13]
	v_pk_fma_f32 v[14:15], v[158:159], v[220:221], v[14:15]
	v_pk_fma_f32 v[16:17], v[160:161], v[210:211], v[16:17]
	v_pk_fma_f32 v[18:19], v[162:163], v[212:213], v[18:19]
	v_pk_fma_f32 v[20:21], v[164:165], v[214:215], v[20:21]
	v_pk_fma_f32 v[22:23], v[166:167], v[216:217], v[22:23]
	v_pk_fma_f32 v[24:25], v[168:169], v[218:219], v[24:25]
	v_pk_fma_f32 v[26:27], v[170:171], v[220:221], v[26:27]
	v_pk_fma_f32 v[28:29], v[172:173], v[210:211], v[28:29]
	v_pk_fma_f32 v[30:31], v[174:175], v[212:213], v[30:31]
	v_pk_fma_f32 v[32:33], v[176:177], v[214:215], v[32:33]
	v_pk_fma_f32 v[34:35], v[178:179], v[216:217], v[34:35]
	v_pk_fma_f32 v[36:37], v[180:181], v[218:219], v[36:37]
	v_pk_fma_f32 v[38:39], v[182:183], v[220:221], v[38:39]
	v_pk_fma_f32 v[40:41], v[184:185], v[210:211], v[40:41]
	v_pk_fma_f32 v[42:43], v[186:187], v[212:213], v[42:43]
	v_pk_fma_f32 v[44:45], v[188:189], v[214:215], v[44:45]
	v_pk_fma_f32 v[46:47], v[190:191], v[216:217], v[46:47]
	v_pk_fma_f32 v[48:49], v[192:193], v[218:219], v[48:49]
	v_pk_fma_f32 v[50:51], v[194:195], v[220:221], v[50:51]
	v_pk_fma_f32 v[52:53], v[100:101], v[210:211], v[52:53]
	v_pk_fma_f32 v[54:55], v[102:103], v[212:213], v[54:55]
	v_pk_fma_f32 v[56:57], v[104:105], v[214:215], v[56:57]
	v_pk_fma_f32 v[58:59], v[106:107], v[216:217], v[58:59]
	v_pk_fma_f32 v[60:61], v[108:109], v[218:219], v[60:61]
	v_pk_fma_f32 v[62:63], v[110:111], v[220:221], v[62:63]
	v_pk_fma_f32 v[64:65], v[112:113], v[210:211], v[64:65]
	v_pk_fma_f32 v[66:67], v[114:115], v[212:213], v[66:67]
	v_pk_fma_f32 v[68:69], v[116:117], v[214:215], v[68:69]
	v_pk_fma_f32 v[70:71], v[118:119], v[216:217], v[70:71]
	v_pk_fma_f32 v[72:73], v[120:121], v[218:219], v[72:73]
	v_pk_fma_f32 v[74:75], v[122:123], v[220:221], v[74:75]
	v_pk_fma_f32 v[76:77], v[124:125], v[210:211], v[76:77]
	v_pk_fma_f32 v[78:79], v[126:127], v[212:213], v[78:79]
	v_pk_fma_f32 v[80:81], v[128:129], v[214:215], v[80:81]
	v_pk_fma_f32 v[82:83], v[130:131], v[216:217], v[82:83]
	v_pk_fma_f32 v[84:85], v[132:133], v[218:219], v[84:85]
	v_pk_fma_f32 v[86:87], v[134:135], v[220:221], v[86:87]
	v_pk_fma_f32 v[88:89], v[136:137], v[210:211], v[88:89]
	v_pk_fma_f32 v[90:91], v[138:139], v[212:213], v[90:91]
	v_pk_fma_f32 v[92:93], v[140:141], v[214:215], v[92:93]
	v_pk_fma_f32 v[94:95], v[142:143], v[216:217], v[94:95]
	v_pk_fma_f32 v[96:97], v[144:145], v[218:219], v[96:97]
	v_pk_fma_f32 v[98:99], v[146:147], v[220:221], v[98:99]
	ds_read_b128 v[210:213], v2 offset:18432
	ds_read_b128 v[214:217], v2 offset:19456
	ds_read_b128 v[218:221], v2 offset:20480
	s_waitcnt vmcnt(9)
	s_add_i32 s52, s41, -18
	s_cmp_lt_i32 s52, 0
	s_cbranch_scc1 .Lcv_z12_zero
	v_lshlrev_b32_e32 v148, 16, v234
	v_and_b32_e32 v149, 0xffff0000, v234
	v_lshlrev_b32_e32 v150, 16, v235
	v_and_b32_e32 v151, 0xffff0000, v235
	v_lshlrev_b32_e32 v152, 16, v236
	v_and_b32_e32 v153, 0xffff0000, v236
	v_lshlrev_b32_e32 v154, 16, v237
	v_and_b32_e32 v155, 0xffff0000, v237
	v_lshlrev_b32_e32 v156, 16, v238
	v_and_b32_e32 v157, 0xffff0000, v238
	v_lshlrev_b32_e32 v158, 16, v239
	v_and_b32_e32 v159, 0xffff0000, v239
	s_branch .Lcv_z12_done

.Lcv_z12_done:
	s_add_i32 s52, s41, -14
	s_max_i32 s52, s52, 0
	s_mulk_i32 s52, 0x600
	v_add_u32_e32 v196, s52, v3
	global_load_dwordx2 v[234:235], v196, s[38:39]
	global_load_dwordx2 v[236:237], v196, s[38:39] offset:512
	global_load_dwordx2 v[238:239], v196, s[38:39] offset:1024
	s_waitcnt lgkmcnt(3)
	v_pk_fma_f32 v[4:5], v[160:161], v[222:223], v[4:5]
	v_pk_fma_f32 v[6:7], v[162:163], v[224:225], v[6:7]
	v_pk_fma_f32 v[8:9], v[164:165], v[226:227], v[8:9]
	v_pk_fma_f32 v[10:11], v[166:167], v[228:229], v[10:11]
	v_pk_fma_f32 v[12:13], v[168:169], v[230:231], v[12:13]
	v_pk_fma_f32 v[14:15], v[170:171], v[232:233], v[14:15]
	v_pk_fma_f32 v[16:17], v[172:173], v[222:223], v[16:17]
	v_pk_fma_f32 v[18:19], v[174:175], v[224:225], v[18:19]
	v_pk_fma_f32 v[20:21], v[176:177], v[226:227], v[20:21]
	v_pk_fma_f32 v[22:23], v[178:179], v[228:229], v[22:23]
	v_pk_fma_f32 v[24:25], v[180:181], v[230:231], v[24:25]
	v_pk_fma_f32 v[26:27], v[182:183], v[232:233], v[26:27]
	v_pk_fma_f32 v[28:29], v[184:185], v[222:223], v[28:29]
	v_pk_fma_f32 v[30:31], v[186:187], v[224:225], v[30:31]
	v_pk_fma_f32 v[32:33], v[188:189], v[226:227], v[32:33]
	v_pk_fma_f32 v[34:35], v[190:191], v[228:229], v[34:35]
	v_pk_fma_f32 v[36:37], v[192:193], v[230:231], v[36:37]
	v_pk_fma_f32 v[38:39], v[194:195], v[232:233], v[38:39]
	v_pk_fma_f32 v[40:41], v[100:101], v[222:223], v[40:41]
	v_pk_fma_f32 v[42:43], v[102:103], v[224:225], v[42:43]
	v_pk_fma_f32 v[44:45], v[104:105], v[226:227], v[44:45]
	v_pk_fma_f32 v[46:47], v[106:107], v[228:229], v[46:47]
	v_pk_fma_f32 v[48:49], v[108:109], v[230:231], v[48:49]
	v_pk_fma_f32 v[50:51], v[110:111], v[232:233], v[50:51]
	v_pk_fma_f32 v[52:53], v[112:113], v[222:223], v[52:53]
	v_pk_fma_f32 v[54:55], v[114:115], v[224:225], v[54:55]
	v_pk_fma_f32 v[56:57], v[116:117], v[226:227], v[56:57]
	v_pk_fma_f32 v[58:59], v[118:119], v[228:229], v[58:59]
	v_pk_fma_f32 v[60:61], v[120:121], v[230:231], v[60:61]
	v_pk_fma_f32 v[62:63], v[122:123], v[232:233], v[62:63]
	v_pk_fma_f32 v[64:65], v[124:125], v[222:223], v[64:65]
	v_pk_fma_f32 v[66:67], v[126:127], v[224:225], v[66:67]
	v_pk_fma_f32 v[68:69], v[128:129], v[226:227], v[68:69]
	v_pk_fma_f32 v[70:71], v[130:131], v[228:229], v[70:71]
	v_pk_fma_f32 v[72:73], v[132:133], v[230:231], v[72:73]
	v_pk_fma_f32 v[74:75], v[134:135], v[232:233], v[74:75]
	v_pk_fma_f32 v[76:77], v[136:137], v[222:223], v[76:77]
	v_pk_fma_f32 v[78:79], v[138:139], v[224:225], v[78:79]
	v_pk_fma_f32 v[80:81], v[140:141], v[226:227], v[80:81]
	v_pk_fma_f32 v[82:83], v[142:143], v[228:229], v[82:83]
	v_pk_fma_f32 v[84:85], v[144:145], v[230:231], v[84:85]
	v_pk_fma_f32 v[86:87], v[146:147], v[232:233], v[86:87]
	v_pk_fma_f32 v[88:89], v[148:149], v[222:223], v[88:89]
	v_pk_fma_f32 v[90:91], v[150:151], v[224:225], v[90:91]
	v_pk_fma_f32 v[92:93], v[152:153], v[226:227], v[92:93]
	v_pk_fma_f32 v[94:95], v[154:155], v[228:229], v[94:95]
	v_pk_fma_f32 v[96:97], v[156:157], v[230:231], v[96:97]
	v_pk_fma_f32 v[98:99], v[158:159], v[232:233], v[98:99]
	ds_read_b128 v[222:225], v2 offset:21504
	ds_read_b128 v[226:229], v2 offset:22528
	ds_read_b128 v[230:233], v2 offset:23552
	s_waitcnt vmcnt(9)
	s_add_i32 s52, s41, -17
	s_cmp_lt_i32 s52, 0
	s_cbranch_scc1 .Lcv_z13_zero
	v_lshlrev_b32_e32 v160, 16, v240
	v_and_b32_e32 v161, 0xffff0000, v240
	v_lshlrev_b32_e32 v162, 16, v241
	v_and_b32_e32 v163, 0xffff0000, v241
	v_lshlrev_b32_e32 v164, 16, v242
	v_and_b32_e32 v165, 0xffff0000, v242
	v_lshlrev_b32_e32 v166, 16, v243
	v_and_b32_e32 v167, 0xffff0000, v243
	v_lshlrev_b32_e32 v168, 16, v244
	v_and_b32_e32 v169, 0xffff0000, v244
	v_lshlrev_b32_e32 v170, 16, v245
	v_and_b32_e32 v171, 0xffff0000, v245
	s_branch .Lcv_z13_done

.Lcv_z13_done:
	s_add_i32 s52, s41, -13
	s_max_i32 s52, s52, 0
	s_mulk_i32 s52, 0x600
	v_add_u32_e32 v196, s52, v3
	global_load_dwordx2 v[240:241], v196, s[38:39]
	global_load_dwordx2 v[242:243], v196, s[38:39] offset:512
	global_load_dwordx2 v[244:245], v196, s[38:39] offset:1024
	s_waitcnt lgkmcnt(3)
	v_pk_fma_f32 v[4:5], v[172:173], v[210:211], v[4:5]
	v_pk_fma_f32 v[6:7], v[174:175], v[212:213], v[6:7]
	v_pk_fma_f32 v[8:9], v[176:177], v[214:215], v[8:9]
	v_pk_fma_f32 v[10:11], v[178:179], v[216:217], v[10:11]
	v_pk_fma_f32 v[12:13], v[180:181], v[218:219], v[12:13]
	v_pk_fma_f32 v[14:15], v[182:183], v[220:221], v[14:15]
	v_pk_fma_f32 v[16:17], v[184:185], v[210:211], v[16:17]
	v_pk_fma_f32 v[18:19], v[186:187], v[212:213], v[18:19]
	v_pk_fma_f32 v[20:21], v[188:189], v[214:215], v[20:21]
	v_pk_fma_f32 v[22:23], v[190:191], v[216:217], v[22:23]
	v_pk_fma_f32 v[24:25], v[192:193], v[218:219], v[24:25]
	v_pk_fma_f32 v[26:27], v[194:195], v[220:221], v[26:27]
	v_pk_fma_f32 v[28:29], v[100:101], v[210:211], v[28:29]
	v_pk_fma_f32 v[30:31], v[102:103], v[212:213], v[30:31]
	v_pk_fma_f32 v[32:33], v[104:105], v[214:215], v[32:33]
	v_pk_fma_f32 v[34:35], v[106:107], v[216:217], v[34:35]
	v_pk_fma_f32 v[36:37], v[108:109], v[218:219], v[36:37]
	v_pk_fma_f32 v[38:39], v[110:111], v[220:221], v[38:39]
	v_pk_fma_f32 v[40:41], v[112:113], v[210:211], v[40:41]
	v_pk_fma_f32 v[42:43], v[114:115], v[212:213], v[42:43]
	v_pk_fma_f32 v[44:45], v[116:117], v[214:215], v[44:45]
	v_pk_fma_f32 v[46:47], v[118:119], v[216:217], v[46:47]
	v_pk_fma_f32 v[48:49], v[120:121], v[218:219], v[48:49]
	v_pk_fma_f32 v[50:51], v[122:123], v[220:221], v[50:51]
	v_pk_fma_f32 v[52:53], v[124:125], v[210:211], v[52:53]
	v_pk_fma_f32 v[54:55], v[126:127], v[212:213], v[54:55]
	v_pk_fma_f32 v[56:57], v[128:129], v[214:215], v[56:57]
	v_pk_fma_f32 v[58:59], v[130:131], v[216:217], v[58:59]
	v_pk_fma_f32 v[60:61], v[132:133], v[218:219], v[60:61]
	v_pk_fma_f32 v[62:63], v[134:135], v[220:221], v[62:63]
	v_pk_fma_f32 v[64:65], v[136:137], v[210:211], v[64:65]
	v_pk_fma_f32 v[66:67], v[138:139], v[212:213], v[66:67]
	v_pk_fma_f32 v[68:69], v[140:141], v[214:215], v[68:69]
	v_pk_fma_f32 v[70:71], v[142:143], v[216:217], v[70:71]
	v_pk_fma_f32 v[72:73], v[144:145], v[218:219], v[72:73]
	v_pk_fma_f32 v[74:75], v[146:147], v[220:221], v[74:75]
	v_pk_fma_f32 v[76:77], v[148:149], v[210:211], v[76:77]
	v_pk_fma_f32 v[78:79], v[150:151], v[212:213], v[78:79]
	v_pk_fma_f32 v[80:81], v[152:153], v[214:215], v[80:81]
	v_pk_fma_f32 v[82:83], v[154:155], v[216:217], v[82:83]
	v_pk_fma_f32 v[84:85], v[156:157], v[218:219], v[84:85]
	v_pk_fma_f32 v[86:87], v[158:159], v[220:221], v[86:87]
	v_pk_fma_f32 v[88:89], v[160:161], v[210:211], v[88:89]
	v_pk_fma_f32 v[90:91], v[162:163], v[212:213], v[90:91]
	v_pk_fma_f32 v[92:93], v[164:165], v[214:215], v[92:93]
	v_pk_fma_f32 v[94:95], v[166:167], v[216:217], v[94:95]
	v_pk_fma_f32 v[96:97], v[168:169], v[218:219], v[96:97]
	v_pk_fma_f32 v[98:99], v[170:171], v[220:221], v[98:99]
	ds_read_b128 v[210:213], v2 offset:24576
	ds_read_b128 v[214:217], v2 offset:25600
	ds_read_b128 v[218:221], v2 offset:26624
	s_waitcnt vmcnt(9)
	s_add_i32 s52, s41, -16
	s_cmp_lt_i32 s52, 0
	s_cbranch_scc1 .Lcv_z14_zero
	v_lshlrev_b32_e32 v172, 16, v246
	v_and_b32_e32 v173, 0xffff0000, v246
	v_lshlrev_b32_e32 v174, 16, v247
	v_and_b32_e32 v175, 0xffff0000, v247
	v_lshlrev_b32_e32 v176, 16, v248
	v_and_b32_e32 v177, 0xffff0000, v248
	v_lshlrev_b32_e32 v178, 16, v249
	v_and_b32_e32 v179, 0xffff0000, v249
	v_lshlrev_b32_e32 v180, 16, v250
	v_and_b32_e32 v181, 0xffff0000, v250
	v_lshlrev_b32_e32 v182, 16, v251
	v_and_b32_e32 v183, 0xffff0000, v251
	s_branch .Lcv_z14_done

.Lcv_z14_done:
	s_add_i32 s52, s41, -12
	s_max_i32 s52, s52, 0
	s_mulk_i32 s52, 0x600
	v_add_u32_e32 v196, s52, v3
	global_load_dwordx2 v[246:247], v196, s[38:39]
	global_load_dwordx2 v[248:249], v196, s[38:39] offset:512
	global_load_dwordx2 v[250:251], v196, s[38:39] offset:1024
	s_waitcnt lgkmcnt(3)
	v_pk_fma_f32 v[4:5], v[184:185], v[222:223], v[4:5]
	v_pk_fma_f32 v[6:7], v[186:187], v[224:225], v[6:7]
	v_pk_fma_f32 v[8:9], v[188:189], v[226:227], v[8:9]
	v_pk_fma_f32 v[10:11], v[190:191], v[228:229], v[10:11]
	v_pk_fma_f32 v[12:13], v[192:193], v[230:231], v[12:13]
	v_pk_fma_f32 v[14:15], v[194:195], v[232:233], v[14:15]
	v_pk_fma_f32 v[16:17], v[100:101], v[222:223], v[16:17]
	v_pk_fma_f32 v[18:19], v[102:103], v[224:225], v[18:19]
	v_pk_fma_f32 v[20:21], v[104:105], v[226:227], v[20:21]
	v_pk_fma_f32 v[22:23], v[106:107], v[228:229], v[22:23]
	v_pk_fma_f32 v[24:25], v[108:109], v[230:231], v[24:25]
	v_pk_fma_f32 v[26:27], v[110:111], v[232:233], v[26:27]
	v_pk_fma_f32 v[28:29], v[112:113], v[222:223], v[28:29]
	v_pk_fma_f32 v[30:31], v[114:115], v[224:225], v[30:31]
	v_pk_fma_f32 v[32:33], v[116:117], v[226:227], v[32:33]
	v_pk_fma_f32 v[34:35], v[118:119], v[228:229], v[34:35]
	v_pk_fma_f32 v[36:37], v[120:121], v[230:231], v[36:37]
	v_pk_fma_f32 v[38:39], v[122:123], v[232:233], v[38:39]
	v_pk_fma_f32 v[40:41], v[124:125], v[222:223], v[40:41]
	v_pk_fma_f32 v[42:43], v[126:127], v[224:225], v[42:43]
	v_pk_fma_f32 v[44:45], v[128:129], v[226:227], v[44:45]
	v_pk_fma_f32 v[46:47], v[130:131], v[228:229], v[46:47]
	v_pk_fma_f32 v[48:49], v[132:133], v[230:231], v[48:49]
	v_pk_fma_f32 v[50:51], v[134:135], v[232:233], v[50:51]
	v_pk_fma_f32 v[52:53], v[136:137], v[222:223], v[52:53]
	v_pk_fma_f32 v[54:55], v[138:139], v[224:225], v[54:55]
	v_pk_fma_f32 v[56:57], v[140:141], v[226:227], v[56:57]
	v_pk_fma_f32 v[58:59], v[142:143], v[228:229], v[58:59]
	v_pk_fma_f32 v[60:61], v[144:145], v[230:231], v[60:61]
	v_pk_fma_f32 v[62:63], v[146:147], v[232:233], v[62:63]
	v_pk_fma_f32 v[64:65], v[148:149], v[222:223], v[64:65]
	v_pk_fma_f32 v[66:67], v[150:151], v[224:225], v[66:67]
	v_pk_fma_f32 v[68:69], v[152:153], v[226:227], v[68:69]
	v_pk_fma_f32 v[70:71], v[154:155], v[228:229], v[70:71]
	v_pk_fma_f32 v[72:73], v[156:157], v[230:231], v[72:73]
	v_pk_fma_f32 v[74:75], v[158:159], v[232:233], v[74:75]
	v_pk_fma_f32 v[76:77], v[160:161], v[222:223], v[76:77]
	v_pk_fma_f32 v[78:79], v[162:163], v[224:225], v[78:79]
	v_pk_fma_f32 v[80:81], v[164:165], v[226:227], v[80:81]
	v_pk_fma_f32 v[82:83], v[166:167], v[228:229], v[82:83]
	v_pk_fma_f32 v[84:85], v[168:169], v[230:231], v[84:85]
	v_pk_fma_f32 v[86:87], v[170:171], v[232:233], v[86:87]
	v_pk_fma_f32 v[88:89], v[172:173], v[222:223], v[88:89]
	v_pk_fma_f32 v[90:91], v[174:175], v[224:225], v[90:91]
	v_pk_fma_f32 v[92:93], v[176:177], v[226:227], v[92:93]
	v_pk_fma_f32 v[94:95], v[178:179], v[228:229], v[94:95]
	v_pk_fma_f32 v[96:97], v[180:181], v[230:231], v[96:97]
	v_pk_fma_f32 v[98:99], v[182:183], v[232:233], v[98:99]
	ds_read_b128 v[222:225], v2 offset:27648
	ds_read_b128 v[226:229], v2 offset:28672
	ds_read_b128 v[230:233], v2 offset:29696
	s_waitcnt vmcnt(9)
	s_add_i32 s52, s41, -15
	s_cmp_lt_i32 s52, 0
	s_cbranch_scc1 .Lcv_z15_zero
	v_lshlrev_b32_e32 v184, 16, v204
	v_and_b32_e32 v185, 0xffff0000, v204
	v_lshlrev_b32_e32 v186, 16, v205
	v_and_b32_e32 v187, 0xffff0000, v205
	v_lshlrev_b32_e32 v188, 16, v206
	v_and_b32_e32 v189, 0xffff0000, v206
	v_lshlrev_b32_e32 v190, 16, v207
	v_and_b32_e32 v191, 0xffff0000, v207
	v_lshlrev_b32_e32 v192, 16, v252
	v_and_b32_e32 v193, 0xffff0000, v252
	v_lshlrev_b32_e32 v194, 16, v253
	v_and_b32_e32 v195, 0xffff0000, v253
	s_branch .Lcv_z15_done

.Lcv_z15_done:
	s_add_i32 s52, s41, -11
	s_max_i32 s52, s52, 0
	s_mulk_i32 s52, 0x600
	v_add_u32_e32 v196, s52, v3
	global_load_dwordx2 v[204:205], v196, s[38:39]
	global_load_dwordx2 v[206:207], v196, s[38:39] offset:512
	global_load_dwordx2 v[252:253], v196, s[38:39] offset:1024
	s_waitcnt lgkmcnt(3)
	v_pk_fma_f32 v[4:5], v[100:101], v[210:211], v[4:5]
	v_pk_fma_f32 v[6:7], v[102:103], v[212:213], v[6:7]
	v_pk_fma_f32 v[8:9], v[104:105], v[214:215], v[8:9]
	v_pk_fma_f32 v[10:11], v[106:107], v[216:217], v[10:11]
	v_pk_fma_f32 v[12:13], v[108:109], v[218:219], v[12:13]
	v_pk_fma_f32 v[14:15], v[110:111], v[220:221], v[14:15]
	v_pk_fma_f32 v[16:17], v[112:113], v[210:211], v[16:17]
	v_pk_fma_f32 v[18:19], v[114:115], v[212:213], v[18:19]
	v_pk_fma_f32 v[20:21], v[116:117], v[214:215], v[20:21]
	v_pk_fma_f32 v[22:23], v[118:119], v[216:217], v[22:23]
	v_pk_fma_f32 v[24:25], v[120:121], v[218:219], v[24:25]
	v_pk_fma_f32 v[26:27], v[122:123], v[220:221], v[26:27]
	v_pk_fma_f32 v[28:29], v[124:125], v[210:211], v[28:29]
	v_pk_fma_f32 v[30:31], v[126:127], v[212:213], v[30:31]
	v_pk_fma_f32 v[32:33], v[128:129], v[214:215], v[32:33]
	v_pk_fma_f32 v[34:35], v[130:131], v[216:217], v[34:35]
	v_pk_fma_f32 v[36:37], v[132:133], v[218:219], v[36:37]
	v_pk_fma_f32 v[38:39], v[134:135], v[220:221], v[38:39]
	v_pk_fma_f32 v[40:41], v[136:137], v[210:211], v[40:41]
	v_pk_fma_f32 v[42:43], v[138:139], v[212:213], v[42:43]
	v_pk_fma_f32 v[44:45], v[140:141], v[214:215], v[44:45]
	v_pk_fma_f32 v[46:47], v[142:143], v[216:217], v[46:47]
	v_pk_fma_f32 v[48:49], v[144:145], v[218:219], v[48:49]
	v_pk_fma_f32 v[50:51], v[146:147], v[220:221], v[50:51]
	v_pk_fma_f32 v[52:53], v[148:149], v[210:211], v[52:53]
	v_pk_fma_f32 v[54:55], v[150:151], v[212:213], v[54:55]
	v_pk_fma_f32 v[56:57], v[152:153], v[214:215], v[56:57]
	v_pk_fma_f32 v[58:59], v[154:155], v[216:217], v[58:59]
	v_pk_fma_f32 v[60:61], v[156:157], v[218:219], v[60:61]
	v_pk_fma_f32 v[62:63], v[158:159], v[220:221], v[62:63]
	v_pk_fma_f32 v[64:65], v[160:161], v[210:211], v[64:65]
	v_pk_fma_f32 v[66:67], v[162:163], v[212:213], v[66:67]
	v_pk_fma_f32 v[68:69], v[164:165], v[214:215], v[68:69]
	v_pk_fma_f32 v[70:71], v[166:167], v[216:217], v[70:71]
	v_pk_fma_f32 v[72:73], v[168:169], v[218:219], v[72:73]
	v_pk_fma_f32 v[74:75], v[170:171], v[220:221], v[74:75]
	v_pk_fma_f32 v[76:77], v[172:173], v[210:211], v[76:77]
	v_pk_fma_f32 v[78:79], v[174:175], v[212:213], v[78:79]
	v_pk_fma_f32 v[80:81], v[176:177], v[214:215], v[80:81]
	v_pk_fma_f32 v[82:83], v[178:179], v[216:217], v[82:83]
	v_pk_fma_f32 v[84:85], v[180:181], v[218:219], v[84:85]
	v_pk_fma_f32 v[86:87], v[182:183], v[220:221], v[86:87]
	v_pk_fma_f32 v[88:89], v[184:185], v[210:211], v[88:89]
	v_pk_fma_f32 v[90:91], v[186:187], v[212:213], v[90:91]
	v_pk_fma_f32 v[92:93], v[188:189], v[214:215], v[92:93]
	v_pk_fma_f32 v[94:95], v[190:191], v[216:217], v[94:95]
	v_pk_fma_f32 v[96:97], v[192:193], v[218:219], v[96:97]
	v_pk_fma_f32 v[98:99], v[194:195], v[220:221], v[98:99]
	ds_read_b128 v[210:213], v2 offset:30720
	ds_read_b128 v[214:217], v2 offset:31744
	ds_read_b128 v[218:221], v2 offset:32768
	s_waitcnt vmcnt(9)
	s_add_i32 s52, s41, -14
	s_cmp_lt_i32 s52, 0
	s_cbranch_scc1 .Lcv_z16_zero
	v_lshlrev_b32_e32 v100, 16, v234
	v_and_b32_e32 v101, 0xffff0000, v234
	v_lshlrev_b32_e32 v102, 16, v235
	v_and_b32_e32 v103, 0xffff0000, v235
	v_lshlrev_b32_e32 v104, 16, v236
	v_and_b32_e32 v105, 0xffff0000, v236
	v_lshlrev_b32_e32 v106, 16, v237
	v_and_b32_e32 v107, 0xffff0000, v237
	v_lshlrev_b32_e32 v108, 16, v238
	v_and_b32_e32 v109, 0xffff0000, v238
	v_lshlrev_b32_e32 v110, 16, v239
	v_and_b32_e32 v111, 0xffff0000, v239
	s_branch .Lcv_z16_done

.Lcv_z16_done:
	s_add_i32 s52, s41, -10
	s_max_i32 s52, s52, 0
	s_mulk_i32 s52, 0x600
	v_add_u32_e32 v196, s52, v3
	global_load_dwordx2 v[234:235], v196, s[38:39]
	global_load_dwordx2 v[236:237], v196, s[38:39] offset:512
	global_load_dwordx2 v[238:239], v196, s[38:39] offset:1024
	s_waitcnt lgkmcnt(3)
	v_pk_fma_f32 v[4:5], v[112:113], v[222:223], v[4:5]
	v_pk_fma_f32 v[6:7], v[114:115], v[224:225], v[6:7]
	v_pk_fma_f32 v[8:9], v[116:117], v[226:227], v[8:9]
	v_pk_fma_f32 v[10:11], v[118:119], v[228:229], v[10:11]
	v_pk_fma_f32 v[12:13], v[120:121], v[230:231], v[12:13]
	v_pk_fma_f32 v[14:15], v[122:123], v[232:233], v[14:15]
	v_pk_fma_f32 v[16:17], v[124:125], v[222:223], v[16:17]
	v_pk_fma_f32 v[18:19], v[126:127], v[224:225], v[18:19]
	v_pk_fma_f32 v[20:21], v[128:129], v[226:227], v[20:21]
	v_pk_fma_f32 v[22:23], v[130:131], v[228:229], v[22:23]
	v_pk_fma_f32 v[24:25], v[132:133], v[230:231], v[24:25]
	v_pk_fma_f32 v[26:27], v[134:135], v[232:233], v[26:27]
	v_pk_fma_f32 v[28:29], v[136:137], v[222:223], v[28:29]
	v_pk_fma_f32 v[30:31], v[138:139], v[224:225], v[30:31]
	v_pk_fma_f32 v[32:33], v[140:141], v[226:227], v[32:33]
	v_pk_fma_f32 v[34:35], v[142:143], v[228:229], v[34:35]
	v_pk_fma_f32 v[36:37], v[144:145], v[230:231], v[36:37]
	v_pk_fma_f32 v[38:39], v[146:147], v[232:233], v[38:39]
	v_pk_fma_f32 v[40:41], v[148:149], v[222:223], v[40:41]
	v_pk_fma_f32 v[42:43], v[150:151], v[224:225], v[42:43]
	v_pk_fma_f32 v[44:45], v[152:153], v[226:227], v[44:45]
	v_pk_fma_f32 v[46:47], v[154:155], v[228:229], v[46:47]
	v_pk_fma_f32 v[48:49], v[156:157], v[230:231], v[48:49]
	v_pk_fma_f32 v[50:51], v[158:159], v[232:233], v[50:51]
	v_pk_fma_f32 v[52:53], v[160:161], v[222:223], v[52:53]
	v_pk_fma_f32 v[54:55], v[162:163], v[224:225], v[54:55]
	v_pk_fma_f32 v[56:57], v[164:165], v[226:227], v[56:57]
	v_pk_fma_f32 v[58:59], v[166:167], v[228:229], v[58:59]
	v_pk_fma_f32 v[60:61], v[168:169], v[230:231], v[60:61]
	v_pk_fma_f32 v[62:63], v[170:171], v[232:233], v[62:63]
	v_pk_fma_f32 v[64:65], v[172:173], v[222:223], v[64:65]
	v_pk_fma_f32 v[66:67], v[174:175], v[224:225], v[66:67]
	v_pk_fma_f32 v[68:69], v[176:177], v[226:227], v[68:69]
	v_pk_fma_f32 v[70:71], v[178:179], v[228:229], v[70:71]
	v_pk_fma_f32 v[72:73], v[180:181], v[230:231], v[72:73]
	v_pk_fma_f32 v[74:75], v[182:183], v[232:233], v[74:75]
	v_pk_fma_f32 v[76:77], v[184:185], v[222:223], v[76:77]
	v_pk_fma_f32 v[78:79], v[186:187], v[224:225], v[78:79]
	v_pk_fma_f32 v[80:81], v[188:189], v[226:227], v[80:81]
	v_pk_fma_f32 v[82:83], v[190:191], v[228:229], v[82:83]
	v_pk_fma_f32 v[84:85], v[192:193], v[230:231], v[84:85]
	v_pk_fma_f32 v[86:87], v[194:195], v[232:233], v[86:87]
	v_pk_fma_f32 v[88:89], v[100:101], v[222:223], v[88:89]
	v_pk_fma_f32 v[90:91], v[102:103], v[224:225], v[90:91]
	v_pk_fma_f32 v[92:93], v[104:105], v[226:227], v[92:93]
	v_pk_fma_f32 v[94:95], v[106:107], v[228:229], v[94:95]
	v_pk_fma_f32 v[96:97], v[108:109], v[230:231], v[96:97]
	v_pk_fma_f32 v[98:99], v[110:111], v[232:233], v[98:99]
	ds_read_b128 v[222:225], v2 offset:33792
	ds_read_b128 v[226:229], v2 offset:34816
	ds_read_b128 v[230:233], v2 offset:35840
	s_waitcnt vmcnt(9)
	s_add_i32 s52, s41, -13
	s_cmp_lt_i32 s52, 0
	s_cbranch_scc1 .Lcv_z17_zero
	v_lshlrev_b32_e32 v112, 16, v240
	v_and_b32_e32 v113, 0xffff0000, v240
	v_lshlrev_b32_e32 v114, 16, v241
	v_and_b32_e32 v115, 0xffff0000, v241
	v_lshlrev_b32_e32 v116, 16, v242
	v_and_b32_e32 v117, 0xffff0000, v242
	v_lshlrev_b32_e32 v118, 16, v243
	v_and_b32_e32 v119, 0xffff0000, v243
	v_lshlrev_b32_e32 v120, 16, v244
	v_and_b32_e32 v121, 0xffff0000, v244
	v_lshlrev_b32_e32 v122, 16, v245
	v_and_b32_e32 v123, 0xffff0000, v245
	s_branch .Lcv_z17_done

.Lcv_z17_done:
	s_add_i32 s52, s41, -9
	s_max_i32 s52, s52, 0
	s_mulk_i32 s52, 0x600
	v_add_u32_e32 v196, s52, v3
	global_load_dwordx2 v[240:241], v196, s[38:39]
	global_load_dwordx2 v[242:243], v196, s[38:39] offset:512
	global_load_dwordx2 v[244:245], v196, s[38:39] offset:1024
	s_waitcnt lgkmcnt(3)
	v_pk_fma_f32 v[4:5], v[124:125], v[210:211], v[4:5]
	v_pk_fma_f32 v[6:7], v[126:127], v[212:213], v[6:7]
	v_pk_fma_f32 v[8:9], v[128:129], v[214:215], v[8:9]
	v_pk_fma_f32 v[10:11], v[130:131], v[216:217], v[10:11]
	v_pk_fma_f32 v[12:13], v[132:133], v[218:219], v[12:13]
	v_pk_fma_f32 v[14:15], v[134:135], v[220:221], v[14:15]
	v_pk_fma_f32 v[16:17], v[136:137], v[210:211], v[16:17]
	v_pk_fma_f32 v[18:19], v[138:139], v[212:213], v[18:19]
	v_pk_fma_f32 v[20:21], v[140:141], v[214:215], v[20:21]
	v_pk_fma_f32 v[22:23], v[142:143], v[216:217], v[22:23]
	v_pk_fma_f32 v[24:25], v[144:145], v[218:219], v[24:25]
	v_pk_fma_f32 v[26:27], v[146:147], v[220:221], v[26:27]
	v_pk_fma_f32 v[28:29], v[148:149], v[210:211], v[28:29]
	v_pk_fma_f32 v[30:31], v[150:151], v[212:213], v[30:31]
	v_pk_fma_f32 v[32:33], v[152:153], v[214:215], v[32:33]
	v_pk_fma_f32 v[34:35], v[154:155], v[216:217], v[34:35]
	v_pk_fma_f32 v[36:37], v[156:157], v[218:219], v[36:37]
	v_pk_fma_f32 v[38:39], v[158:159], v[220:221], v[38:39]
	v_pk_fma_f32 v[40:41], v[160:161], v[210:211], v[40:41]
	v_pk_fma_f32 v[42:43], v[162:163], v[212:213], v[42:43]
	v_pk_fma_f32 v[44:45], v[164:165], v[214:215], v[44:45]
	v_pk_fma_f32 v[46:47], v[166:167], v[216:217], v[46:47]
	v_pk_fma_f32 v[48:49], v[168:169], v[218:219], v[48:49]
	v_pk_fma_f32 v[50:51], v[170:171], v[220:221], v[50:51]
	v_pk_fma_f32 v[52:53], v[172:173], v[210:211], v[52:53]
	v_pk_fma_f32 v[54:55], v[174:175], v[212:213], v[54:55]
	v_pk_fma_f32 v[56:57], v[176:177], v[214:215], v[56:57]
	v_pk_fma_f32 v[58:59], v[178:179], v[216:217], v[58:59]
	v_pk_fma_f32 v[60:61], v[180:181], v[218:219], v[60:61]
	v_pk_fma_f32 v[62:63], v[182:183], v[220:221], v[62:63]
	v_pk_fma_f32 v[64:65], v[184:185], v[210:211], v[64:65]
	v_pk_fma_f32 v[66:67], v[186:187], v[212:213], v[66:67]
	v_pk_fma_f32 v[68:69], v[188:189], v[214:215], v[68:69]
	v_pk_fma_f32 v[70:71], v[190:191], v[216:217], v[70:71]
	v_pk_fma_f32 v[72:73], v[192:193], v[218:219], v[72:73]
	v_pk_fma_f32 v[74:75], v[194:195], v[220:221], v[74:75]
	v_pk_fma_f32 v[76:77], v[100:101], v[210:211], v[76:77]
	v_pk_fma_f32 v[78:79], v[102:103], v[212:213], v[78:79]
	v_pk_fma_f32 v[80:81], v[104:105], v[214:215], v[80:81]
	v_pk_fma_f32 v[82:83], v[106:107], v[216:217], v[82:83]
	v_pk_fma_f32 v[84:85], v[108:109], v[218:219], v[84:85]
	v_pk_fma_f32 v[86:87], v[110:111], v[220:221], v[86:87]
	v_pk_fma_f32 v[88:89], v[112:113], v[210:211], v[88:89]
	v_pk_fma_f32 v[90:91], v[114:115], v[212:213], v[90:91]
	v_pk_fma_f32 v[92:93], v[116:117], v[214:215], v[92:93]
	v_pk_fma_f32 v[94:95], v[118:119], v[216:217], v[94:95]
	v_pk_fma_f32 v[96:97], v[120:121], v[218:219], v[96:97]
	v_pk_fma_f32 v[98:99], v[122:123], v[220:221], v[98:99]
	ds_read_b128 v[210:213], v2 offset:36864
	ds_read_b128 v[214:217], v2 offset:37888
	ds_read_b128 v[218:221], v2 offset:38912
	s_waitcnt vmcnt(9)
	s_add_i32 s52, s41, -12
	s_cmp_lt_i32 s52, 0
	s_cbranch_scc1 .Lcv_z18_zero
	v_lshlrev_b32_e32 v124, 16, v246
	v_and_b32_e32 v125, 0xffff0000, v246
	v_lshlrev_b32_e32 v126, 16, v247
	v_and_b32_e32 v127, 0xffff0000, v247
	v_lshlrev_b32_e32 v128, 16, v248
	v_and_b32_e32 v129, 0xffff0000, v248
	v_lshlrev_b32_e32 v130, 16, v249
	v_and_b32_e32 v131, 0xffff0000, v249
	v_lshlrev_b32_e32 v132, 16, v250
	v_and_b32_e32 v133, 0xffff0000, v250
	v_lshlrev_b32_e32 v134, 16, v251
	v_and_b32_e32 v135, 0xffff0000, v251
	s_branch .Lcv_z18_done

.Lcv_z18_done:
	s_add_i32 s52, s41, -8
	s_max_i32 s52, s52, 0
	s_mulk_i32 s52, 0x600
	v_add_u32_e32 v196, s52, v3
	global_load_dwordx2 v[246:247], v196, s[38:39]
	global_load_dwordx2 v[248:249], v196, s[38:39] offset:512
	global_load_dwordx2 v[250:251], v196, s[38:39] offset:1024
	s_waitcnt lgkmcnt(3)
	v_pk_fma_f32 v[4:5], v[136:137], v[222:223], v[4:5]
	v_pk_fma_f32 v[6:7], v[138:139], v[224:225], v[6:7]
	v_pk_fma_f32 v[8:9], v[140:141], v[226:227], v[8:9]
	v_pk_fma_f32 v[10:11], v[142:143], v[228:229], v[10:11]
	v_pk_fma_f32 v[12:13], v[144:145], v[230:231], v[12:13]
	v_pk_fma_f32 v[14:15], v[146:147], v[232:233], v[14:15]
	v_pk_fma_f32 v[16:17], v[148:149], v[222:223], v[16:17]
	v_pk_fma_f32 v[18:19], v[150:151], v[224:225], v[18:19]
	v_pk_fma_f32 v[20:21], v[152:153], v[226:227], v[20:21]
	v_pk_fma_f32 v[22:23], v[154:155], v[228:229], v[22:23]
	v_pk_fma_f32 v[24:25], v[156:157], v[230:231], v[24:25]
	v_pk_fma_f32 v[26:27], v[158:159], v[232:233], v[26:27]
	v_pk_fma_f32 v[28:29], v[160:161], v[222:223], v[28:29]
	v_pk_fma_f32 v[30:31], v[162:163], v[224:225], v[30:31]
	v_pk_fma_f32 v[32:33], v[164:165], v[226:227], v[32:33]
	v_pk_fma_f32 v[34:35], v[166:167], v[228:229], v[34:35]
	v_pk_fma_f32 v[36:37], v[168:169], v[230:231], v[36:37]
	v_pk_fma_f32 v[38:39], v[170:171], v[232:233], v[38:39]
	v_pk_fma_f32 v[40:41], v[172:173], v[222:223], v[40:41]
	v_pk_fma_f32 v[42:43], v[174:175], v[224:225], v[42:43]
	v_pk_fma_f32 v[44:45], v[176:177], v[226:227], v[44:45]
	v_pk_fma_f32 v[46:47], v[178:179], v[228:229], v[46:47]
	v_pk_fma_f32 v[48:49], v[180:181], v[230:231], v[48:49]
	v_pk_fma_f32 v[50:51], v[182:183], v[232:233], v[50:51]
	v_pk_fma_f32 v[52:53], v[184:185], v[222:223], v[52:53]
	v_pk_fma_f32 v[54:55], v[186:187], v[224:225], v[54:55]
	v_pk_fma_f32 v[56:57], v[188:189], v[226:227], v[56:57]
	v_pk_fma_f32 v[58:59], v[190:191], v[228:229], v[58:59]
	v_pk_fma_f32 v[60:61], v[192:193], v[230:231], v[60:61]
	v_pk_fma_f32 v[62:63], v[194:195], v[232:233], v[62:63]
	v_pk_fma_f32 v[64:65], v[100:101], v[222:223], v[64:65]
	v_pk_fma_f32 v[66:67], v[102:103], v[224:225], v[66:67]
	v_pk_fma_f32 v[68:69], v[104:105], v[226:227], v[68:69]
	v_pk_fma_f32 v[70:71], v[106:107], v[228:229], v[70:71]
	v_pk_fma_f32 v[72:73], v[108:109], v[230:231], v[72:73]
	v_pk_fma_f32 v[74:75], v[110:111], v[232:233], v[74:75]
	v_pk_fma_f32 v[76:77], v[112:113], v[222:223], v[76:77]
	v_pk_fma_f32 v[78:79], v[114:115], v[224:225], v[78:79]
	v_pk_fma_f32 v[80:81], v[116:117], v[226:227], v[80:81]
	v_pk_fma_f32 v[82:83], v[118:119], v[228:229], v[82:83]
	v_pk_fma_f32 v[84:85], v[120:121], v[230:231], v[84:85]
	v_pk_fma_f32 v[86:87], v[122:123], v[232:233], v[86:87]
	v_pk_fma_f32 v[88:89], v[124:125], v[222:223], v[88:89]
	v_pk_fma_f32 v[90:91], v[126:127], v[224:225], v[90:91]
	v_pk_fma_f32 v[92:93], v[128:129], v[226:227], v[92:93]
	v_pk_fma_f32 v[94:95], v[130:131], v[228:229], v[94:95]
	v_pk_fma_f32 v[96:97], v[132:133], v[230:231], v[96:97]
	v_pk_fma_f32 v[98:99], v[134:135], v[232:233], v[98:99]
	ds_read_b128 v[222:225], v2 offset:39936
	ds_read_b128 v[226:229], v2 offset:40960
	ds_read_b128 v[230:233], v2 offset:41984
	s_waitcnt vmcnt(9)
	s_add_i32 s52, s41, -11
	s_cmp_lt_i32 s52, 0
	s_cbranch_scc1 .Lcv_z19_zero
	v_lshlrev_b32_e32 v136, 16, v204
	v_and_b32_e32 v137, 0xffff0000, v204
	v_lshlrev_b32_e32 v138, 16, v205
	v_and_b32_e32 v139, 0xffff0000, v205
	v_lshlrev_b32_e32 v140, 16, v206
	v_and_b32_e32 v141, 0xffff0000, v206
	v_lshlrev_b32_e32 v142, 16, v207
	v_and_b32_e32 v143, 0xffff0000, v207
	v_lshlrev_b32_e32 v144, 16, v252
	v_and_b32_e32 v145, 0xffff0000, v252
	v_lshlrev_b32_e32 v146, 16, v253
	v_and_b32_e32 v147, 0xffff0000, v253
	s_branch .Lcv_z19_done

.Lcv_z19_done:
	s_add_i32 s52, s41, -7
	s_max_i32 s52, s52, 0
	s_mulk_i32 s52, 0x600
	v_add_u32_e32 v196, s52, v3
	global_load_dwordx2 v[204:205], v196, s[38:39]
	global_load_dwordx2 v[206:207], v196, s[38:39] offset:512
	global_load_dwordx2 v[252:253], v196, s[38:39] offset:1024
	s_waitcnt lgkmcnt(3)
	v_pk_fma_f32 v[4:5], v[148:149], v[210:211], v[4:5]
	v_pk_fma_f32 v[6:7], v[150:151], v[212:213], v[6:7]
	v_pk_fma_f32 v[8:9], v[152:153], v[214:215], v[8:9]
	v_pk_fma_f32 v[10:11], v[154:155], v[216:217], v[10:11]
	v_pk_fma_f32 v[12:13], v[156:157], v[218:219], v[12:13]
	v_pk_fma_f32 v[14:15], v[158:159], v[220:221], v[14:15]
	v_pk_fma_f32 v[16:17], v[160:161], v[210:211], v[16:17]
	v_pk_fma_f32 v[18:19], v[162:163], v[212:213], v[18:19]
	v_pk_fma_f32 v[20:21], v[164:165], v[214:215], v[20:21]
	v_pk_fma_f32 v[22:23], v[166:167], v[216:217], v[22:23]
	v_pk_fma_f32 v[24:25], v[168:169], v[218:219], v[24:25]
	v_pk_fma_f32 v[26:27], v[170:171], v[220:221], v[26:27]
	v_pk_fma_f32 v[28:29], v[172:173], v[210:211], v[28:29]
	v_pk_fma_f32 v[30:31], v[174:175], v[212:213], v[30:31]
	v_pk_fma_f32 v[32:33], v[176:177], v[214:215], v[32:33]
	v_pk_fma_f32 v[34:35], v[178:179], v[216:217], v[34:35]
	v_pk_fma_f32 v[36:37], v[180:181], v[218:219], v[36:37]
	v_pk_fma_f32 v[38:39], v[182:183], v[220:221], v[38:39]
	v_pk_fma_f32 v[40:41], v[184:185], v[210:211], v[40:41]
	v_pk_fma_f32 v[42:43], v[186:187], v[212:213], v[42:43]
	v_pk_fma_f32 v[44:45], v[188:189], v[214:215], v[44:45]
	v_pk_fma_f32 v[46:47], v[190:191], v[216:217], v[46:47]
	v_pk_fma_f32 v[48:49], v[192:193], v[218:219], v[48:49]
	v_pk_fma_f32 v[50:51], v[194:195], v[220:221], v[50:51]
	v_pk_fma_f32 v[52:53], v[100:101], v[210:211], v[52:53]
	v_pk_fma_f32 v[54:55], v[102:103], v[212:213], v[54:55]
	v_pk_fma_f32 v[56:57], v[104:105], v[214:215], v[56:57]
	v_pk_fma_f32 v[58:59], v[106:107], v[216:217], v[58:59]
	v_pk_fma_f32 v[60:61], v[108:109], v[218:219], v[60:61]
	v_pk_fma_f32 v[62:63], v[110:111], v[220:221], v[62:63]
	v_pk_fma_f32 v[64:65], v[112:113], v[210:211], v[64:65]
	v_pk_fma_f32 v[66:67], v[114:115], v[212:213], v[66:67]
	v_pk_fma_f32 v[68:69], v[116:117], v[214:215], v[68:69]
	v_pk_fma_f32 v[70:71], v[118:119], v[216:217], v[70:71]
	v_pk_fma_f32 v[72:73], v[120:121], v[218:219], v[72:73]
	v_pk_fma_f32 v[74:75], v[122:123], v[220:221], v[74:75]
	v_pk_fma_f32 v[76:77], v[124:125], v[210:211], v[76:77]
	v_pk_fma_f32 v[78:79], v[126:127], v[212:213], v[78:79]
	v_pk_fma_f32 v[80:81], v[128:129], v[214:215], v[80:81]
	v_pk_fma_f32 v[82:83], v[130:131], v[216:217], v[82:83]
	v_pk_fma_f32 v[84:85], v[132:133], v[218:219], v[84:85]
	v_pk_fma_f32 v[86:87], v[134:135], v[220:221], v[86:87]
	v_pk_fma_f32 v[88:89], v[136:137], v[210:211], v[88:89]
	v_pk_fma_f32 v[90:91], v[138:139], v[212:213], v[90:91]
	v_pk_fma_f32 v[92:93], v[140:141], v[214:215], v[92:93]
	v_pk_fma_f32 v[94:95], v[142:143], v[216:217], v[94:95]
	v_pk_fma_f32 v[96:97], v[144:145], v[218:219], v[96:97]
	v_pk_fma_f32 v[98:99], v[146:147], v[220:221], v[98:99]
	ds_read_b128 v[210:213], v2 offset:43008
	ds_read_b128 v[214:217], v2 offset:44032
	ds_read_b128 v[218:221], v2 offset:45056
	s_waitcnt vmcnt(9)
	s_add_i32 s52, s41, -10
	s_cmp_lt_i32 s52, 0
	s_cbranch_scc1 .Lcv_z20_zero
	v_lshlrev_b32_e32 v148, 16, v234
	v_and_b32_e32 v149, 0xffff0000, v234
	v_lshlrev_b32_e32 v150, 16, v235
	v_and_b32_e32 v151, 0xffff0000, v235
	v_lshlrev_b32_e32 v152, 16, v236
	v_and_b32_e32 v153, 0xffff0000, v236
	v_lshlrev_b32_e32 v154, 16, v237
	v_and_b32_e32 v155, 0xffff0000, v237
	v_lshlrev_b32_e32 v156, 16, v238
	v_and_b32_e32 v157, 0xffff0000, v238
	v_lshlrev_b32_e32 v158, 16, v239
	v_and_b32_e32 v159, 0xffff0000, v239
	s_branch .Lcv_z20_done

.Lcv_z20_done:
	s_add_i32 s52, s41, -6
	s_max_i32 s52, s52, 0
	s_mulk_i32 s52, 0x600
	v_add_u32_e32 v196, s52, v3
	global_load_dwordx2 v[234:235], v196, s[38:39]
	global_load_dwordx2 v[236:237], v196, s[38:39] offset:512
	global_load_dwordx2 v[238:239], v196, s[38:39] offset:1024
	s_waitcnt lgkmcnt(3)
	v_pk_fma_f32 v[4:5], v[160:161], v[222:223], v[4:5]
	v_pk_fma_f32 v[6:7], v[162:163], v[224:225], v[6:7]
	v_pk_fma_f32 v[8:9], v[164:165], v[226:227], v[8:9]
	v_pk_fma_f32 v[10:11], v[166:167], v[228:229], v[10:11]
	v_pk_fma_f32 v[12:13], v[168:169], v[230:231], v[12:13]
	v_pk_fma_f32 v[14:15], v[170:171], v[232:233], v[14:15]
	v_pk_fma_f32 v[16:17], v[172:173], v[222:223], v[16:17]
	v_pk_fma_f32 v[18:19], v[174:175], v[224:225], v[18:19]
	v_pk_fma_f32 v[20:21], v[176:177], v[226:227], v[20:21]
	v_pk_fma_f32 v[22:23], v[178:179], v[228:229], v[22:23]
	v_pk_fma_f32 v[24:25], v[180:181], v[230:231], v[24:25]
	v_pk_fma_f32 v[26:27], v[182:183], v[232:233], v[26:27]
	v_pk_fma_f32 v[28:29], v[184:185], v[222:223], v[28:29]
	v_pk_fma_f32 v[30:31], v[186:187], v[224:225], v[30:31]
	v_pk_fma_f32 v[32:33], v[188:189], v[226:227], v[32:33]
	v_pk_fma_f32 v[34:35], v[190:191], v[228:229], v[34:35]
	v_pk_fma_f32 v[36:37], v[192:193], v[230:231], v[36:37]
	v_pk_fma_f32 v[38:39], v[194:195], v[232:233], v[38:39]
	v_pk_fma_f32 v[40:41], v[100:101], v[222:223], v[40:41]
	v_pk_fma_f32 v[42:43], v[102:103], v[224:225], v[42:43]
	v_pk_fma_f32 v[44:45], v[104:105], v[226:227], v[44:45]
	v_pk_fma_f32 v[46:47], v[106:107], v[228:229], v[46:47]
	v_pk_fma_f32 v[48:49], v[108:109], v[230:231], v[48:49]
	v_pk_fma_f32 v[50:51], v[110:111], v[232:233], v[50:51]
	v_pk_fma_f32 v[52:53], v[112:113], v[222:223], v[52:53]
	v_pk_fma_f32 v[54:55], v[114:115], v[224:225], v[54:55]
	v_pk_fma_f32 v[56:57], v[116:117], v[226:227], v[56:57]
	v_pk_fma_f32 v[58:59], v[118:119], v[228:229], v[58:59]
	v_pk_fma_f32 v[60:61], v[120:121], v[230:231], v[60:61]
	v_pk_fma_f32 v[62:63], v[122:123], v[232:233], v[62:63]
	v_pk_fma_f32 v[64:65], v[124:125], v[222:223], v[64:65]
	v_pk_fma_f32 v[66:67], v[126:127], v[224:225], v[66:67]
	v_pk_fma_f32 v[68:69], v[128:129], v[226:227], v[68:69]
	v_pk_fma_f32 v[70:71], v[130:131], v[228:229], v[70:71]
	v_pk_fma_f32 v[72:73], v[132:133], v[230:231], v[72:73]
	v_pk_fma_f32 v[74:75], v[134:135], v[232:233], v[74:75]
	v_pk_fma_f32 v[76:77], v[136:137], v[222:223], v[76:77]
	v_pk_fma_f32 v[78:79], v[138:139], v[224:225], v[78:79]
	v_pk_fma_f32 v[80:81], v[140:141], v[226:227], v[80:81]
	v_pk_fma_f32 v[82:83], v[142:143], v[228:229], v[82:83]
	v_pk_fma_f32 v[84:85], v[144:145], v[230:231], v[84:85]
	v_pk_fma_f32 v[86:87], v[146:147], v[232:233], v[86:87]
	v_pk_fma_f32 v[88:89], v[148:149], v[222:223], v[88:89]
	v_pk_fma_f32 v[90:91], v[150:151], v[224:225], v[90:91]
	v_pk_fma_f32 v[92:93], v[152:153], v[226:227], v[92:93]
	v_pk_fma_f32 v[94:95], v[154:155], v[228:229], v[94:95]
	v_pk_fma_f32 v[96:97], v[156:157], v[230:231], v[96:97]
	v_pk_fma_f32 v[98:99], v[158:159], v[232:233], v[98:99]
	ds_read_b128 v[222:225], v2 offset:46080
	ds_read_b128 v[226:229], v2 offset:47104
	ds_read_b128 v[230:233], v2 offset:48128
	s_waitcnt vmcnt(9)
	s_add_i32 s52, s41, -9
	s_cmp_lt_i32 s52, 0
	s_cbranch_scc1 .Lcv_z21_zero
	v_lshlrev_b32_e32 v160, 16, v240
	v_and_b32_e32 v161, 0xffff0000, v240
	v_lshlrev_b32_e32 v162, 16, v241
	v_and_b32_e32 v163, 0xffff0000, v241
	v_lshlrev_b32_e32 v164, 16, v242
	v_and_b32_e32 v165, 0xffff0000, v242
	v_lshlrev_b32_e32 v166, 16, v243
	v_and_b32_e32 v167, 0xffff0000, v243
	v_lshlrev_b32_e32 v168, 16, v244
	v_and_b32_e32 v169, 0xffff0000, v244
	v_lshlrev_b32_e32 v170, 16, v245
	v_and_b32_e32 v171, 0xffff0000, v245
	s_branch .Lcv_z21_done

.Lcv_z21_done:
	s_add_i32 s52, s41, -5
	s_max_i32 s52, s52, 0
	s_mulk_i32 s52, 0x600
	v_add_u32_e32 v196, s52, v3
	global_load_dwordx2 v[240:241], v196, s[38:39]
	global_load_dwordx2 v[242:243], v196, s[38:39] offset:512
	global_load_dwordx2 v[244:245], v196, s[38:39] offset:1024
	s_waitcnt lgkmcnt(3)
	v_pk_fma_f32 v[4:5], v[172:173], v[210:211], v[4:5]
	v_pk_fma_f32 v[6:7], v[174:175], v[212:213], v[6:7]
	v_pk_fma_f32 v[8:9], v[176:177], v[214:215], v[8:9]
	v_pk_fma_f32 v[10:11], v[178:179], v[216:217], v[10:11]
	v_pk_fma_f32 v[12:13], v[180:181], v[218:219], v[12:13]
	v_pk_fma_f32 v[14:15], v[182:183], v[220:221], v[14:15]
	v_pk_fma_f32 v[16:17], v[184:185], v[210:211], v[16:17]
	v_pk_fma_f32 v[18:19], v[186:187], v[212:213], v[18:19]
	v_pk_fma_f32 v[20:21], v[188:189], v[214:215], v[20:21]
	v_pk_fma_f32 v[22:23], v[190:191], v[216:217], v[22:23]
	v_pk_fma_f32 v[24:25], v[192:193], v[218:219], v[24:25]
	v_pk_fma_f32 v[26:27], v[194:195], v[220:221], v[26:27]
	v_pk_fma_f32 v[28:29], v[100:101], v[210:211], v[28:29]
	v_pk_fma_f32 v[30:31], v[102:103], v[212:213], v[30:31]
	v_pk_fma_f32 v[32:33], v[104:105], v[214:215], v[32:33]
	v_pk_fma_f32 v[34:35], v[106:107], v[216:217], v[34:35]
	v_pk_fma_f32 v[36:37], v[108:109], v[218:219], v[36:37]
	v_pk_fma_f32 v[38:39], v[110:111], v[220:221], v[38:39]
	v_pk_fma_f32 v[40:41], v[112:113], v[210:211], v[40:41]
	v_pk_fma_f32 v[42:43], v[114:115], v[212:213], v[42:43]
	v_pk_fma_f32 v[44:45], v[116:117], v[214:215], v[44:45]
	v_pk_fma_f32 v[46:47], v[118:119], v[216:217], v[46:47]
	v_pk_fma_f32 v[48:49], v[120:121], v[218:219], v[48:49]
	v_pk_fma_f32 v[50:51], v[122:123], v[220:221], v[50:51]
	v_pk_fma_f32 v[52:53], v[124:125], v[210:211], v[52:53]
	v_pk_fma_f32 v[54:55], v[126:127], v[212:213], v[54:55]
	v_pk_fma_f32 v[56:57], v[128:129], v[214:215], v[56:57]
	v_pk_fma_f32 v[58:59], v[130:131], v[216:217], v[58:59]
	v_pk_fma_f32 v[60:61], v[132:133], v[218:219], v[60:61]
	v_pk_fma_f32 v[62:63], v[134:135], v[220:221], v[62:63]
	v_pk_fma_f32 v[64:65], v[136:137], v[210:211], v[64:65]
	v_pk_fma_f32 v[66:67], v[138:139], v[212:213], v[66:67]
	v_pk_fma_f32 v[68:69], v[140:141], v[214:215], v[68:69]
	v_pk_fma_f32 v[70:71], v[142:143], v[216:217], v[70:71]
	v_pk_fma_f32 v[72:73], v[144:145], v[218:219], v[72:73]
	v_pk_fma_f32 v[74:75], v[146:147], v[220:221], v[74:75]
	v_pk_fma_f32 v[76:77], v[148:149], v[210:211], v[76:77]
	v_pk_fma_f32 v[78:79], v[150:151], v[212:213], v[78:79]
	v_pk_fma_f32 v[80:81], v[152:153], v[214:215], v[80:81]
	v_pk_fma_f32 v[82:83], v[154:155], v[216:217], v[82:83]
	v_pk_fma_f32 v[84:85], v[156:157], v[218:219], v[84:85]
	v_pk_fma_f32 v[86:87], v[158:159], v[220:221], v[86:87]
	v_pk_fma_f32 v[88:89], v[160:161], v[210:211], v[88:89]
	v_pk_fma_f32 v[90:91], v[162:163], v[212:213], v[90:91]
	v_pk_fma_f32 v[92:93], v[164:165], v[214:215], v[92:93]
	v_pk_fma_f32 v[94:95], v[166:167], v[216:217], v[94:95]
	v_pk_fma_f32 v[96:97], v[168:169], v[218:219], v[96:97]
	v_pk_fma_f32 v[98:99], v[170:171], v[220:221], v[98:99]
	ds_read_b128 v[210:213], v2 offset:49152
	ds_read_b128 v[214:217], v2 offset:50176
	ds_read_b128 v[218:221], v2 offset:51200
	s_waitcnt vmcnt(9)
	s_add_i32 s52, s41, -8
	s_cmp_lt_i32 s52, 0
	s_cbranch_scc1 .Lcv_z22_zero
	v_lshlrev_b32_e32 v172, 16, v246
	v_and_b32_e32 v173, 0xffff0000, v246
	v_lshlrev_b32_e32 v174, 16, v247
	v_and_b32_e32 v175, 0xffff0000, v247
	v_lshlrev_b32_e32 v176, 16, v248
	v_and_b32_e32 v177, 0xffff0000, v248
	v_lshlrev_b32_e32 v178, 16, v249
	v_and_b32_e32 v179, 0xffff0000, v249
	v_lshlrev_b32_e32 v180, 16, v250
	v_and_b32_e32 v181, 0xffff0000, v250
	v_lshlrev_b32_e32 v182, 16, v251
	v_and_b32_e32 v183, 0xffff0000, v251
	s_branch .Lcv_z22_done

.Lcv_z22_done:
	s_add_i32 s52, s41, -4
	s_max_i32 s52, s52, 0
	s_mulk_i32 s52, 0x600
	v_add_u32_e32 v196, s52, v3
	global_load_dwordx2 v[246:247], v196, s[38:39]
	global_load_dwordx2 v[248:249], v196, s[38:39] offset:512
	global_load_dwordx2 v[250:251], v196, s[38:39] offset:1024
	s_waitcnt lgkmcnt(3)
	v_pk_fma_f32 v[4:5], v[184:185], v[222:223], v[4:5]
	v_pk_fma_f32 v[6:7], v[186:187], v[224:225], v[6:7]
	v_pk_fma_f32 v[8:9], v[188:189], v[226:227], v[8:9]
	v_pk_fma_f32 v[10:11], v[190:191], v[228:229], v[10:11]
	v_pk_fma_f32 v[12:13], v[192:193], v[230:231], v[12:13]
	v_pk_fma_f32 v[14:15], v[194:195], v[232:233], v[14:15]
	v_pk_fma_f32 v[16:17], v[100:101], v[222:223], v[16:17]
	v_pk_fma_f32 v[18:19], v[102:103], v[224:225], v[18:19]
	v_pk_fma_f32 v[20:21], v[104:105], v[226:227], v[20:21]
	v_pk_fma_f32 v[22:23], v[106:107], v[228:229], v[22:23]
	v_pk_fma_f32 v[24:25], v[108:109], v[230:231], v[24:25]
	v_pk_fma_f32 v[26:27], v[110:111], v[232:233], v[26:27]
	v_pk_fma_f32 v[28:29], v[112:113], v[222:223], v[28:29]
	v_pk_fma_f32 v[30:31], v[114:115], v[224:225], v[30:31]
	v_pk_fma_f32 v[32:33], v[116:117], v[226:227], v[32:33]
	v_pk_fma_f32 v[34:35], v[118:119], v[228:229], v[34:35]
	v_pk_fma_f32 v[36:37], v[120:121], v[230:231], v[36:37]
	v_pk_fma_f32 v[38:39], v[122:123], v[232:233], v[38:39]
	v_pk_fma_f32 v[40:41], v[124:125], v[222:223], v[40:41]
	v_pk_fma_f32 v[42:43], v[126:127], v[224:225], v[42:43]
	v_pk_fma_f32 v[44:45], v[128:129], v[226:227], v[44:45]
	v_pk_fma_f32 v[46:47], v[130:131], v[228:229], v[46:47]
	v_pk_fma_f32 v[48:49], v[132:133], v[230:231], v[48:49]
	v_pk_fma_f32 v[50:51], v[134:135], v[232:233], v[50:51]
	v_pk_fma_f32 v[52:53], v[136:137], v[222:223], v[52:53]
	v_pk_fma_f32 v[54:55], v[138:139], v[224:225], v[54:55]
	v_pk_fma_f32 v[56:57], v[140:141], v[226:227], v[56:57]
	v_pk_fma_f32 v[58:59], v[142:143], v[228:229], v[58:59]
	v_pk_fma_f32 v[60:61], v[144:145], v[230:231], v[60:61]
	v_pk_fma_f32 v[62:63], v[146:147], v[232:233], v[62:63]
	v_pk_fma_f32 v[64:65], v[148:149], v[222:223], v[64:65]
	v_pk_fma_f32 v[66:67], v[150:151], v[224:225], v[66:67]
	v_pk_fma_f32 v[68:69], v[152:153], v[226:227], v[68:69]
	v_pk_fma_f32 v[70:71], v[154:155], v[228:229], v[70:71]
	v_pk_fma_f32 v[72:73], v[156:157], v[230:231], v[72:73]
	v_pk_fma_f32 v[74:75], v[158:159], v[232:233], v[74:75]
	v_pk_fma_f32 v[76:77], v[160:161], v[222:223], v[76:77]
	v_pk_fma_f32 v[78:79], v[162:163], v[224:225], v[78:79]
	v_pk_fma_f32 v[80:81], v[164:165], v[226:227], v[80:81]
	v_pk_fma_f32 v[82:83], v[166:167], v[228:229], v[82:83]
	v_pk_fma_f32 v[84:85], v[168:169], v[230:231], v[84:85]
	v_pk_fma_f32 v[86:87], v[170:171], v[232:233], v[86:87]
	v_pk_fma_f32 v[88:89], v[172:173], v[222:223], v[88:89]
	v_pk_fma_f32 v[90:91], v[174:175], v[224:225], v[90:91]
	v_pk_fma_f32 v[92:93], v[176:177], v[226:227], v[92:93]
	v_pk_fma_f32 v[94:95], v[178:179], v[228:229], v[94:95]
	v_pk_fma_f32 v[96:97], v[180:181], v[230:231], v[96:97]
	v_pk_fma_f32 v[98:99], v[182:183], v[232:233], v[98:99]
	ds_read_b128 v[222:225], v2 offset:52224
	ds_read_b128 v[226:229], v2 offset:53248
	ds_read_b128 v[230:233], v2 offset:54272
	s_waitcnt vmcnt(9)
	s_add_i32 s52, s41, -7
	s_cmp_lt_i32 s52, 0
	s_cbranch_scc1 .Lcv_z23_zero
	v_lshlrev_b32_e32 v184, 16, v204
	v_and_b32_e32 v185, 0xffff0000, v204
	v_lshlrev_b32_e32 v186, 16, v205
	v_and_b32_e32 v187, 0xffff0000, v205
	v_lshlrev_b32_e32 v188, 16, v206
	v_and_b32_e32 v189, 0xffff0000, v206
	v_lshlrev_b32_e32 v190, 16, v207
	v_and_b32_e32 v191, 0xffff0000, v207
	v_lshlrev_b32_e32 v192, 16, v252
	v_and_b32_e32 v193, 0xffff0000, v252
	v_lshlrev_b32_e32 v194, 16, v253
	v_and_b32_e32 v195, 0xffff0000, v253
	s_branch .Lcv_z23_done

.Lcv_z23_done:
	s_add_i32 s52, s41, -3
	s_max_i32 s52, s52, 0
	s_mulk_i32 s52, 0x600
	v_add_u32_e32 v196, s52, v3
	global_load_dwordx2 v[204:205], v196, s[38:39]
	global_load_dwordx2 v[206:207], v196, s[38:39] offset:512
	global_load_dwordx2 v[252:253], v196, s[38:39] offset:1024
	s_waitcnt lgkmcnt(3)
	v_pk_fma_f32 v[4:5], v[100:101], v[210:211], v[4:5]
	v_pk_fma_f32 v[6:7], v[102:103], v[212:213], v[6:7]
	v_pk_fma_f32 v[8:9], v[104:105], v[214:215], v[8:9]
	v_pk_fma_f32 v[10:11], v[106:107], v[216:217], v[10:11]
	v_pk_fma_f32 v[12:13], v[108:109], v[218:219], v[12:13]
	v_pk_fma_f32 v[14:15], v[110:111], v[220:221], v[14:15]
	v_pk_fma_f32 v[16:17], v[112:113], v[210:211], v[16:17]
	v_pk_fma_f32 v[18:19], v[114:115], v[212:213], v[18:19]
	v_pk_fma_f32 v[20:21], v[116:117], v[214:215], v[20:21]
	v_pk_fma_f32 v[22:23], v[118:119], v[216:217], v[22:23]
	v_pk_fma_f32 v[24:25], v[120:121], v[218:219], v[24:25]
	v_pk_fma_f32 v[26:27], v[122:123], v[220:221], v[26:27]
	v_pk_fma_f32 v[28:29], v[124:125], v[210:211], v[28:29]
	v_pk_fma_f32 v[30:31], v[126:127], v[212:213], v[30:31]
	v_pk_fma_f32 v[32:33], v[128:129], v[214:215], v[32:33]
	v_pk_fma_f32 v[34:35], v[130:131], v[216:217], v[34:35]
	v_pk_fma_f32 v[36:37], v[132:133], v[218:219], v[36:37]
	v_pk_fma_f32 v[38:39], v[134:135], v[220:221], v[38:39]
	v_pk_fma_f32 v[40:41], v[136:137], v[210:211], v[40:41]
	v_pk_fma_f32 v[42:43], v[138:139], v[212:213], v[42:43]
	v_pk_fma_f32 v[44:45], v[140:141], v[214:215], v[44:45]
	v_pk_fma_f32 v[46:47], v[142:143], v[216:217], v[46:47]
	v_pk_fma_f32 v[48:49], v[144:145], v[218:219], v[48:49]
	v_pk_fma_f32 v[50:51], v[146:147], v[220:221], v[50:51]
	v_pk_fma_f32 v[52:53], v[148:149], v[210:211], v[52:53]
	v_pk_fma_f32 v[54:55], v[150:151], v[212:213], v[54:55]
	v_pk_fma_f32 v[56:57], v[152:153], v[214:215], v[56:57]
	v_pk_fma_f32 v[58:59], v[154:155], v[216:217], v[58:59]
	v_pk_fma_f32 v[60:61], v[156:157], v[218:219], v[60:61]
	v_pk_fma_f32 v[62:63], v[158:159], v[220:221], v[62:63]
	v_pk_fma_f32 v[64:65], v[160:161], v[210:211], v[64:65]
	v_pk_fma_f32 v[66:67], v[162:163], v[212:213], v[66:67]
	v_pk_fma_f32 v[68:69], v[164:165], v[214:215], v[68:69]
	v_pk_fma_f32 v[70:71], v[166:167], v[216:217], v[70:71]
	v_pk_fma_f32 v[72:73], v[168:169], v[218:219], v[72:73]
	v_pk_fma_f32 v[74:75], v[170:171], v[220:221], v[74:75]
	v_pk_fma_f32 v[76:77], v[172:173], v[210:211], v[76:77]
	v_pk_fma_f32 v[78:79], v[174:175], v[212:213], v[78:79]
	v_pk_fma_f32 v[80:81], v[176:177], v[214:215], v[80:81]
	v_pk_fma_f32 v[82:83], v[178:179], v[216:217], v[82:83]
	v_pk_fma_f32 v[84:85], v[180:181], v[218:219], v[84:85]
	v_pk_fma_f32 v[86:87], v[182:183], v[220:221], v[86:87]
	v_pk_fma_f32 v[88:89], v[184:185], v[210:211], v[88:89]
	v_pk_fma_f32 v[90:91], v[186:187], v[212:213], v[90:91]
	v_pk_fma_f32 v[92:93], v[188:189], v[214:215], v[92:93]
	v_pk_fma_f32 v[94:95], v[190:191], v[216:217], v[94:95]
	v_pk_fma_f32 v[96:97], v[192:193], v[218:219], v[96:97]
	v_pk_fma_f32 v[98:99], v[194:195], v[220:221], v[98:99]
	ds_read_b128 v[210:213], v2 offset:55296
	ds_read_b128 v[214:217], v2 offset:56320
	ds_read_b128 v[218:221], v2 offset:57344
	s_waitcnt vmcnt(9)
	s_add_i32 s52, s41, -6
	s_cmp_lt_i32 s52, 0
	s_cbranch_scc1 .Lcv_z24_zero
	v_lshlrev_b32_e32 v100, 16, v234
	v_and_b32_e32 v101, 0xffff0000, v234
	v_lshlrev_b32_e32 v102, 16, v235
	v_and_b32_e32 v103, 0xffff0000, v235
	v_lshlrev_b32_e32 v104, 16, v236
	v_and_b32_e32 v105, 0xffff0000, v236
	v_lshlrev_b32_e32 v106, 16, v237
	v_and_b32_e32 v107, 0xffff0000, v237
	v_lshlrev_b32_e32 v108, 16, v238
	v_and_b32_e32 v109, 0xffff0000, v238
	v_lshlrev_b32_e32 v110, 16, v239
	v_and_b32_e32 v111, 0xffff0000, v239
	s_branch .Lcv_z24_done

.Lcv_z24_done:
	s_add_i32 s52, s41, -2
	s_max_i32 s52, s52, 0
	s_mulk_i32 s52, 0x600
	v_add_u32_e32 v196, s52, v3
	global_load_dwordx2 v[234:235], v196, s[38:39]
	global_load_dwordx2 v[236:237], v196, s[38:39] offset:512
	global_load_dwordx2 v[238:239], v196, s[38:39] offset:1024
	s_waitcnt lgkmcnt(3)
	v_pk_fma_f32 v[4:5], v[112:113], v[222:223], v[4:5]
	v_pk_fma_f32 v[6:7], v[114:115], v[224:225], v[6:7]
	v_pk_fma_f32 v[8:9], v[116:117], v[226:227], v[8:9]
	v_pk_fma_f32 v[10:11], v[118:119], v[228:229], v[10:11]
	v_pk_fma_f32 v[12:13], v[120:121], v[230:231], v[12:13]
	v_pk_fma_f32 v[14:15], v[122:123], v[232:233], v[14:15]
	v_pk_fma_f32 v[16:17], v[124:125], v[222:223], v[16:17]
	v_pk_fma_f32 v[18:19], v[126:127], v[224:225], v[18:19]
	v_pk_fma_f32 v[20:21], v[128:129], v[226:227], v[20:21]
	v_pk_fma_f32 v[22:23], v[130:131], v[228:229], v[22:23]
	v_pk_fma_f32 v[24:25], v[132:133], v[230:231], v[24:25]
	v_pk_fma_f32 v[26:27], v[134:135], v[232:233], v[26:27]
	v_pk_fma_f32 v[28:29], v[136:137], v[222:223], v[28:29]
	v_pk_fma_f32 v[30:31], v[138:139], v[224:225], v[30:31]
	v_pk_fma_f32 v[32:33], v[140:141], v[226:227], v[32:33]
	v_pk_fma_f32 v[34:35], v[142:143], v[228:229], v[34:35]
	v_pk_fma_f32 v[36:37], v[144:145], v[230:231], v[36:37]
	v_pk_fma_f32 v[38:39], v[146:147], v[232:233], v[38:39]
	v_pk_fma_f32 v[40:41], v[148:149], v[222:223], v[40:41]
	v_pk_fma_f32 v[42:43], v[150:151], v[224:225], v[42:43]
	v_pk_fma_f32 v[44:45], v[152:153], v[226:227], v[44:45]
	v_pk_fma_f32 v[46:47], v[154:155], v[228:229], v[46:47]
	v_pk_fma_f32 v[48:49], v[156:157], v[230:231], v[48:49]
	v_pk_fma_f32 v[50:51], v[158:159], v[232:233], v[50:51]
	v_pk_fma_f32 v[52:53], v[160:161], v[222:223], v[52:53]
	v_pk_fma_f32 v[54:55], v[162:163], v[224:225], v[54:55]
	v_pk_fma_f32 v[56:57], v[164:165], v[226:227], v[56:57]
	v_pk_fma_f32 v[58:59], v[166:167], v[228:229], v[58:59]
	v_pk_fma_f32 v[60:61], v[168:169], v[230:231], v[60:61]
	v_pk_fma_f32 v[62:63], v[170:171], v[232:233], v[62:63]
	v_pk_fma_f32 v[64:65], v[172:173], v[222:223], v[64:65]
	v_pk_fma_f32 v[66:67], v[174:175], v[224:225], v[66:67]
	v_pk_fma_f32 v[68:69], v[176:177], v[226:227], v[68:69]
	v_pk_fma_f32 v[70:71], v[178:179], v[228:229], v[70:71]
	v_pk_fma_f32 v[72:73], v[180:181], v[230:231], v[72:73]
	v_pk_fma_f32 v[74:75], v[182:183], v[232:233], v[74:75]
	v_pk_fma_f32 v[76:77], v[184:185], v[222:223], v[76:77]
	v_pk_fma_f32 v[78:79], v[186:187], v[224:225], v[78:79]
	v_pk_fma_f32 v[80:81], v[188:189], v[226:227], v[80:81]
	v_pk_fma_f32 v[82:83], v[190:191], v[228:229], v[82:83]
	v_pk_fma_f32 v[84:85], v[192:193], v[230:231], v[84:85]
	v_pk_fma_f32 v[86:87], v[194:195], v[232:233], v[86:87]
	v_pk_fma_f32 v[88:89], v[100:101], v[222:223], v[88:89]
	v_pk_fma_f32 v[90:91], v[102:103], v[224:225], v[90:91]
	v_pk_fma_f32 v[92:93], v[104:105], v[226:227], v[92:93]
	v_pk_fma_f32 v[94:95], v[106:107], v[228:229], v[94:95]
	v_pk_fma_f32 v[96:97], v[108:109], v[230:231], v[96:97]
	v_pk_fma_f32 v[98:99], v[110:111], v[232:233], v[98:99]
	ds_read_b128 v[222:225], v2 offset:58368
	ds_read_b128 v[226:229], v2 offset:59392
	ds_read_b128 v[230:233], v2 offset:60416
	s_waitcnt vmcnt(9)
	s_add_i32 s52, s41, -5
	s_cmp_lt_i32 s52, 0
	s_cbranch_scc1 .Lcv_z25_zero
	v_lshlrev_b32_e32 v112, 16, v240
	v_and_b32_e32 v113, 0xffff0000, v240
	v_lshlrev_b32_e32 v114, 16, v241
	v_and_b32_e32 v115, 0xffff0000, v241
	v_lshlrev_b32_e32 v116, 16, v242
	v_and_b32_e32 v117, 0xffff0000, v242
	v_lshlrev_b32_e32 v118, 16, v243
	v_and_b32_e32 v119, 0xffff0000, v243
	v_lshlrev_b32_e32 v120, 16, v244
	v_and_b32_e32 v121, 0xffff0000, v244
	v_lshlrev_b32_e32 v122, 16, v245
	v_and_b32_e32 v123, 0xffff0000, v245
	s_branch .Lcv_z25_done

.Lcv_z25_done:
	s_add_i32 s52, s41, -1
	s_max_i32 s52, s52, 0
	s_mulk_i32 s52, 0x600
	v_add_u32_e32 v196, s52, v3
	global_load_dwordx2 v[240:241], v196, s[38:39]
	global_load_dwordx2 v[242:243], v196, s[38:39] offset:512
	global_load_dwordx2 v[244:245], v196, s[38:39] offset:1024
	s_waitcnt lgkmcnt(3)
	v_pk_fma_f32 v[4:5], v[124:125], v[210:211], v[4:5]
	v_pk_fma_f32 v[6:7], v[126:127], v[212:213], v[6:7]
	v_pk_fma_f32 v[8:9], v[128:129], v[214:215], v[8:9]
	v_pk_fma_f32 v[10:11], v[130:131], v[216:217], v[10:11]
	v_pk_fma_f32 v[12:13], v[132:133], v[218:219], v[12:13]
	v_pk_fma_f32 v[14:15], v[134:135], v[220:221], v[14:15]
	v_pk_fma_f32 v[16:17], v[136:137], v[210:211], v[16:17]
	v_pk_fma_f32 v[18:19], v[138:139], v[212:213], v[18:19]
	v_pk_fma_f32 v[20:21], v[140:141], v[214:215], v[20:21]
	v_pk_fma_f32 v[22:23], v[142:143], v[216:217], v[22:23]
	v_pk_fma_f32 v[24:25], v[144:145], v[218:219], v[24:25]
	v_pk_fma_f32 v[26:27], v[146:147], v[220:221], v[26:27]
	v_pk_fma_f32 v[28:29], v[148:149], v[210:211], v[28:29]
	v_pk_fma_f32 v[30:31], v[150:151], v[212:213], v[30:31]
	v_pk_fma_f32 v[32:33], v[152:153], v[214:215], v[32:33]
	v_pk_fma_f32 v[34:35], v[154:155], v[216:217], v[34:35]
	v_pk_fma_f32 v[36:37], v[156:157], v[218:219], v[36:37]
	v_pk_fma_f32 v[38:39], v[158:159], v[220:221], v[38:39]
	v_pk_fma_f32 v[40:41], v[160:161], v[210:211], v[40:41]
	v_pk_fma_f32 v[42:43], v[162:163], v[212:213], v[42:43]
	v_pk_fma_f32 v[44:45], v[164:165], v[214:215], v[44:45]
	v_pk_fma_f32 v[46:47], v[166:167], v[216:217], v[46:47]
	v_pk_fma_f32 v[48:49], v[168:169], v[218:219], v[48:49]
	v_pk_fma_f32 v[50:51], v[170:171], v[220:221], v[50:51]
	v_pk_fma_f32 v[52:53], v[172:173], v[210:211], v[52:53]
	v_pk_fma_f32 v[54:55], v[174:175], v[212:213], v[54:55]
	v_pk_fma_f32 v[56:57], v[176:177], v[214:215], v[56:57]
	v_pk_fma_f32 v[58:59], v[178:179], v[216:217], v[58:59]
	v_pk_fma_f32 v[60:61], v[180:181], v[218:219], v[60:61]
	v_pk_fma_f32 v[62:63], v[182:183], v[220:221], v[62:63]
	v_pk_fma_f32 v[64:65], v[184:185], v[210:211], v[64:65]
	v_pk_fma_f32 v[66:67], v[186:187], v[212:213], v[66:67]
	v_pk_fma_f32 v[68:69], v[188:189], v[214:215], v[68:69]
	v_pk_fma_f32 v[70:71], v[190:191], v[216:217], v[70:71]
	v_pk_fma_f32 v[72:73], v[192:193], v[218:219], v[72:73]
	v_pk_fma_f32 v[74:75], v[194:195], v[220:221], v[74:75]
	v_pk_fma_f32 v[76:77], v[100:101], v[210:211], v[76:77]
	v_pk_fma_f32 v[78:79], v[102:103], v[212:213], v[78:79]
	v_pk_fma_f32 v[80:81], v[104:105], v[214:215], v[80:81]
	v_pk_fma_f32 v[82:83], v[106:107], v[216:217], v[82:83]
	v_pk_fma_f32 v[84:85], v[108:109], v[218:219], v[84:85]
	v_pk_fma_f32 v[86:87], v[110:111], v[220:221], v[86:87]
	v_pk_fma_f32 v[88:89], v[112:113], v[210:211], v[88:89]
	v_pk_fma_f32 v[90:91], v[114:115], v[212:213], v[90:91]
	v_pk_fma_f32 v[92:93], v[116:117], v[214:215], v[92:93]
	v_pk_fma_f32 v[94:95], v[118:119], v[216:217], v[94:95]
	v_pk_fma_f32 v[96:97], v[120:121], v[218:219], v[96:97]
	v_pk_fma_f32 v[98:99], v[122:123], v[220:221], v[98:99]
	ds_read_b128 v[210:213], v2 offset:61440
	ds_read_b128 v[214:217], v2 offset:62464
	ds_read_b128 v[218:221], v2 offset:63488
	s_waitcnt vmcnt(9)
	s_add_i32 s52, s41, -4
	s_cmp_lt_i32 s52, 0
	s_cbranch_scc1 .Lcv_z26_zero
	v_lshlrev_b32_e32 v124, 16, v246
	v_and_b32_e32 v125, 0xffff0000, v246
	v_lshlrev_b32_e32 v126, 16, v247
	v_and_b32_e32 v127, 0xffff0000, v247
	v_lshlrev_b32_e32 v128, 16, v248
	v_and_b32_e32 v129, 0xffff0000, v248
	v_lshlrev_b32_e32 v130, 16, v249
	v_and_b32_e32 v131, 0xffff0000, v249
	v_lshlrev_b32_e32 v132, 16, v250
	v_and_b32_e32 v133, 0xffff0000, v250
	v_lshlrev_b32_e32 v134, 16, v251
	v_and_b32_e32 v135, 0xffff0000, v251
	s_branch .Lcv_z26_done

.Lcv_z26_done:
	s_add_i32 s52, s41, 0
	s_mulk_i32 s52, 0x600
	v_add_u32_e32 v196, s52, v3
	global_load_dwordx2 v[246:247], v196, s[38:39]
	global_load_dwordx2 v[248:249], v196, s[38:39] offset:512
	global_load_dwordx2 v[250:251], v196, s[38:39] offset:1024
	s_waitcnt lgkmcnt(3)
	v_pk_fma_f32 v[4:5], v[136:137], v[222:223], v[4:5]
	v_pk_fma_f32 v[6:7], v[138:139], v[224:225], v[6:7]
	v_pk_fma_f32 v[8:9], v[140:141], v[226:227], v[8:9]
	v_pk_fma_f32 v[10:11], v[142:143], v[228:229], v[10:11]
	v_pk_fma_f32 v[12:13], v[144:145], v[230:231], v[12:13]
	v_pk_fma_f32 v[14:15], v[146:147], v[232:233], v[14:15]
	v_pk_fma_f32 v[16:17], v[148:149], v[222:223], v[16:17]
	v_pk_fma_f32 v[18:19], v[150:151], v[224:225], v[18:19]
	v_pk_fma_f32 v[20:21], v[152:153], v[226:227], v[20:21]
	v_pk_fma_f32 v[22:23], v[154:155], v[228:229], v[22:23]
	v_pk_fma_f32 v[24:25], v[156:157], v[230:231], v[24:25]
	v_pk_fma_f32 v[26:27], v[158:159], v[232:233], v[26:27]
	v_pk_fma_f32 v[28:29], v[160:161], v[222:223], v[28:29]
	v_pk_fma_f32 v[30:31], v[162:163], v[224:225], v[30:31]
	v_pk_fma_f32 v[32:33], v[164:165], v[226:227], v[32:33]
	v_pk_fma_f32 v[34:35], v[166:167], v[228:229], v[34:35]
	v_pk_fma_f32 v[36:37], v[168:169], v[230:231], v[36:37]
	v_pk_fma_f32 v[38:39], v[170:171], v[232:233], v[38:39]
	v_pk_fma_f32 v[40:41], v[172:173], v[222:223], v[40:41]
	v_pk_fma_f32 v[42:43], v[174:175], v[224:225], v[42:43]
	v_pk_fma_f32 v[44:45], v[176:177], v[226:227], v[44:45]
	v_pk_fma_f32 v[46:47], v[178:179], v[228:229], v[46:47]
	v_pk_fma_f32 v[48:49], v[180:181], v[230:231], v[48:49]
	v_pk_fma_f32 v[50:51], v[182:183], v[232:233], v[50:51]
	v_pk_fma_f32 v[52:53], v[184:185], v[222:223], v[52:53]
	v_pk_fma_f32 v[54:55], v[186:187], v[224:225], v[54:55]
	v_pk_fma_f32 v[56:57], v[188:189], v[226:227], v[56:57]
	v_pk_fma_f32 v[58:59], v[190:191], v[228:229], v[58:59]
	v_pk_fma_f32 v[60:61], v[192:193], v[230:231], v[60:61]
	v_pk_fma_f32 v[62:63], v[194:195], v[232:233], v[62:63]
	v_pk_fma_f32 v[64:65], v[100:101], v[222:223], v[64:65]
	v_pk_fma_f32 v[66:67], v[102:103], v[224:225], v[66:67]
	v_pk_fma_f32 v[68:69], v[104:105], v[226:227], v[68:69]
	v_pk_fma_f32 v[70:71], v[106:107], v[228:229], v[70:71]
	v_pk_fma_f32 v[72:73], v[108:109], v[230:231], v[72:73]
	v_pk_fma_f32 v[74:75], v[110:111], v[232:233], v[74:75]
	v_pk_fma_f32 v[76:77], v[112:113], v[222:223], v[76:77]
	v_pk_fma_f32 v[78:79], v[114:115], v[224:225], v[78:79]
	v_pk_fma_f32 v[80:81], v[116:117], v[226:227], v[80:81]
	v_pk_fma_f32 v[82:83], v[118:119], v[228:229], v[82:83]
	v_pk_fma_f32 v[84:85], v[120:121], v[230:231], v[84:85]
	v_pk_fma_f32 v[86:87], v[122:123], v[232:233], v[86:87]
	v_pk_fma_f32 v[88:89], v[124:125], v[222:223], v[88:89]
	v_pk_fma_f32 v[90:91], v[126:127], v[224:225], v[90:91]
	v_pk_fma_f32 v[92:93], v[128:129], v[226:227], v[92:93]
	v_pk_fma_f32 v[94:95], v[130:131], v[228:229], v[94:95]
	v_pk_fma_f32 v[96:97], v[132:133], v[230:231], v[96:97]
	v_pk_fma_f32 v[98:99], v[134:135], v[232:233], v[98:99]
	ds_read_b128 v[222:225], v2 offset:64512
	ds_read_b128 v[226:229], v208
	ds_read_b128 v[230:233], v208 offset:1024
	s_waitcnt vmcnt(9)
	s_add_i32 s52, s41, -3
	s_cmp_lt_i32 s52, 0
	s_cbranch_scc1 .Lcv_z27_zero
	v_lshlrev_b32_e32 v136, 16, v204
	v_and_b32_e32 v137, 0xffff0000, v204
	v_lshlrev_b32_e32 v138, 16, v205
	v_and_b32_e32 v139, 0xffff0000, v205
	v_lshlrev_b32_e32 v140, 16, v206
	v_and_b32_e32 v141, 0xffff0000, v206
	v_lshlrev_b32_e32 v142, 16, v207
	v_and_b32_e32 v143, 0xffff0000, v207
	v_lshlrev_b32_e32 v144, 16, v252
	v_and_b32_e32 v145, 0xffff0000, v252
	v_lshlrev_b32_e32 v146, 16, v253
	v_and_b32_e32 v147, 0xffff0000, v253
	s_branch .Lcv_z27_done

.Lcv_z27_done:
	s_add_i32 s52, s41, 1
	s_mulk_i32 s52, 0x600
	v_add_u32_e32 v196, s52, v3
	global_load_dwordx2 v[204:205], v196, s[38:39]
	global_load_dwordx2 v[206:207], v196, s[38:39] offset:512
	global_load_dwordx2 v[252:253], v196, s[38:39] offset:1024
	s_waitcnt lgkmcnt(3)
	v_pk_fma_f32 v[4:5], v[148:149], v[210:211], v[4:5]
	v_pk_fma_f32 v[6:7], v[150:151], v[212:213], v[6:7]
	v_pk_fma_f32 v[8:9], v[152:153], v[214:215], v[8:9]
	v_pk_fma_f32 v[10:11], v[154:155], v[216:217], v[10:11]
	v_pk_fma_f32 v[12:13], v[156:157], v[218:219], v[12:13]
	v_pk_fma_f32 v[14:15], v[158:159], v[220:221], v[14:15]
	v_pk_fma_f32 v[16:17], v[160:161], v[210:211], v[16:17]
	v_pk_fma_f32 v[18:19], v[162:163], v[212:213], v[18:19]
	v_pk_fma_f32 v[20:21], v[164:165], v[214:215], v[20:21]
	v_pk_fma_f32 v[22:23], v[166:167], v[216:217], v[22:23]
	v_pk_fma_f32 v[24:25], v[168:169], v[218:219], v[24:25]
	v_pk_fma_f32 v[26:27], v[170:171], v[220:221], v[26:27]
	v_pk_fma_f32 v[28:29], v[172:173], v[210:211], v[28:29]
	v_pk_fma_f32 v[30:31], v[174:175], v[212:213], v[30:31]
	v_pk_fma_f32 v[32:33], v[176:177], v[214:215], v[32:33]
	v_pk_fma_f32 v[34:35], v[178:179], v[216:217], v[34:35]
	v_pk_fma_f32 v[36:37], v[180:181], v[218:219], v[36:37]
	v_pk_fma_f32 v[38:39], v[182:183], v[220:221], v[38:39]
	v_pk_fma_f32 v[40:41], v[184:185], v[210:211], v[40:41]
	v_pk_fma_f32 v[42:43], v[186:187], v[212:213], v[42:43]
	v_pk_fma_f32 v[44:45], v[188:189], v[214:215], v[44:45]
	v_pk_fma_f32 v[46:47], v[190:191], v[216:217], v[46:47]
	v_pk_fma_f32 v[48:49], v[192:193], v[218:219], v[48:49]
	v_pk_fma_f32 v[50:51], v[194:195], v[220:221], v[50:51]
	v_pk_fma_f32 v[52:53], v[100:101], v[210:211], v[52:53]
	v_pk_fma_f32 v[54:55], v[102:103], v[212:213], v[54:55]
	v_pk_fma_f32 v[56:57], v[104:105], v[214:215], v[56:57]
	v_pk_fma_f32 v[58:59], v[106:107], v[216:217], v[58:59]
	v_pk_fma_f32 v[60:61], v[108:109], v[218:219], v[60:61]
	v_pk_fma_f32 v[62:63], v[110:111], v[220:221], v[62:63]
	v_pk_fma_f32 v[64:65], v[112:113], v[210:211], v[64:65]
	v_pk_fma_f32 v[66:67], v[114:115], v[212:213], v[66:67]
	v_pk_fma_f32 v[68:69], v[116:117], v[214:215], v[68:69]
	v_pk_fma_f32 v[70:71], v[118:119], v[216:217], v[70:71]
	v_pk_fma_f32 v[72:73], v[120:121], v[218:219], v[72:73]
	v_pk_fma_f32 v[74:75], v[122:123], v[220:221], v[74:75]
	v_pk_fma_f32 v[76:77], v[124:125], v[210:211], v[76:77]
	v_pk_fma_f32 v[78:79], v[126:127], v[212:213], v[78:79]
	v_pk_fma_f32 v[80:81], v[128:129], v[214:215], v[80:81]
	v_pk_fma_f32 v[82:83], v[130:131], v[216:217], v[82:83]
	v_pk_fma_f32 v[84:85], v[132:133], v[218:219], v[84:85]
	v_pk_fma_f32 v[86:87], v[134:135], v[220:221], v[86:87]
	v_pk_fma_f32 v[88:89], v[136:137], v[210:211], v[88:89]
	v_pk_fma_f32 v[90:91], v[138:139], v[212:213], v[90:91]
	v_pk_fma_f32 v[92:93], v[140:141], v[214:215], v[92:93]
	v_pk_fma_f32 v[94:95], v[142:143], v[216:217], v[94:95]
	v_pk_fma_f32 v[96:97], v[144:145], v[218:219], v[96:97]
	v_pk_fma_f32 v[98:99], v[146:147], v[220:221], v[98:99]
	ds_read_b128 v[210:213], v208 offset:2048
	ds_read_b128 v[214:217], v208 offset:3072
	ds_read_b128 v[218:221], v208 offset:4096
	s_waitcnt vmcnt(9)
	s_add_i32 s52, s41, -2
	s_cmp_lt_i32 s52, 0
	s_cbranch_scc1 .Lcv_z28_zero
	v_lshlrev_b32_e32 v148, 16, v234
	v_and_b32_e32 v149, 0xffff0000, v234
	v_lshlrev_b32_e32 v150, 16, v235
	v_and_b32_e32 v151, 0xffff0000, v235
	v_lshlrev_b32_e32 v152, 16, v236
	v_and_b32_e32 v153, 0xffff0000, v236
	v_lshlrev_b32_e32 v154, 16, v237
	v_and_b32_e32 v155, 0xffff0000, v237
	v_lshlrev_b32_e32 v156, 16, v238
	v_and_b32_e32 v157, 0xffff0000, v238
	v_lshlrev_b32_e32 v158, 16, v239
	v_and_b32_e32 v159, 0xffff0000, v239
	s_branch .Lcv_z28_done

.Lcv_z28_done:
	s_add_i32 s52, s41, 2
	s_mulk_i32 s52, 0x600
	v_add_u32_e32 v196, s52, v3
	global_load_dwordx2 v[234:235], v196, s[38:39]
	global_load_dwordx2 v[236:237], v196, s[38:39] offset:512
	global_load_dwordx2 v[238:239], v196, s[38:39] offset:1024
	s_waitcnt lgkmcnt(3)
	v_pk_fma_f32 v[4:5], v[160:161], v[222:223], v[4:5]
	v_pk_fma_f32 v[6:7], v[162:163], v[224:225], v[6:7]
	v_pk_fma_f32 v[8:9], v[164:165], v[226:227], v[8:9]
	v_pk_fma_f32 v[10:11], v[166:167], v[228:229], v[10:11]
	v_pk_fma_f32 v[12:13], v[168:169], v[230:231], v[12:13]
	v_pk_fma_f32 v[14:15], v[170:171], v[232:233], v[14:15]
	v_pk_fma_f32 v[16:17], v[172:173], v[222:223], v[16:17]
	v_pk_fma_f32 v[18:19], v[174:175], v[224:225], v[18:19]
	v_pk_fma_f32 v[20:21], v[176:177], v[226:227], v[20:21]
	v_pk_fma_f32 v[22:23], v[178:179], v[228:229], v[22:23]
	v_pk_fma_f32 v[24:25], v[180:181], v[230:231], v[24:25]
	v_pk_fma_f32 v[26:27], v[182:183], v[232:233], v[26:27]
	v_pk_fma_f32 v[28:29], v[184:185], v[222:223], v[28:29]
	v_pk_fma_f32 v[30:31], v[186:187], v[224:225], v[30:31]
	v_pk_fma_f32 v[32:33], v[188:189], v[226:227], v[32:33]
	v_pk_fma_f32 v[34:35], v[190:191], v[228:229], v[34:35]
	v_pk_fma_f32 v[36:37], v[192:193], v[230:231], v[36:37]
	v_pk_fma_f32 v[38:39], v[194:195], v[232:233], v[38:39]
	v_pk_fma_f32 v[40:41], v[100:101], v[222:223], v[40:41]
	v_pk_fma_f32 v[42:43], v[102:103], v[224:225], v[42:43]
	v_pk_fma_f32 v[44:45], v[104:105], v[226:227], v[44:45]
	v_pk_fma_f32 v[46:47], v[106:107], v[228:229], v[46:47]
	v_pk_fma_f32 v[48:49], v[108:109], v[230:231], v[48:49]
	v_pk_fma_f32 v[50:51], v[110:111], v[232:233], v[50:51]
	v_pk_fma_f32 v[52:53], v[112:113], v[222:223], v[52:53]
	v_pk_fma_f32 v[54:55], v[114:115], v[224:225], v[54:55]
	v_pk_fma_f32 v[56:57], v[116:117], v[226:227], v[56:57]
	v_pk_fma_f32 v[58:59], v[118:119], v[228:229], v[58:59]
	v_pk_fma_f32 v[60:61], v[120:121], v[230:231], v[60:61]
	v_pk_fma_f32 v[62:63], v[122:123], v[232:233], v[62:63]
	v_pk_fma_f32 v[64:65], v[124:125], v[222:223], v[64:65]
	v_pk_fma_f32 v[66:67], v[126:127], v[224:225], v[66:67]
	v_pk_fma_f32 v[68:69], v[128:129], v[226:227], v[68:69]
	v_pk_fma_f32 v[70:71], v[130:131], v[228:229], v[70:71]
	v_pk_fma_f32 v[72:73], v[132:133], v[230:231], v[72:73]
	v_pk_fma_f32 v[74:75], v[134:135], v[232:233], v[74:75]
	v_pk_fma_f32 v[76:77], v[136:137], v[222:223], v[76:77]
	v_pk_fma_f32 v[78:79], v[138:139], v[224:225], v[78:79]
	v_pk_fma_f32 v[80:81], v[140:141], v[226:227], v[80:81]
	v_pk_fma_f32 v[82:83], v[142:143], v[228:229], v[82:83]
	v_pk_fma_f32 v[84:85], v[144:145], v[230:231], v[84:85]
	v_pk_fma_f32 v[86:87], v[146:147], v[232:233], v[86:87]
	v_pk_fma_f32 v[88:89], v[148:149], v[222:223], v[88:89]
	v_pk_fma_f32 v[90:91], v[150:151], v[224:225], v[90:91]
	v_pk_fma_f32 v[92:93], v[152:153], v[226:227], v[92:93]
	v_pk_fma_f32 v[94:95], v[154:155], v[228:229], v[94:95]
	v_pk_fma_f32 v[96:97], v[156:157], v[230:231], v[96:97]
	v_pk_fma_f32 v[98:99], v[158:159], v[232:233], v[98:99]
	ds_read_b128 v[222:225], v208 offset:5120
	ds_read_b128 v[226:229], v208 offset:6144
	ds_read_b128 v[230:233], v208 offset:7168
	s_waitcnt vmcnt(9)
	s_add_i32 s52, s41, -1
	s_cmp_lt_i32 s52, 0
	s_cbranch_scc1 .Lcv_z29_zero
	v_lshlrev_b32_e32 v160, 16, v240
	v_and_b32_e32 v161, 0xffff0000, v240
	v_lshlrev_b32_e32 v162, 16, v241
	v_and_b32_e32 v163, 0xffff0000, v241
	v_lshlrev_b32_e32 v164, 16, v242
	v_and_b32_e32 v165, 0xffff0000, v242
	v_lshlrev_b32_e32 v166, 16, v243
	v_and_b32_e32 v167, 0xffff0000, v243
	v_lshlrev_b32_e32 v168, 16, v244
	v_and_b32_e32 v169, 0xffff0000, v244
	v_lshlrev_b32_e32 v170, 16, v245
	v_and_b32_e32 v171, 0xffff0000, v245
	s_branch .Lcv_z29_done

.Lcv_z29_done:
	s_add_i32 s52, s41, 3
	s_mulk_i32 s52, 0x600
	v_add_u32_e32 v196, s52, v3
	global_load_dwordx2 v[240:241], v196, s[38:39]
	global_load_dwordx2 v[242:243], v196, s[38:39] offset:512
	global_load_dwordx2 v[244:245], v196, s[38:39] offset:1024
	s_waitcnt lgkmcnt(3)
	v_pk_fma_f32 v[4:5], v[172:173], v[210:211], v[4:5]
	v_pk_fma_f32 v[6:7], v[174:175], v[212:213], v[6:7]
	v_pk_fma_f32 v[8:9], v[176:177], v[214:215], v[8:9]
	v_pk_fma_f32 v[10:11], v[178:179], v[216:217], v[10:11]
	v_pk_fma_f32 v[12:13], v[180:181], v[218:219], v[12:13]
	v_pk_fma_f32 v[14:15], v[182:183], v[220:221], v[14:15]
	v_pk_fma_f32 v[16:17], v[184:185], v[210:211], v[16:17]
	v_pk_fma_f32 v[18:19], v[186:187], v[212:213], v[18:19]
	v_pk_fma_f32 v[20:21], v[188:189], v[214:215], v[20:21]
	v_pk_fma_f32 v[22:23], v[190:191], v[216:217], v[22:23]
	v_pk_fma_f32 v[24:25], v[192:193], v[218:219], v[24:25]
	v_pk_fma_f32 v[26:27], v[194:195], v[220:221], v[26:27]
	v_pk_fma_f32 v[28:29], v[100:101], v[210:211], v[28:29]
	v_pk_fma_f32 v[30:31], v[102:103], v[212:213], v[30:31]
	v_pk_fma_f32 v[32:33], v[104:105], v[214:215], v[32:33]
	v_pk_fma_f32 v[34:35], v[106:107], v[216:217], v[34:35]
	v_pk_fma_f32 v[36:37], v[108:109], v[218:219], v[36:37]
	v_pk_fma_f32 v[38:39], v[110:111], v[220:221], v[38:39]
	v_pk_fma_f32 v[40:41], v[112:113], v[210:211], v[40:41]
	v_pk_fma_f32 v[42:43], v[114:115], v[212:213], v[42:43]
	v_pk_fma_f32 v[44:45], v[116:117], v[214:215], v[44:45]
	v_pk_fma_f32 v[46:47], v[118:119], v[216:217], v[46:47]
	v_pk_fma_f32 v[48:49], v[120:121], v[218:219], v[48:49]
	v_pk_fma_f32 v[50:51], v[122:123], v[220:221], v[50:51]
	v_pk_fma_f32 v[52:53], v[124:125], v[210:211], v[52:53]
	v_pk_fma_f32 v[54:55], v[126:127], v[212:213], v[54:55]
	v_pk_fma_f32 v[56:57], v[128:129], v[214:215], v[56:57]
	v_pk_fma_f32 v[58:59], v[130:131], v[216:217], v[58:59]
	v_pk_fma_f32 v[60:61], v[132:133], v[218:219], v[60:61]
	v_pk_fma_f32 v[62:63], v[134:135], v[220:221], v[62:63]
	v_pk_fma_f32 v[64:65], v[136:137], v[210:211], v[64:65]
	v_pk_fma_f32 v[66:67], v[138:139], v[212:213], v[66:67]
	v_pk_fma_f32 v[68:69], v[140:141], v[214:215], v[68:69]
	v_pk_fma_f32 v[70:71], v[142:143], v[216:217], v[70:71]
	v_pk_fma_f32 v[72:73], v[144:145], v[218:219], v[72:73]
	v_pk_fma_f32 v[74:75], v[146:147], v[220:221], v[74:75]
	v_pk_fma_f32 v[76:77], v[148:149], v[210:211], v[76:77]
	v_pk_fma_f32 v[78:79], v[150:151], v[212:213], v[78:79]
	v_pk_fma_f32 v[80:81], v[152:153], v[214:215], v[80:81]
	v_pk_fma_f32 v[82:83], v[154:155], v[216:217], v[82:83]
	v_pk_fma_f32 v[84:85], v[156:157], v[218:219], v[84:85]
	v_pk_fma_f32 v[86:87], v[158:159], v[220:221], v[86:87]
	v_pk_fma_f32 v[88:89], v[160:161], v[210:211], v[88:89]
	v_pk_fma_f32 v[90:91], v[162:163], v[212:213], v[90:91]
	v_pk_fma_f32 v[92:93], v[164:165], v[214:215], v[92:93]
	v_pk_fma_f32 v[94:95], v[166:167], v[216:217], v[94:95]
	v_pk_fma_f32 v[96:97], v[168:169], v[218:219], v[96:97]
	v_pk_fma_f32 v[98:99], v[170:171], v[220:221], v[98:99]
	ds_read_b128 v[210:213], v208 offset:8192
	ds_read_b128 v[214:217], v208 offset:9216
	ds_read_b128 v[218:221], v208 offset:10240
	s_waitcnt vmcnt(9)
	v_lshlrev_b32_e32 v172, 16, v246
	v_and_b32_e32 v173, 0xffff0000, v246
	v_lshlrev_b32_e32 v174, 16, v247
	v_and_b32_e32 v175, 0xffff0000, v247
	v_lshlrev_b32_e32 v176, 16, v248
	v_and_b32_e32 v177, 0xffff0000, v248
	v_lshlrev_b32_e32 v178, 16, v249
	v_and_b32_e32 v179, 0xffff0000, v249
	v_lshlrev_b32_e32 v180, 16, v250
	v_and_b32_e32 v181, 0xffff0000, v250
	v_lshlrev_b32_e32 v182, 16, v251
	v_and_b32_e32 v183, 0xffff0000, v251
	s_add_i32 s52, s41, 4
	s_mulk_i32 s52, 0x600
	v_add_u32_e32 v196, s52, v3
	global_load_dwordx2 v[246:247], v196, s[38:39]
	global_load_dwordx2 v[248:249], v196, s[38:39] offset:512
	global_load_dwordx2 v[250:251], v196, s[38:39] offset:1024
	s_waitcnt lgkmcnt(3)
	v_pk_fma_f32 v[4:5], v[184:185], v[222:223], v[4:5]
	v_pk_fma_f32 v[6:7], v[186:187], v[224:225], v[6:7]
	v_pk_fma_f32 v[8:9], v[188:189], v[226:227], v[8:9]
	v_pk_fma_f32 v[10:11], v[190:191], v[228:229], v[10:11]
	v_pk_fma_f32 v[12:13], v[192:193], v[230:231], v[12:13]
	v_pk_fma_f32 v[14:15], v[194:195], v[232:233], v[14:15]
	v_pk_fma_f32 v[16:17], v[100:101], v[222:223], v[16:17]
	v_pk_fma_f32 v[18:19], v[102:103], v[224:225], v[18:19]
	v_pk_fma_f32 v[20:21], v[104:105], v[226:227], v[20:21]
	v_pk_fma_f32 v[22:23], v[106:107], v[228:229], v[22:23]
	v_pk_fma_f32 v[24:25], v[108:109], v[230:231], v[24:25]
	v_pk_fma_f32 v[26:27], v[110:111], v[232:233], v[26:27]
	v_pk_fma_f32 v[28:29], v[112:113], v[222:223], v[28:29]
	v_pk_fma_f32 v[30:31], v[114:115], v[224:225], v[30:31]
	v_pk_fma_f32 v[32:33], v[116:117], v[226:227], v[32:33]
	v_pk_fma_f32 v[34:35], v[118:119], v[228:229], v[34:35]
	v_pk_fma_f32 v[36:37], v[120:121], v[230:231], v[36:37]
	v_pk_fma_f32 v[38:39], v[122:123], v[232:233], v[38:39]
	v_pk_fma_f32 v[40:41], v[124:125], v[222:223], v[40:41]
	v_pk_fma_f32 v[42:43], v[126:127], v[224:225], v[42:43]
	v_pk_fma_f32 v[44:45], v[128:129], v[226:227], v[44:45]
	v_pk_fma_f32 v[46:47], v[130:131], v[228:229], v[46:47]
	v_pk_fma_f32 v[48:49], v[132:133], v[230:231], v[48:49]
	v_pk_fma_f32 v[50:51], v[134:135], v[232:233], v[50:51]
	v_pk_fma_f32 v[52:53], v[136:137], v[222:223], v[52:53]
	v_pk_fma_f32 v[54:55], v[138:139], v[224:225], v[54:55]
	v_pk_fma_f32 v[56:57], v[140:141], v[226:227], v[56:57]
	v_pk_fma_f32 v[58:59], v[142:143], v[228:229], v[58:59]
	v_pk_fma_f32 v[60:61], v[144:145], v[230:231], v[60:61]
	v_pk_fma_f32 v[62:63], v[146:147], v[232:233], v[62:63]
	v_pk_fma_f32 v[64:65], v[148:149], v[222:223], v[64:65]
	v_pk_fma_f32 v[66:67], v[150:151], v[224:225], v[66:67]
	v_pk_fma_f32 v[68:69], v[152:153], v[226:227], v[68:69]
	v_pk_fma_f32 v[70:71], v[154:155], v[228:229], v[70:71]
	v_pk_fma_f32 v[72:73], v[156:157], v[230:231], v[72:73]
	v_pk_fma_f32 v[74:75], v[158:159], v[232:233], v[74:75]
	v_pk_fma_f32 v[76:77], v[160:161], v[222:223], v[76:77]
	v_pk_fma_f32 v[78:79], v[162:163], v[224:225], v[78:79]
	v_pk_fma_f32 v[80:81], v[164:165], v[226:227], v[80:81]
	v_pk_fma_f32 v[82:83], v[166:167], v[228:229], v[82:83]
	v_pk_fma_f32 v[84:85], v[168:169], v[230:231], v[84:85]
	v_pk_fma_f32 v[86:87], v[170:171], v[232:233], v[86:87]
	v_pk_fma_f32 v[88:89], v[172:173], v[222:223], v[88:89]
	v_pk_fma_f32 v[90:91], v[174:175], v[224:225], v[90:91]
	v_pk_fma_f32 v[92:93], v[176:177], v[226:227], v[92:93]
	v_pk_fma_f32 v[94:95], v[178:179], v[228:229], v[94:95]
	v_pk_fma_f32 v[96:97], v[180:181], v[230:231], v[96:97]
	v_pk_fma_f32 v[98:99], v[182:183], v[232:233], v[98:99]
	ds_read_b128 v[222:225], v208 offset:11264
	ds_read_b128 v[226:229], v208 offset:12288
	ds_read_b128 v[230:233], v208 offset:13312
	s_waitcnt vmcnt(9)
	v_lshlrev_b32_e32 v184, 16, v204
	v_and_b32_e32 v185, 0xffff0000, v204
	v_lshlrev_b32_e32 v186, 16, v205
	v_and_b32_e32 v187, 0xffff0000, v205
	v_lshlrev_b32_e32 v188, 16, v206
	v_and_b32_e32 v189, 0xffff0000, v206
	v_lshlrev_b32_e32 v190, 16, v207
	v_and_b32_e32 v191, 0xffff0000, v207
	v_lshlrev_b32_e32 v192, 16, v252
	v_and_b32_e32 v193, 0xffff0000, v252
	v_lshlrev_b32_e32 v194, 16, v253
	v_and_b32_e32 v195, 0xffff0000, v253
	s_add_i32 s52, s41, 5
	s_mulk_i32 s52, 0x600
	v_add_u32_e32 v196, s52, v3
	global_load_dwordx2 v[204:205], v196, s[38:39]
	global_load_dwordx2 v[206:207], v196, s[38:39] offset:512
	global_load_dwordx2 v[252:253], v196, s[38:39] offset:1024
	s_waitcnt lgkmcnt(3)
	v_pk_fma_f32 v[4:5], v[100:101], v[210:211], v[4:5]
	v_pk_fma_f32 v[6:7], v[102:103], v[212:213], v[6:7]
	v_pk_fma_f32 v[8:9], v[104:105], v[214:215], v[8:9]
	v_pk_fma_f32 v[10:11], v[106:107], v[216:217], v[10:11]
	v_pk_fma_f32 v[12:13], v[108:109], v[218:219], v[12:13]
	v_pk_fma_f32 v[14:15], v[110:111], v[220:221], v[14:15]
	v_pk_fma_f32 v[16:17], v[112:113], v[210:211], v[16:17]
	v_pk_fma_f32 v[18:19], v[114:115], v[212:213], v[18:19]
	v_pk_fma_f32 v[20:21], v[116:117], v[214:215], v[20:21]
	v_pk_fma_f32 v[22:23], v[118:119], v[216:217], v[22:23]
	v_pk_fma_f32 v[24:25], v[120:121], v[218:219], v[24:25]
	v_pk_fma_f32 v[26:27], v[122:123], v[220:221], v[26:27]
	v_pk_fma_f32 v[28:29], v[124:125], v[210:211], v[28:29]
	v_pk_fma_f32 v[30:31], v[126:127], v[212:213], v[30:31]
	v_pk_fma_f32 v[32:33], v[128:129], v[214:215], v[32:33]
	v_pk_fma_f32 v[34:35], v[130:131], v[216:217], v[34:35]
	v_pk_fma_f32 v[36:37], v[132:133], v[218:219], v[36:37]
	v_pk_fma_f32 v[38:39], v[134:135], v[220:221], v[38:39]
	v_pk_fma_f32 v[40:41], v[136:137], v[210:211], v[40:41]
	v_pk_fma_f32 v[42:43], v[138:139], v[212:213], v[42:43]
	v_pk_fma_f32 v[44:45], v[140:141], v[214:215], v[44:45]
	v_pk_fma_f32 v[46:47], v[142:143], v[216:217], v[46:47]
	v_pk_fma_f32 v[48:49], v[144:145], v[218:219], v[48:49]
	v_pk_fma_f32 v[50:51], v[146:147], v[220:221], v[50:51]
	v_pk_fma_f32 v[52:53], v[148:149], v[210:211], v[52:53]
	v_pk_fma_f32 v[54:55], v[150:151], v[212:213], v[54:55]
	v_pk_fma_f32 v[56:57], v[152:153], v[214:215], v[56:57]
	v_pk_fma_f32 v[58:59], v[154:155], v[216:217], v[58:59]
	v_pk_fma_f32 v[60:61], v[156:157], v[218:219], v[60:61]
	v_pk_fma_f32 v[62:63], v[158:159], v[220:221], v[62:63]
	v_pk_fma_f32 v[64:65], v[160:161], v[210:211], v[64:65]
	v_pk_fma_f32 v[66:67], v[162:163], v[212:213], v[66:67]
	v_pk_fma_f32 v[68:69], v[164:165], v[214:215], v[68:69]
	v_pk_fma_f32 v[70:71], v[166:167], v[216:217], v[70:71]
	v_pk_fma_f32 v[72:73], v[168:169], v[218:219], v[72:73]
	v_pk_fma_f32 v[74:75], v[170:171], v[220:221], v[74:75]
	v_pk_fma_f32 v[76:77], v[172:173], v[210:211], v[76:77]
	v_pk_fma_f32 v[78:79], v[174:175], v[212:213], v[78:79]
	v_pk_fma_f32 v[80:81], v[176:177], v[214:215], v[80:81]
	v_pk_fma_f32 v[82:83], v[178:179], v[216:217], v[82:83]
	v_pk_fma_f32 v[84:85], v[180:181], v[218:219], v[84:85]
	v_pk_fma_f32 v[86:87], v[182:183], v[220:221], v[86:87]
	v_pk_fma_f32 v[88:89], v[184:185], v[210:211], v[88:89]
	v_pk_fma_f32 v[90:91], v[186:187], v[212:213], v[90:91]
	v_pk_fma_f32 v[92:93], v[188:189], v[214:215], v[92:93]
	v_pk_fma_f32 v[94:95], v[190:191], v[216:217], v[94:95]
	v_pk_fma_f32 v[96:97], v[192:193], v[218:219], v[96:97]
	v_pk_fma_f32 v[98:99], v[194:195], v[220:221], v[98:99]
	ds_read_b128 v[210:213], v208 offset:14336
	ds_read_b128 v[214:217], v208 offset:15360
	ds_read_b128 v[218:221], v208 offset:16384
	s_waitcnt vmcnt(9)
	v_lshlrev_b32_e32 v100, 16, v234
	v_and_b32_e32 v101, 0xffff0000, v234
	v_lshlrev_b32_e32 v102, 16, v235
	v_and_b32_e32 v103, 0xffff0000, v235
	v_lshlrev_b32_e32 v104, 16, v236
	v_and_b32_e32 v105, 0xffff0000, v236
	v_lshlrev_b32_e32 v106, 16, v237
	v_and_b32_e32 v107, 0xffff0000, v237
	v_lshlrev_b32_e32 v108, 16, v238
	v_and_b32_e32 v109, 0xffff0000, v238
	v_lshlrev_b32_e32 v110, 16, v239
	v_and_b32_e32 v111, 0xffff0000, v239
	s_add_i32 s52, s41, 6
	s_mulk_i32 s52, 0x600
	v_add_u32_e32 v196, s52, v3
	global_load_dwordx2 v[234:235], v196, s[38:39]
	global_load_dwordx2 v[236:237], v196, s[38:39] offset:512
	global_load_dwordx2 v[238:239], v196, s[38:39] offset:1024
	s_waitcnt lgkmcnt(3)
	v_pk_fma_f32 v[4:5], v[112:113], v[222:223], v[4:5]
	v_pk_fma_f32 v[6:7], v[114:115], v[224:225], v[6:7]
	v_pk_fma_f32 v[8:9], v[116:117], v[226:227], v[8:9]
	v_pk_fma_f32 v[10:11], v[118:119], v[228:229], v[10:11]
	v_pk_fma_f32 v[12:13], v[120:121], v[230:231], v[12:13]
	v_pk_fma_f32 v[14:15], v[122:123], v[232:233], v[14:15]
	v_pk_fma_f32 v[16:17], v[124:125], v[222:223], v[16:17]
	v_pk_fma_f32 v[18:19], v[126:127], v[224:225], v[18:19]
	v_pk_fma_f32 v[20:21], v[128:129], v[226:227], v[20:21]
	v_pk_fma_f32 v[22:23], v[130:131], v[228:229], v[22:23]
	v_pk_fma_f32 v[24:25], v[132:133], v[230:231], v[24:25]
	v_pk_fma_f32 v[26:27], v[134:135], v[232:233], v[26:27]
	v_pk_fma_f32 v[28:29], v[136:137], v[222:223], v[28:29]
	v_pk_fma_f32 v[30:31], v[138:139], v[224:225], v[30:31]
	v_pk_fma_f32 v[32:33], v[140:141], v[226:227], v[32:33]
	v_pk_fma_f32 v[34:35], v[142:143], v[228:229], v[34:35]
	v_pk_fma_f32 v[36:37], v[144:145], v[230:231], v[36:37]
	v_pk_fma_f32 v[38:39], v[146:147], v[232:233], v[38:39]
	v_pk_fma_f32 v[40:41], v[148:149], v[222:223], v[40:41]
	v_pk_fma_f32 v[42:43], v[150:151], v[224:225], v[42:43]
	v_pk_fma_f32 v[44:45], v[152:153], v[226:227], v[44:45]
	v_pk_fma_f32 v[46:47], v[154:155], v[228:229], v[46:47]
	v_pk_fma_f32 v[48:49], v[156:157], v[230:231], v[48:49]
	v_pk_fma_f32 v[50:51], v[158:159], v[232:233], v[50:51]
	v_pk_fma_f32 v[52:53], v[160:161], v[222:223], v[52:53]
	v_pk_fma_f32 v[54:55], v[162:163], v[224:225], v[54:55]
	v_pk_fma_f32 v[56:57], v[164:165], v[226:227], v[56:57]
	v_pk_fma_f32 v[58:59], v[166:167], v[228:229], v[58:59]
	v_pk_fma_f32 v[60:61], v[168:169], v[230:231], v[60:61]
	v_pk_fma_f32 v[62:63], v[170:171], v[232:233], v[62:63]
	v_pk_fma_f32 v[64:65], v[172:173], v[222:223], v[64:65]
	v_pk_fma_f32 v[66:67], v[174:175], v[224:225], v[66:67]
	v_pk_fma_f32 v[68:69], v[176:177], v[226:227], v[68:69]
	v_pk_fma_f32 v[70:71], v[178:179], v[228:229], v[70:71]
	v_pk_fma_f32 v[72:73], v[180:181], v[230:231], v[72:73]
	v_pk_fma_f32 v[74:75], v[182:183], v[232:233], v[74:75]
	v_pk_fma_f32 v[76:77], v[184:185], v[222:223], v[76:77]
	v_pk_fma_f32 v[78:79], v[186:187], v[224:225], v[78:79]
	v_pk_fma_f32 v[80:81], v[188:189], v[226:227], v[80:81]
	v_pk_fma_f32 v[82:83], v[190:191], v[228:229], v[82:83]
	v_pk_fma_f32 v[84:85], v[192:193], v[230:231], v[84:85]
	v_pk_fma_f32 v[86:87], v[194:195], v[232:233], v[86:87]
	v_pk_fma_f32 v[88:89], v[100:101], v[222:223], v[88:89]
	v_pk_fma_f32 v[90:91], v[102:103], v[224:225], v[90:91]
	v_pk_fma_f32 v[92:93], v[104:105], v[226:227], v[92:93]
	v_pk_fma_f32 v[94:95], v[106:107], v[228:229], v[94:95]
	v_pk_fma_f32 v[96:97], v[108:109], v[230:231], v[96:97]
	v_pk_fma_f32 v[98:99], v[110:111], v[232:233], v[98:99]
	ds_read_b128 v[222:225], v208 offset:17408
	ds_read_b128 v[226:229], v208 offset:18432
	ds_read_b128 v[230:233], v208 offset:19456
	s_waitcnt vmcnt(9)
	v_lshlrev_b32_e32 v112, 16, v240
	v_and_b32_e32 v113, 0xffff0000, v240
	v_lshlrev_b32_e32 v114, 16, v241
	v_and_b32_e32 v115, 0xffff0000, v241
	v_lshlrev_b32_e32 v116, 16, v242
	v_and_b32_e32 v117, 0xffff0000, v242
	v_lshlrev_b32_e32 v118, 16, v243
	v_and_b32_e32 v119, 0xffff0000, v243
	v_lshlrev_b32_e32 v120, 16, v244
	v_and_b32_e32 v121, 0xffff0000, v244
	v_lshlrev_b32_e32 v122, 16, v245
	v_and_b32_e32 v123, 0xffff0000, v245
	s_add_i32 s52, s41, 7
	s_mulk_i32 s52, 0x600
	v_add_u32_e32 v196, s52, v3
	global_load_dwordx2 v[240:241], v196, s[38:39]
	global_load_dwordx2 v[242:243], v196, s[38:39] offset:512
	global_load_dwordx2 v[244:245], v196, s[38:39] offset:1024
	s_waitcnt lgkmcnt(3)
	v_pk_fma_f32 v[4:5], v[124:125], v[210:211], v[4:5]
	v_pk_fma_f32 v[6:7], v[126:127], v[212:213], v[6:7]
	v_pk_fma_f32 v[8:9], v[128:129], v[214:215], v[8:9]
	v_pk_fma_f32 v[10:11], v[130:131], v[216:217], v[10:11]
	v_pk_fma_f32 v[12:13], v[132:133], v[218:219], v[12:13]
	v_pk_fma_f32 v[14:15], v[134:135], v[220:221], v[14:15]
	v_pk_fma_f32 v[16:17], v[136:137], v[210:211], v[16:17]
	v_pk_fma_f32 v[18:19], v[138:139], v[212:213], v[18:19]
	v_pk_fma_f32 v[20:21], v[140:141], v[214:215], v[20:21]
	v_pk_fma_f32 v[22:23], v[142:143], v[216:217], v[22:23]
	v_pk_fma_f32 v[24:25], v[144:145], v[218:219], v[24:25]
	v_pk_fma_f32 v[26:27], v[146:147], v[220:221], v[26:27]
	v_pk_fma_f32 v[28:29], v[148:149], v[210:211], v[28:29]
	v_pk_fma_f32 v[30:31], v[150:151], v[212:213], v[30:31]
	v_pk_fma_f32 v[32:33], v[152:153], v[214:215], v[32:33]
	v_pk_fma_f32 v[34:35], v[154:155], v[216:217], v[34:35]
	v_pk_fma_f32 v[36:37], v[156:157], v[218:219], v[36:37]
	v_pk_fma_f32 v[38:39], v[158:159], v[220:221], v[38:39]
	v_pk_fma_f32 v[40:41], v[160:161], v[210:211], v[40:41]
	v_pk_fma_f32 v[42:43], v[162:163], v[212:213], v[42:43]
	v_pk_fma_f32 v[44:45], v[164:165], v[214:215], v[44:45]
	v_pk_fma_f32 v[46:47], v[166:167], v[216:217], v[46:47]
	v_pk_fma_f32 v[48:49], v[168:169], v[218:219], v[48:49]
	v_pk_fma_f32 v[50:51], v[170:171], v[220:221], v[50:51]
	v_pk_fma_f32 v[52:53], v[172:173], v[210:211], v[52:53]
	v_pk_fma_f32 v[54:55], v[174:175], v[212:213], v[54:55]
	v_pk_fma_f32 v[56:57], v[176:177], v[214:215], v[56:57]
	v_pk_fma_f32 v[58:59], v[178:179], v[216:217], v[58:59]
	v_pk_fma_f32 v[60:61], v[180:181], v[218:219], v[60:61]
	v_pk_fma_f32 v[62:63], v[182:183], v[220:221], v[62:63]
	v_pk_fma_f32 v[64:65], v[184:185], v[210:211], v[64:65]
	v_pk_fma_f32 v[66:67], v[186:187], v[212:213], v[66:67]
	v_pk_fma_f32 v[68:69], v[188:189], v[214:215], v[68:69]
	v_pk_fma_f32 v[70:71], v[190:191], v[216:217], v[70:71]
	v_pk_fma_f32 v[72:73], v[192:193], v[218:219], v[72:73]
	v_pk_fma_f32 v[74:75], v[194:195], v[220:221], v[74:75]
	v_pk_fma_f32 v[76:77], v[100:101], v[210:211], v[76:77]
	v_pk_fma_f32 v[78:79], v[102:103], v[212:213], v[78:79]
	v_pk_fma_f32 v[80:81], v[104:105], v[214:215], v[80:81]
	v_pk_fma_f32 v[82:83], v[106:107], v[216:217], v[82:83]
	v_pk_fma_f32 v[84:85], v[108:109], v[218:219], v[84:85]
	v_pk_fma_f32 v[86:87], v[110:111], v[220:221], v[86:87]
	v_pk_fma_f32 v[88:89], v[112:113], v[210:211], v[88:89]
	v_pk_fma_f32 v[90:91], v[114:115], v[212:213], v[90:91]
	v_pk_fma_f32 v[92:93], v[116:117], v[214:215], v[92:93]
	v_pk_fma_f32 v[94:95], v[118:119], v[216:217], v[94:95]
	v_pk_fma_f32 v[96:97], v[120:121], v[218:219], v[96:97]
	v_pk_fma_f32 v[98:99], v[122:123], v[220:221], v[98:99]
	ds_read_b128 v[210:213], v208 offset:20480
	ds_read_b128 v[214:217], v208 offset:21504
	ds_read_b128 v[218:221], v208 offset:22528
	s_waitcnt vmcnt(9)
	v_lshlrev_b32_e32 v124, 16, v246
	v_and_b32_e32 v125, 0xffff0000, v246
	v_lshlrev_b32_e32 v126, 16, v247
	v_and_b32_e32 v127, 0xffff0000, v247
	v_lshlrev_b32_e32 v128, 16, v248
	v_and_b32_e32 v129, 0xffff0000, v248
	v_lshlrev_b32_e32 v130, 16, v249
	v_and_b32_e32 v131, 0xffff0000, v249
	v_lshlrev_b32_e32 v132, 16, v250
	v_and_b32_e32 v133, 0xffff0000, v250
	v_lshlrev_b32_e32 v134, 16, v251
	v_and_b32_e32 v135, 0xffff0000, v251
	s_waitcnt lgkmcnt(3)
	v_pk_fma_f32 v[4:5], v[136:137], v[222:223], v[4:5]
	v_pk_fma_f32 v[6:7], v[138:139], v[224:225], v[6:7]
	v_pk_fma_f32 v[8:9], v[140:141], v[226:227], v[8:9]
	v_pk_fma_f32 v[10:11], v[142:143], v[228:229], v[10:11]
	v_pk_fma_f32 v[12:13], v[144:145], v[230:231], v[12:13]
	v_pk_fma_f32 v[14:15], v[146:147], v[232:233], v[14:15]
	v_pk_fma_f32 v[16:17], v[148:149], v[222:223], v[16:17]
	v_pk_fma_f32 v[18:19], v[150:151], v[224:225], v[18:19]
	v_pk_fma_f32 v[20:21], v[152:153], v[226:227], v[20:21]
	v_pk_fma_f32 v[22:23], v[154:155], v[228:229], v[22:23]
	v_pk_fma_f32 v[24:25], v[156:157], v[230:231], v[24:25]
	v_pk_fma_f32 v[26:27], v[158:159], v[232:233], v[26:27]
	v_pk_fma_f32 v[28:29], v[160:161], v[222:223], v[28:29]
	v_pk_fma_f32 v[30:31], v[162:163], v[224:225], v[30:31]
	v_pk_fma_f32 v[32:33], v[164:165], v[226:227], v[32:33]
	v_pk_fma_f32 v[34:35], v[166:167], v[228:229], v[34:35]
	v_pk_fma_f32 v[36:37], v[168:169], v[230:231], v[36:37]
	v_pk_fma_f32 v[38:39], v[170:171], v[232:233], v[38:39]
	v_pk_fma_f32 v[40:41], v[172:173], v[222:223], v[40:41]
	v_pk_fma_f32 v[42:43], v[174:175], v[224:225], v[42:43]
	v_pk_fma_f32 v[44:45], v[176:177], v[226:227], v[44:45]
	v_pk_fma_f32 v[46:47], v[178:179], v[228:229], v[46:47]
	v_pk_fma_f32 v[48:49], v[180:181], v[230:231], v[48:49]
	v_pk_fma_f32 v[50:51], v[182:183], v[232:233], v[50:51]
	v_pk_fma_f32 v[52:53], v[184:185], v[222:223], v[52:53]
	v_pk_fma_f32 v[54:55], v[186:187], v[224:225], v[54:55]
	v_pk_fma_f32 v[56:57], v[188:189], v[226:227], v[56:57]
	v_pk_fma_f32 v[58:59], v[190:191], v[228:229], v[58:59]
	v_pk_fma_f32 v[60:61], v[192:193], v[230:231], v[60:61]
	v_pk_fma_f32 v[62:63], v[194:195], v[232:233], v[62:63]
	v_pk_fma_f32 v[64:65], v[100:101], v[222:223], v[64:65]
	v_pk_fma_f32 v[66:67], v[102:103], v[224:225], v[66:67]
	v_pk_fma_f32 v[68:69], v[104:105], v[226:227], v[68:69]
	v_pk_fma_f32 v[70:71], v[106:107], v[228:229], v[70:71]
	v_pk_fma_f32 v[72:73], v[108:109], v[230:231], v[72:73]
	v_pk_fma_f32 v[74:75], v[110:111], v[232:233], v[74:75]
	v_pk_fma_f32 v[76:77], v[112:113], v[222:223], v[76:77]
	v_pk_fma_f32 v[78:79], v[114:115], v[224:225], v[78:79]
	v_pk_fma_f32 v[80:81], v[116:117], v[226:227], v[80:81]
	v_pk_fma_f32 v[82:83], v[118:119], v[228:229], v[82:83]
	v_pk_fma_f32 v[84:85], v[120:121], v[230:231], v[84:85]
	v_pk_fma_f32 v[86:87], v[122:123], v[232:233], v[86:87]
	v_pk_fma_f32 v[88:89], v[124:125], v[222:223], v[88:89]
	v_pk_fma_f32 v[90:91], v[126:127], v[224:225], v[90:91]
	v_pk_fma_f32 v[92:93], v[128:129], v[226:227], v[92:93]
	v_pk_fma_f32 v[94:95], v[130:131], v[228:229], v[94:95]
	v_pk_fma_f32 v[96:97], v[132:133], v[230:231], v[96:97]
	v_pk_fma_f32 v[98:99], v[134:135], v[232:233], v[98:99]
	ds_read_b128 v[222:225], v208 offset:23552
	ds_read_b128 v[226:229], v208 offset:24576
	ds_read_b128 v[230:233], v208 offset:25600
	s_waitcnt vmcnt(6)
	v_lshlrev_b32_e32 v136, 16, v204
	v_and_b32_e32 v137, 0xffff0000, v204
	v_lshlrev_b32_e32 v138, 16, v205
	v_and_b32_e32 v139, 0xffff0000, v205
	v_lshlrev_b32_e32 v140, 16, v206
	v_and_b32_e32 v141, 0xffff0000, v206
	v_lshlrev_b32_e32 v142, 16, v207
	v_and_b32_e32 v143, 0xffff0000, v207
	v_lshlrev_b32_e32 v144, 16, v252
	v_and_b32_e32 v145, 0xffff0000, v252
	v_lshlrev_b32_e32 v146, 16, v253
	v_and_b32_e32 v147, 0xffff0000, v253
	s_waitcnt lgkmcnt(3)
	v_pk_fma_f32 v[4:5], v[148:149], v[210:211], v[4:5]
	v_pk_fma_f32 v[6:7], v[150:151], v[212:213], v[6:7]
	v_pk_fma_f32 v[8:9], v[152:153], v[214:215], v[8:9]
	v_pk_fma_f32 v[10:11], v[154:155], v[216:217], v[10:11]
	v_pk_fma_f32 v[12:13], v[156:157], v[218:219], v[12:13]
	v_pk_fma_f32 v[14:15], v[158:159], v[220:221], v[14:15]
	v_pk_fma_f32 v[16:17], v[160:161], v[210:211], v[16:17]
	v_pk_fma_f32 v[18:19], v[162:163], v[212:213], v[18:19]
	v_pk_fma_f32 v[20:21], v[164:165], v[214:215], v[20:21]
	v_pk_fma_f32 v[22:23], v[166:167], v[216:217], v[22:23]
	v_pk_fma_f32 v[24:25], v[168:169], v[218:219], v[24:25]
	v_pk_fma_f32 v[26:27], v[170:171], v[220:221], v[26:27]
	v_pk_fma_f32 v[28:29], v[172:173], v[210:211], v[28:29]
	v_pk_fma_f32 v[30:31], v[174:175], v[212:213], v[30:31]
	v_pk_fma_f32 v[32:33], v[176:177], v[214:215], v[32:33]
	v_pk_fma_f32 v[34:35], v[178:179], v[216:217], v[34:35]
	v_pk_fma_f32 v[36:37], v[180:181], v[218:219], v[36:37]
	v_pk_fma_f32 v[38:39], v[182:183], v[220:221], v[38:39]
	v_pk_fma_f32 v[40:41], v[184:185], v[210:211], v[40:41]
	v_pk_fma_f32 v[42:43], v[186:187], v[212:213], v[42:43]
	v_pk_fma_f32 v[44:45], v[188:189], v[214:215], v[44:45]
	v_pk_fma_f32 v[46:47], v[190:191], v[216:217], v[46:47]
	v_pk_fma_f32 v[48:49], v[192:193], v[218:219], v[48:49]
	v_pk_fma_f32 v[50:51], v[194:195], v[220:221], v[50:51]
	v_pk_fma_f32 v[52:53], v[100:101], v[210:211], v[52:53]
	v_pk_fma_f32 v[54:55], v[102:103], v[212:213], v[54:55]
	v_pk_fma_f32 v[56:57], v[104:105], v[214:215], v[56:57]
	v_pk_fma_f32 v[58:59], v[106:107], v[216:217], v[58:59]
	v_pk_fma_f32 v[60:61], v[108:109], v[218:219], v[60:61]
	v_pk_fma_f32 v[62:63], v[110:111], v[220:221], v[62:63]
	v_pk_fma_f32 v[64:65], v[112:113], v[210:211], v[64:65]
	v_pk_fma_f32 v[66:67], v[114:115], v[212:213], v[66:67]
	v_pk_fma_f32 v[68:69], v[116:117], v[214:215], v[68:69]
	v_pk_fma_f32 v[70:71], v[118:119], v[216:217], v[70:71]
	v_pk_fma_f32 v[72:73], v[120:121], v[218:219], v[72:73]
	v_pk_fma_f32 v[74:75], v[122:123], v[220:221], v[74:75]
	v_pk_fma_f32 v[76:77], v[124:125], v[210:211], v[76:77]
	v_pk_fma_f32 v[78:79], v[126:127], v[212:213], v[78:79]
	v_pk_fma_f32 v[80:81], v[128:129], v[214:215], v[80:81]
	v_pk_fma_f32 v[82:83], v[130:131], v[216:217], v[82:83]
	v_pk_fma_f32 v[84:85], v[132:133], v[218:219], v[84:85]
	v_pk_fma_f32 v[86:87], v[134:135], v[220:221], v[86:87]
	v_pk_fma_f32 v[88:89], v[136:137], v[210:211], v[88:89]
	v_pk_fma_f32 v[90:91], v[138:139], v[212:213], v[90:91]
	v_pk_fma_f32 v[92:93], v[140:141], v[214:215], v[92:93]
	v_pk_fma_f32 v[94:95], v[142:143], v[216:217], v[94:95]
	v_pk_fma_f32 v[96:97], v[144:145], v[218:219], v[96:97]
	v_pk_fma_f32 v[98:99], v[146:147], v[220:221], v[98:99]
	ds_read_b128 v[210:213], v208 offset:26624
	ds_read_b128 v[214:217], v208 offset:27648
	ds_read_b128 v[218:221], v208 offset:28672
	s_waitcnt vmcnt(3)
	v_lshlrev_b32_e32 v148, 16, v234
	v_and_b32_e32 v149, 0xffff0000, v234
	v_lshlrev_b32_e32 v150, 16, v235
	v_and_b32_e32 v151, 0xffff0000, v235
	v_lshlrev_b32_e32 v152, 16, v236
	v_and_b32_e32 v153, 0xffff0000, v236
	v_lshlrev_b32_e32 v154, 16, v237
	v_and_b32_e32 v155, 0xffff0000, v237
	v_lshlrev_b32_e32 v156, 16, v238
	v_and_b32_e32 v157, 0xffff0000, v238
	v_lshlrev_b32_e32 v158, 16, v239
	v_and_b32_e32 v159, 0xffff0000, v239
	s_waitcnt lgkmcnt(3)
	v_pk_fma_f32 v[4:5], v[160:161], v[222:223], v[4:5]
	v_pk_fma_f32 v[6:7], v[162:163], v[224:225], v[6:7]
	v_pk_fma_f32 v[8:9], v[164:165], v[226:227], v[8:9]
	v_pk_fma_f32 v[10:11], v[166:167], v[228:229], v[10:11]
	v_pk_fma_f32 v[12:13], v[168:169], v[230:231], v[12:13]
	v_pk_fma_f32 v[14:15], v[170:171], v[232:233], v[14:15]
	v_pk_fma_f32 v[16:17], v[172:173], v[222:223], v[16:17]
	v_pk_fma_f32 v[18:19], v[174:175], v[224:225], v[18:19]
	v_pk_fma_f32 v[20:21], v[176:177], v[226:227], v[20:21]
	v_pk_fma_f32 v[22:23], v[178:179], v[228:229], v[22:23]
	v_pk_fma_f32 v[24:25], v[180:181], v[230:231], v[24:25]
	v_pk_fma_f32 v[26:27], v[182:183], v[232:233], v[26:27]
	v_pk_fma_f32 v[28:29], v[184:185], v[222:223], v[28:29]
	v_pk_fma_f32 v[30:31], v[186:187], v[224:225], v[30:31]
	v_pk_fma_f32 v[32:33], v[188:189], v[226:227], v[32:33]
	v_pk_fma_f32 v[34:35], v[190:191], v[228:229], v[34:35]
	v_pk_fma_f32 v[36:37], v[192:193], v[230:231], v[36:37]
	v_pk_fma_f32 v[38:39], v[194:195], v[232:233], v[38:39]
	v_pk_fma_f32 v[40:41], v[100:101], v[222:223], v[40:41]
	v_pk_fma_f32 v[42:43], v[102:103], v[224:225], v[42:43]
	v_pk_fma_f32 v[44:45], v[104:105], v[226:227], v[44:45]
	v_pk_fma_f32 v[46:47], v[106:107], v[228:229], v[46:47]
	v_pk_fma_f32 v[48:49], v[108:109], v[230:231], v[48:49]
	v_pk_fma_f32 v[50:51], v[110:111], v[232:233], v[50:51]
	v_pk_fma_f32 v[52:53], v[112:113], v[222:223], v[52:53]
	v_pk_fma_f32 v[54:55], v[114:115], v[224:225], v[54:55]
	v_pk_fma_f32 v[56:57], v[116:117], v[226:227], v[56:57]
	v_pk_fma_f32 v[58:59], v[118:119], v[228:229], v[58:59]
	v_pk_fma_f32 v[60:61], v[120:121], v[230:231], v[60:61]
	v_pk_fma_f32 v[62:63], v[122:123], v[232:233], v[62:63]
	v_pk_fma_f32 v[64:65], v[124:125], v[222:223], v[64:65]
	v_pk_fma_f32 v[66:67], v[126:127], v[224:225], v[66:67]
	v_pk_fma_f32 v[68:69], v[128:129], v[226:227], v[68:69]
	v_pk_fma_f32 v[70:71], v[130:131], v[228:229], v[70:71]
	v_pk_fma_f32 v[72:73], v[132:133], v[230:231], v[72:73]
	v_pk_fma_f32 v[74:75], v[134:135], v[232:233], v[74:75]
	v_pk_fma_f32 v[76:77], v[136:137], v[222:223], v[76:77]
	v_pk_fma_f32 v[78:79], v[138:139], v[224:225], v[78:79]
	v_pk_fma_f32 v[80:81], v[140:141], v[226:227], v[80:81]
	v_pk_fma_f32 v[82:83], v[142:143], v[228:229], v[82:83]
	v_pk_fma_f32 v[84:85], v[144:145], v[230:231], v[84:85]
	v_pk_fma_f32 v[86:87], v[146:147], v[232:233], v[86:87]
	v_pk_fma_f32 v[88:89], v[148:149], v[222:223], v[88:89]
	v_pk_fma_f32 v[90:91], v[150:151], v[224:225], v[90:91]
	v_pk_fma_f32 v[92:93], v[152:153], v[226:227], v[92:93]
	v_pk_fma_f32 v[94:95], v[154:155], v[228:229], v[94:95]
	v_pk_fma_f32 v[96:97], v[156:157], v[230:231], v[96:97]
	v_pk_fma_f32 v[98:99], v[158:159], v[232:233], v[98:99]
	s_waitcnt vmcnt(0)
	v_lshlrev_b32_e32 v160, 16, v240
	v_and_b32_e32 v161, 0xffff0000, v240
	v_lshlrev_b32_e32 v162, 16, v241
	v_and_b32_e32 v163, 0xffff0000, v241
	v_lshlrev_b32_e32 v164, 16, v242
	v_and_b32_e32 v165, 0xffff0000, v242
	v_lshlrev_b32_e32 v166, 16, v243
	v_and_b32_e32 v167, 0xffff0000, v243
	v_lshlrev_b32_e32 v168, 16, v244
	v_and_b32_e32 v169, 0xffff0000, v244
	v_lshlrev_b32_e32 v170, 16, v245
	v_and_b32_e32 v171, 0xffff0000, v245
	global_load_dwordx4 v[222:225], v2, s[66:67]
	global_load_dwordx4 v[226:229], v2, s[66:67] offset:1024
	global_load_dwordx4 v[230:233], v2, s[66:67] offset:2048
	global_load_dwordx4 v[234:237], v2, s[42:43]
	global_load_dwordx4 v[238:241], v2, s[42:43] offset:1024
	global_load_dwordx4 v[242:245], v2, s[42:43] offset:2048
	s_waitcnt lgkmcnt(0)
	v_pk_fma_f32 v[4:5], v[172:173], v[210:211], v[4:5]
	v_pk_fma_f32 v[6:7], v[174:175], v[212:213], v[6:7]
	v_pk_fma_f32 v[8:9], v[176:177], v[214:215], v[8:9]
	v_pk_fma_f32 v[10:11], v[178:179], v[216:217], v[10:11]
	v_pk_fma_f32 v[12:13], v[180:181], v[218:219], v[12:13]
	v_pk_fma_f32 v[14:15], v[182:183], v[220:221], v[14:15]
	v_pk_fma_f32 v[16:17], v[184:185], v[210:211], v[16:17]
	v_pk_fma_f32 v[18:19], v[186:187], v[212:213], v[18:19]
	v_pk_fma_f32 v[20:21], v[188:189], v[214:215], v[20:21]
	v_pk_fma_f32 v[22:23], v[190:191], v[216:217], v[22:23]
	v_pk_fma_f32 v[24:25], v[192:193], v[218:219], v[24:25]
	v_pk_fma_f32 v[26:27], v[194:195], v[220:221], v[26:27]
	v_pk_fma_f32 v[28:29], v[100:101], v[210:211], v[28:29]
	v_pk_fma_f32 v[30:31], v[102:103], v[212:213], v[30:31]
	v_pk_fma_f32 v[32:33], v[104:105], v[214:215], v[32:33]
	v_pk_fma_f32 v[34:35], v[106:107], v[216:217], v[34:35]
	v_pk_fma_f32 v[36:37], v[108:109], v[218:219], v[36:37]
	v_pk_fma_f32 v[38:39], v[110:111], v[220:221], v[38:39]
	v_pk_fma_f32 v[40:41], v[112:113], v[210:211], v[40:41]
	v_pk_fma_f32 v[42:43], v[114:115], v[212:213], v[42:43]
	v_pk_fma_f32 v[44:45], v[116:117], v[214:215], v[44:45]
	v_pk_fma_f32 v[46:47], v[118:119], v[216:217], v[46:47]
	v_pk_fma_f32 v[48:49], v[120:121], v[218:219], v[48:49]
	v_pk_fma_f32 v[50:51], v[122:123], v[220:221], v[50:51]
	v_pk_fma_f32 v[52:53], v[124:125], v[210:211], v[52:53]
	v_pk_fma_f32 v[54:55], v[126:127], v[212:213], v[54:55]
	v_pk_fma_f32 v[56:57], v[128:129], v[214:215], v[56:57]
	v_pk_fma_f32 v[58:59], v[130:131], v[216:217], v[58:59]
	v_pk_fma_f32 v[60:61], v[132:133], v[218:219], v[60:61]
	v_pk_fma_f32 v[62:63], v[134:135], v[220:221], v[62:63]
	v_pk_fma_f32 v[64:65], v[136:137], v[210:211], v[64:65]
	v_pk_fma_f32 v[66:67], v[138:139], v[212:213], v[66:67]
	v_pk_fma_f32 v[68:69], v[140:141], v[214:215], v[68:69]
	v_pk_fma_f32 v[70:71], v[142:143], v[216:217], v[70:71]
	v_pk_fma_f32 v[72:73], v[144:145], v[218:219], v[72:73]
	v_pk_fma_f32 v[74:75], v[146:147], v[220:221], v[74:75]
	v_pk_fma_f32 v[76:77], v[148:149], v[210:211], v[76:77]
	v_pk_fma_f32 v[78:79], v[150:151], v[212:213], v[78:79]
	v_pk_fma_f32 v[80:81], v[152:153], v[214:215], v[80:81]
	v_pk_fma_f32 v[82:83], v[154:155], v[216:217], v[82:83]
	v_pk_fma_f32 v[84:85], v[156:157], v[218:219], v[84:85]
	v_pk_fma_f32 v[86:87], v[158:159], v[220:221], v[86:87]
	v_pk_fma_f32 v[88:89], v[160:161], v[210:211], v[88:89]
	v_pk_fma_f32 v[90:91], v[162:163], v[212:213], v[90:91]
	v_pk_fma_f32 v[92:93], v[164:165], v[214:215], v[92:93]
	v_pk_fma_f32 v[94:95], v[166:167], v[216:217], v[94:95]
	v_pk_fma_f32 v[96:97], v[168:169], v[218:219], v[96:97]
	v_pk_fma_f32 v[98:99], v[170:171], v[220:221], v[98:99]
	s_waitcnt vmcnt(0)
	v_mov_b32_e32 v197, 0x3727c5ac
	v_add_f32_e32 v100, v4, v5
	v_add_f32_e32 v100, v100, v6
	v_add_f32_e32 v100, v100, v7
	v_add_f32_e32 v100, v100, v8
	v_add_f32_e32 v100, v100, v9
	v_add_f32_e32 v100, v100, v10
	v_add_f32_e32 v100, v100, v11
	v_add_f32_e32 v100, v100, v12
	v_add_f32_e32 v100, v100, v13
	v_add_f32_e32 v100, v100, v14
	v_add_f32_e32 v100, v100, v15
	s_nop 1
	v_add_f32_dpp v100, v100, v100 row_shr:1 row_mask:0xf bank_mask:0xf bound_ctrl:1
	s_nop 1
	v_add_f32_dpp v100, v100, v100 row_shr:2 row_mask:0xf bank_mask:0xf bound_ctrl:1
	s_nop 1
	v_add_f32_dpp v100, v100, v100 row_shr:4 row_mask:0xf bank_mask:0xf bound_ctrl:1
	s_nop 1
	v_add_f32_dpp v100, v100, v100 row_shr:8 row_mask:0xf bank_mask:0xf bound_ctrl:1
	s_nop 1
	v_add_f32_dpp v100, v100, v100 row_bcast:15 row_mask:0xa bank_mask:0xf
	s_nop 1
	v_add_f32_dpp v100, v100, v100 row_bcast:31 row_mask:0xc bank_mask:0xf
	s_nop 0
	v_readlane_b32 s53, v100, 63
	s_nop 1
	v_mov_b32_e32 v101, s53
	v_fmac_f32_e32 v4, 0xbaaaaaab, v101
	v_fmac_f32_e32 v5, 0xbaaaaaab, v101
	v_fmac_f32_e32 v6, 0xbaaaaaab, v101
	v_fmac_f32_e32 v7, 0xbaaaaaab, v101
	v_fmac_f32_e32 v8, 0xbaaaaaab, v101
	v_fmac_f32_e32 v9, 0xbaaaaaab, v101
	v_fmac_f32_e32 v10, 0xbaaaaaab, v101
	v_fmac_f32_e32 v11, 0xbaaaaaab, v101
	v_fmac_f32_e32 v12, 0xbaaaaaab, v101
	v_fmac_f32_e32 v13, 0xbaaaaaab, v101
	v_fmac_f32_e32 v14, 0xbaaaaaab, v101
	v_fmac_f32_e32 v15, 0xbaaaaaab, v101
	v_mul_f32_e32 v102, v4, v4
	v_fmac_f32_e32 v102, v5, v5
	v_fmac_f32_e32 v102, v6, v6
	v_fmac_f32_e32 v102, v7, v7
	v_fmac_f32_e32 v102, v8, v8
	v_fmac_f32_e32 v102, v9, v9
	v_fmac_f32_e32 v102, v10, v10
	v_fmac_f32_e32 v102, v11, v11
	v_fmac_f32_e32 v102, v12, v12
	v_fmac_f32_e32 v102, v13, v13
	v_fmac_f32_e32 v102, v14, v14
	v_fmac_f32_e32 v102, v15, v15
	s_nop 1
	v_add_f32_dpp v102, v102, v102 row_shr:1 row_mask:0xf bank_mask:0xf bound_ctrl:1
	s_nop 1
	v_add_f32_dpp v102, v102, v102 row_shr:2 row_mask:0xf bank_mask:0xf bound_ctrl:1
	s_nop 1
	v_add_f32_dpp v102, v102, v102 row_shr:4 row_mask:0xf bank_mask:0xf bound_ctrl:1
	s_nop 1
	v_add_f32_dpp v102, v102, v102 row_shr:8 row_mask:0xf bank_mask:0xf bound_ctrl:1
	s_nop 1
	v_add_f32_dpp v102, v102, v102 row_bcast:15 row_mask:0xa bank_mask:0xf
	s_nop 1
	v_add_f32_dpp v102, v102, v102 row_bcast:31 row_mask:0xc bank_mask:0xf
	s_nop 0
	v_readlane_b32 s53, v102, 63
	s_nop 1
	v_mov_b32_e32 v101, s53
	v_fmamk_f32 v101, v101, 0x3aaaaaab, v197
	v_rsq_f32_e32 v103, v101
	s_nop 0
	v_mul_f32_e32 v4, v4, v103
	v_mul_f32_e32 v5, v5, v103
	v_mul_f32_e32 v6, v6, v103
	v_mul_f32_e32 v7, v7, v103
	v_mul_f32_e32 v8, v8, v103
	v_mul_f32_e32 v9, v9, v103
	v_mul_f32_e32 v10, v10, v103
	v_mul_f32_e32 v11, v11, v103
	v_mul_f32_e32 v12, v12, v103
	v_mul_f32_e32 v13, v13, v103
	v_mul_f32_e32 v14, v14, v103
	v_mul_f32_e32 v15, v15, v103
	v_fma_f32 v4, v222, v4, v234
	v_fma_f32 v5, v223, v5, v235
	v_fma_f32 v6, v224, v6, v236
	v_fma_f32 v7, v225, v7, v237
	v_fma_f32 v8, v226, v8, v238
	v_fma_f32 v9, v227, v9, v239
	v_fma_f32 v10, v228, v10, v240
	v_fma_f32 v11, v229, v11, v241
	v_fma_f32 v12, v230, v12, v242
	v_fma_f32 v13, v231, v13, v243
	v_fma_f32 v14, v232, v14, v244
	v_fma_f32 v15, v233, v15, v245
	s_lshl_b32 s52, s41, 11
	s_add_i32 s52, s52, 0
	v_add_u32_e32 v196, s52, v3
	v_mul_f32_e32 v108, 0xbfb8aa3b, v4
	v_exp_f32_e32 v109, v108
	s_nop 0
	v_add_f32_e32 v110, 1.0, v109
	v_div_scale_f32 v111, s[54:55], v110, v110, 1.0
	v_rcp_f32_e32 v112, v111
	v_div_scale_f32 v113, vcc, 1.0, v110, 1.0
	v_fma_f32 v115, -v111, v112, 1.0
	v_fmac_f32_e32 v112, v115, v112
	v_mul_f32_e32 v114, v113, v112
	v_fma_f32 v115, -v111, v114, v113
	v_fmac_f32_e32 v114, v115, v112
	v_fma_f32 v115, -v111, v114, v113
	v_div_fmas_f32 v115, v115, v112, v114
	v_div_fixup_f32 v115, v115, v110, 1.0
	v_mul_f32_e32 v120, v4, v115
	v_mul_f32_e32 v108, 0xbfb8aa3b, v5
	v_exp_f32_e32 v109, v108
	s_nop 0
	v_add_f32_e32 v110, 1.0, v109
	v_div_scale_f32 v111, s[54:55], v110, v110, 1.0
	v_rcp_f32_e32 v112, v111
	v_div_scale_f32 v113, vcc, 1.0, v110, 1.0
	v_fma_f32 v115, -v111, v112, 1.0
	v_fmac_f32_e32 v112, v115, v112
	v_mul_f32_e32 v114, v113, v112
	v_fma_f32 v115, -v111, v114, v113
	v_fmac_f32_e32 v114, v115, v112
	v_fma_f32 v115, -v111, v114, v113
	v_div_fmas_f32 v115, v115, v112, v114
	v_div_fixup_f32 v115, v115, v110, 1.0
	v_mul_f32_e32 v121, v5, v115
	v_mul_f32_e32 v108, 0xbfb8aa3b, v6
	v_exp_f32_e32 v109, v108
	s_nop 0
	v_add_f32_e32 v110, 1.0, v109
	v_div_scale_f32 v111, s[54:55], v110, v110, 1.0
	v_rcp_f32_e32 v112, v111
	v_div_scale_f32 v113, vcc, 1.0, v110, 1.0
	v_fma_f32 v115, -v111, v112, 1.0
	v_fmac_f32_e32 v112, v115, v112
	v_mul_f32_e32 v114, v113, v112
	v_fma_f32 v115, -v111, v114, v113
	v_fmac_f32_e32 v114, v115, v112
	v_fma_f32 v115, -v111, v114, v113
	v_div_fmas_f32 v115, v115, v112, v114
	v_div_fixup_f32 v115, v115, v110, 1.0
	v_mul_f32_e32 v122, v6, v115
	v_mul_f32_e32 v108, 0xbfb8aa3b, v7
	v_exp_f32_e32 v109, v108
	s_nop 0
	v_add_f32_e32 v110, 1.0, v109
	v_div_scale_f32 v111, s[54:55], v110, v110, 1.0
	v_rcp_f32_e32 v112, v111
	v_div_scale_f32 v113, vcc, 1.0, v110, 1.0
	v_fma_f32 v115, -v111, v112, 1.0
	v_fmac_f32_e32 v112, v115, v112
	v_mul_f32_e32 v114, v113, v112
	v_fma_f32 v115, -v111, v114, v113
	v_fmac_f32_e32 v114, v115, v112
	v_fma_f32 v115, -v111, v114, v113
	v_div_fmas_f32 v115, v115, v112, v114
	v_div_fixup_f32 v115, v115, v110, 1.0
	v_mul_f32_e32 v123, v7, v115
	v_cvt_pk_bf16_f32 v124, v120, v121
	v_cvt_pk_bf16_f32 v125, v122, v123
	global_store_dwordx2 v196, v[124:125], s[44:45]
	v_mul_f32_e32 v108, 0xbfb8aa3b, v8
	v_exp_f32_e32 v109, v108
	s_nop 0
	v_add_f32_e32 v110, 1.0, v109
	v_div_scale_f32 v111, s[54:55], v110, v110, 1.0
	v_rcp_f32_e32 v112, v111
	v_div_scale_f32 v113, vcc, 1.0, v110, 1.0
	v_fma_f32 v115, -v111, v112, 1.0
	v_fmac_f32_e32 v112, v115, v112
	v_mul_f32_e32 v114, v113, v112
	v_fma_f32 v115, -v111, v114, v113
	v_fmac_f32_e32 v114, v115, v112
	v_fma_f32 v115, -v111, v114, v113
	v_div_fmas_f32 v115, v115, v112, v114
	v_div_fixup_f32 v115, v115, v110, 1.0
	v_mul_f32_e32 v120, v8, v115
	v_mul_f32_e32 v108, 0xbfb8aa3b, v9
	v_exp_f32_e32 v109, v108
	s_nop 0
	v_add_f32_e32 v110, 1.0, v109
	v_div_scale_f32 v111, s[54:55], v110, v110, 1.0
	v_rcp_f32_e32 v112, v111
	v_div_scale_f32 v113, vcc, 1.0, v110, 1.0
	v_fma_f32 v115, -v111, v112, 1.0
	v_fmac_f32_e32 v112, v115, v112
	v_mul_f32_e32 v114, v113, v112
	v_fma_f32 v115, -v111, v114, v113
	v_fmac_f32_e32 v114, v115, v112
	v_fma_f32 v115, -v111, v114, v113
	v_div_fmas_f32 v115, v115, v112, v114
	v_div_fixup_f32 v115, v115, v110, 1.0
	v_mul_f32_e32 v121, v9, v115
	v_mul_f32_e32 v108, 0xbfb8aa3b, v10
	v_exp_f32_e32 v109, v108
	s_nop 0
	v_add_f32_e32 v110, 1.0, v109
	v_div_scale_f32 v111, s[54:55], v110, v110, 1.0
	v_rcp_f32_e32 v112, v111
	v_div_scale_f32 v113, vcc, 1.0, v110, 1.0
	v_fma_f32 v115, -v111, v112, 1.0
	v_fmac_f32_e32 v112, v115, v112
	v_mul_f32_e32 v114, v113, v112
	v_fma_f32 v115, -v111, v114, v113
	v_fmac_f32_e32 v114, v115, v112
	v_fma_f32 v115, -v111, v114, v113
	v_div_fmas_f32 v115, v115, v112, v114
	v_div_fixup_f32 v115, v115, v110, 1.0
	v_mul_f32_e32 v122, v10, v115
	v_mul_f32_e32 v108, 0xbfb8aa3b, v11
	v_exp_f32_e32 v109, v108
	s_nop 0
	v_add_f32_e32 v110, 1.0, v109
	v_div_scale_f32 v111, s[54:55], v110, v110, 1.0
	v_rcp_f32_e32 v112, v111
	v_div_scale_f32 v113, vcc, 1.0, v110, 1.0
	v_fma_f32 v115, -v111, v112, 1.0
	v_fmac_f32_e32 v112, v115, v112
	v_mul_f32_e32 v114, v113, v112
	v_fma_f32 v115, -v111, v114, v113
	v_fmac_f32_e32 v114, v115, v112
	v_fma_f32 v115, -v111, v114, v113
	v_div_fmas_f32 v115, v115, v112, v114
	v_div_fixup_f32 v115, v115, v110, 1.0
	v_mul_f32_e32 v123, v11, v115
	v_cvt_pk_bf16_f32 v124, v120, v121
	v_cvt_pk_bf16_f32 v125, v122, v123
	global_store_dwordx2 v196, v[124:125], s[44:45] offset:512
	v_mul_f32_e32 v108, 0xbfb8aa3b, v12
	v_exp_f32_e32 v109, v108
	s_nop 0
	v_add_f32_e32 v110, 1.0, v109
	v_div_scale_f32 v111, s[54:55], v110, v110, 1.0
	v_rcp_f32_e32 v112, v111
	v_div_scale_f32 v113, vcc, 1.0, v110, 1.0
	v_fma_f32 v115, -v111, v112, 1.0
	v_fmac_f32_e32 v112, v115, v112
	v_mul_f32_e32 v114, v113, v112
	v_fma_f32 v115, -v111, v114, v113
	v_fmac_f32_e32 v114, v115, v112
	v_fma_f32 v115, -v111, v114, v113
	v_div_fmas_f32 v115, v115, v112, v114
	v_div_fixup_f32 v115, v115, v110, 1.0
	v_mul_f32_e32 v120, v12, v115
	v_mul_f32_e32 v108, 0xbfb8aa3b, v13
	v_exp_f32_e32 v109, v108
	s_nop 0
	v_add_f32_e32 v110, 1.0, v109
	v_div_scale_f32 v111, s[54:55], v110, v110, 1.0
	v_rcp_f32_e32 v112, v111
	v_div_scale_f32 v113, vcc, 1.0, v110, 1.0
	v_fma_f32 v115, -v111, v112, 1.0
	v_fmac_f32_e32 v112, v115, v112
	v_mul_f32_e32 v114, v113, v112
	v_fma_f32 v115, -v111, v114, v113
	v_fmac_f32_e32 v114, v115, v112
	v_fma_f32 v115, -v111, v114, v113
	v_div_fmas_f32 v115, v115, v112, v114
	v_div_fixup_f32 v115, v115, v110, 1.0
	v_mul_f32_e32 v121, v13, v115
	v_mul_f32_e32 v108, 0xbfb8aa3b, v14
	v_exp_f32_e32 v109, v108
	s_nop 0
	v_add_f32_e32 v110, 1.0, v109
	v_div_scale_f32 v111, s[54:55], v110, v110, 1.0
	v_rcp_f32_e32 v112, v111
	v_div_scale_f32 v113, vcc, 1.0, v110, 1.0
	v_fma_f32 v115, -v111, v112, 1.0
	v_fmac_f32_e32 v112, v115, v112
	v_mul_f32_e32 v114, v113, v112
	v_fma_f32 v115, -v111, v114, v113
	v_fmac_f32_e32 v114, v115, v112
	v_fma_f32 v115, -v111, v114, v113
	v_div_fmas_f32 v115, v115, v112, v114
	v_div_fixup_f32 v115, v115, v110, 1.0
	v_mul_f32_e32 v122, v14, v115
	v_mul_f32_e32 v108, 0xbfb8aa3b, v15
	v_exp_f32_e32 v109, v108
	s_nop 0
	v_add_f32_e32 v110, 1.0, v109
	v_div_scale_f32 v111, s[54:55], v110, v110, 1.0
	v_rcp_f32_e32 v112, v111
	v_div_scale_f32 v113, vcc, 1.0, v110, 1.0
	v_fma_f32 v115, -v111, v112, 1.0
	v_fmac_f32_e32 v112, v115, v112
	v_mul_f32_e32 v114, v113, v112
	v_fma_f32 v115, -v111, v114, v113
	v_fmac_f32_e32 v114, v115, v112
	v_fma_f32 v115, -v111, v114, v113
	v_div_fmas_f32 v115, v115, v112, v114
	v_div_fixup_f32 v115, v115, v110, 1.0
	v_mul_f32_e32 v123, v15, v115
	v_cvt_pk_bf16_f32 v124, v120, v121
	v_cvt_pk_bf16_f32 v125, v122, v123
	global_store_dwordx2 v196, v[124:125], s[44:45] offset:1024
	v_add_f32_e32 v100, v16, v17
	v_add_f32_e32 v100, v100, v18
	v_add_f32_e32 v100, v100, v19
	v_add_f32_e32 v100, v100, v20
	v_add_f32_e32 v100, v100, v21
	v_add_f32_e32 v100, v100, v22
	v_add_f32_e32 v100, v100, v23
	v_add_f32_e32 v100, v100, v24
	v_add_f32_e32 v100, v100, v25
	v_add_f32_e32 v100, v100, v26
	v_add_f32_e32 v100, v100, v27
	s_nop 1
	v_add_f32_dpp v100, v100, v100 row_shr:1 row_mask:0xf bank_mask:0xf bound_ctrl:1
	s_nop 1
	v_add_f32_dpp v100, v100, v100 row_shr:2 row_mask:0xf bank_mask:0xf bound_ctrl:1
	s_nop 1
	v_add_f32_dpp v100, v100, v100 row_shr:4 row_mask:0xf bank_mask:0xf bound_ctrl:1
	s_nop 1
	v_add_f32_dpp v100, v100, v100 row_shr:8 row_mask:0xf bank_mask:0xf bound_ctrl:1
	s_nop 1
	v_add_f32_dpp v100, v100, v100 row_bcast:15 row_mask:0xa bank_mask:0xf
	s_nop 1
	v_add_f32_dpp v100, v100, v100 row_bcast:31 row_mask:0xc bank_mask:0xf
	s_nop 0
	v_readlane_b32 s53, v100, 63
	s_nop 1
	v_mov_b32_e32 v101, s53
	v_fmac_f32_e32 v16, 0xbaaaaaab, v101
	v_fmac_f32_e32 v17, 0xbaaaaaab, v101
	v_fmac_f32_e32 v18, 0xbaaaaaab, v101
	v_fmac_f32_e32 v19, 0xbaaaaaab, v101
	v_fmac_f32_e32 v20, 0xbaaaaaab, v101
	v_fmac_f32_e32 v21, 0xbaaaaaab, v101
	v_fmac_f32_e32 v22, 0xbaaaaaab, v101
	v_fmac_f32_e32 v23, 0xbaaaaaab, v101
	v_fmac_f32_e32 v24, 0xbaaaaaab, v101
	v_fmac_f32_e32 v25, 0xbaaaaaab, v101
	v_fmac_f32_e32 v26, 0xbaaaaaab, v101
	v_fmac_f32_e32 v27, 0xbaaaaaab, v101
	v_mul_f32_e32 v102, v16, v16
	v_fmac_f32_e32 v102, v17, v17
	v_fmac_f32_e32 v102, v18, v18
	v_fmac_f32_e32 v102, v19, v19
	v_fmac_f32_e32 v102, v20, v20
	v_fmac_f32_e32 v102, v21, v21
	v_fmac_f32_e32 v102, v22, v22
	v_fmac_f32_e32 v102, v23, v23
	v_fmac_f32_e32 v102, v24, v24
	v_fmac_f32_e32 v102, v25, v25
	v_fmac_f32_e32 v102, v26, v26
	v_fmac_f32_e32 v102, v27, v27
	s_nop 1
	v_add_f32_dpp v102, v102, v102 row_shr:1 row_mask:0xf bank_mask:0xf bound_ctrl:1
	s_nop 1
	v_add_f32_dpp v102, v102, v102 row_shr:2 row_mask:0xf bank_mask:0xf bound_ctrl:1
	s_nop 1
	v_add_f32_dpp v102, v102, v102 row_shr:4 row_mask:0xf bank_mask:0xf bound_ctrl:1
	s_nop 1
	v_add_f32_dpp v102, v102, v102 row_shr:8 row_mask:0xf bank_mask:0xf bound_ctrl:1
	s_nop 1
	v_add_f32_dpp v102, v102, v102 row_bcast:15 row_mask:0xa bank_mask:0xf
	s_nop 1
	v_add_f32_dpp v102, v102, v102 row_bcast:31 row_mask:0xc bank_mask:0xf
	s_nop 0
	v_readlane_b32 s53, v102, 63
	s_nop 1
	v_mov_b32_e32 v101, s53
	v_fmamk_f32 v101, v101, 0x3aaaaaab, v197
	v_rsq_f32_e32 v103, v101
	s_nop 0
	v_mul_f32_e32 v16, v16, v103
	v_mul_f32_e32 v17, v17, v103
	v_mul_f32_e32 v18, v18, v103
	v_mul_f32_e32 v19, v19, v103
	v_mul_f32_e32 v20, v20, v103
	v_mul_f32_e32 v21, v21, v103
	v_mul_f32_e32 v22, v22, v103
	v_mul_f32_e32 v23, v23, v103
	v_mul_f32_e32 v24, v24, v103
	v_mul_f32_e32 v25, v25, v103
	v_mul_f32_e32 v26, v26, v103
	v_mul_f32_e32 v27, v27, v103
	v_fma_f32 v16, v222, v16, v234
	v_fma_f32 v17, v223, v17, v235
	v_fma_f32 v18, v224, v18, v236
	v_fma_f32 v19, v225, v19, v237
	v_fma_f32 v20, v226, v20, v238
	v_fma_f32 v21, v227, v21, v239
	v_fma_f32 v22, v228, v22, v240
	v_fma_f32 v23, v229, v23, v241
	v_fma_f32 v24, v230, v24, v242
	v_fma_f32 v25, v231, v25, v243
	v_fma_f32 v26, v232, v26, v244
	v_fma_f32 v27, v233, v27, v245
	s_lshl_b32 s52, s41, 11
	s_add_i32 s52, s52, 2048
	v_add_u32_e32 v196, s52, v3
	v_mul_f32_e32 v108, 0xbfb8aa3b, v16
	v_exp_f32_e32 v109, v108
	s_nop 0
	v_add_f32_e32 v110, 1.0, v109
	v_div_scale_f32 v111, s[54:55], v110, v110, 1.0
	v_rcp_f32_e32 v112, v111
	v_div_scale_f32 v113, vcc, 1.0, v110, 1.0
	v_fma_f32 v115, -v111, v112, 1.0
	v_fmac_f32_e32 v112, v115, v112
	v_mul_f32_e32 v114, v113, v112
	v_fma_f32 v115, -v111, v114, v113
	v_fmac_f32_e32 v114, v115, v112
	v_fma_f32 v115, -v111, v114, v113
	v_div_fmas_f32 v115, v115, v112, v114
	v_div_fixup_f32 v115, v115, v110, 1.0
	v_mul_f32_e32 v120, v16, v115
	v_mul_f32_e32 v108, 0xbfb8aa3b, v17
	v_exp_f32_e32 v109, v108
	s_nop 0
	v_add_f32_e32 v110, 1.0, v109
	v_div_scale_f32 v111, s[54:55], v110, v110, 1.0
	v_rcp_f32_e32 v112, v111
	v_div_scale_f32 v113, vcc, 1.0, v110, 1.0
	v_fma_f32 v115, -v111, v112, 1.0
	v_fmac_f32_e32 v112, v115, v112
	v_mul_f32_e32 v114, v113, v112
	v_fma_f32 v115, -v111, v114, v113
	v_fmac_f32_e32 v114, v115, v112
	v_fma_f32 v115, -v111, v114, v113
	v_div_fmas_f32 v115, v115, v112, v114
	v_div_fixup_f32 v115, v115, v110, 1.0
	v_mul_f32_e32 v121, v17, v115
	v_mul_f32_e32 v108, 0xbfb8aa3b, v18
	v_exp_f32_e32 v109, v108
	s_nop 0
	v_add_f32_e32 v110, 1.0, v109
	v_div_scale_f32 v111, s[54:55], v110, v110, 1.0
	v_rcp_f32_e32 v112, v111
	v_div_scale_f32 v113, vcc, 1.0, v110, 1.0
	v_fma_f32 v115, -v111, v112, 1.0
	v_fmac_f32_e32 v112, v115, v112
	v_mul_f32_e32 v114, v113, v112
	v_fma_f32 v115, -v111, v114, v113
	v_fmac_f32_e32 v114, v115, v112
	v_fma_f32 v115, -v111, v114, v113
	v_div_fmas_f32 v115, v115, v112, v114
	v_div_fixup_f32 v115, v115, v110, 1.0
	v_mul_f32_e32 v122, v18, v115
	v_mul_f32_e32 v108, 0xbfb8aa3b, v19
	v_exp_f32_e32 v109, v108
	s_nop 0
	v_add_f32_e32 v110, 1.0, v109
	v_div_scale_f32 v111, s[54:55], v110, v110, 1.0
	v_rcp_f32_e32 v112, v111
	v_div_scale_f32 v113, vcc, 1.0, v110, 1.0
	v_fma_f32 v115, -v111, v112, 1.0
	v_fmac_f32_e32 v112, v115, v112
	v_mul_f32_e32 v114, v113, v112
	v_fma_f32 v115, -v111, v114, v113
	v_fmac_f32_e32 v114, v115, v112
	v_fma_f32 v115, -v111, v114, v113
	v_div_fmas_f32 v115, v115, v112, v114
	v_div_fixup_f32 v115, v115, v110, 1.0
	v_mul_f32_e32 v123, v19, v115
	v_cvt_pk_bf16_f32 v124, v120, v121
	v_cvt_pk_bf16_f32 v125, v122, v123
	global_store_dwordx2 v196, v[124:125], s[44:45]
	v_mul_f32_e32 v108, 0xbfb8aa3b, v20
	v_exp_f32_e32 v109, v108
	s_nop 0
	v_add_f32_e32 v110, 1.0, v109
	v_div_scale_f32 v111, s[54:55], v110, v110, 1.0
	v_rcp_f32_e32 v112, v111
	v_div_scale_f32 v113, vcc, 1.0, v110, 1.0
	v_fma_f32 v115, -v111, v112, 1.0
	v_fmac_f32_e32 v112, v115, v112
	v_mul_f32_e32 v114, v113, v112
	v_fma_f32 v115, -v111, v114, v113
	v_fmac_f32_e32 v114, v115, v112
	v_fma_f32 v115, -v111, v114, v113
	v_div_fmas_f32 v115, v115, v112, v114
	v_div_fixup_f32 v115, v115, v110, 1.0
	v_mul_f32_e32 v120, v20, v115
	v_mul_f32_e32 v108, 0xbfb8aa3b, v21
	v_exp_f32_e32 v109, v108
	s_nop 0
	v_add_f32_e32 v110, 1.0, v109
	v_div_scale_f32 v111, s[54:55], v110, v110, 1.0
	v_rcp_f32_e32 v112, v111
	v_div_scale_f32 v113, vcc, 1.0, v110, 1.0
	v_fma_f32 v115, -v111, v112, 1.0
	v_fmac_f32_e32 v112, v115, v112
	v_mul_f32_e32 v114, v113, v112
	v_fma_f32 v115, -v111, v114, v113
	v_fmac_f32_e32 v114, v115, v112
	v_fma_f32 v115, -v111, v114, v113
	v_div_fmas_f32 v115, v115, v112, v114
	v_div_fixup_f32 v115, v115, v110, 1.0
	v_mul_f32_e32 v121, v21, v115
	v_mul_f32_e32 v108, 0xbfb8aa3b, v22
	v_exp_f32_e32 v109, v108
	s_nop 0
	v_add_f32_e32 v110, 1.0, v109
	v_div_scale_f32 v111, s[54:55], v110, v110, 1.0
	v_rcp_f32_e32 v112, v111
	v_div_scale_f32 v113, vcc, 1.0, v110, 1.0
	v_fma_f32 v115, -v111, v112, 1.0
	v_fmac_f32_e32 v112, v115, v112
	v_mul_f32_e32 v114, v113, v112
	v_fma_f32 v115, -v111, v114, v113
	v_fmac_f32_e32 v114, v115, v112
	v_fma_f32 v115, -v111, v114, v113
	v_div_fmas_f32 v115, v115, v112, v114
	v_div_fixup_f32 v115, v115, v110, 1.0
	v_mul_f32_e32 v122, v22, v115
	v_mul_f32_e32 v108, 0xbfb8aa3b, v23
	v_exp_f32_e32 v109, v108
	s_nop 0
	v_add_f32_e32 v110, 1.0, v109
	v_div_scale_f32 v111, s[54:55], v110, v110, 1.0
	v_rcp_f32_e32 v112, v111
	v_div_scale_f32 v113, vcc, 1.0, v110, 1.0
	v_fma_f32 v115, -v111, v112, 1.0
	v_fmac_f32_e32 v112, v115, v112
	v_mul_f32_e32 v114, v113, v112
	v_fma_f32 v115, -v111, v114, v113
	v_fmac_f32_e32 v114, v115, v112
	v_fma_f32 v115, -v111, v114, v113
	v_div_fmas_f32 v115, v115, v112, v114
	v_div_fixup_f32 v115, v115, v110, 1.0
	v_mul_f32_e32 v123, v23, v115
	v_cvt_pk_bf16_f32 v124, v120, v121
	v_cvt_pk_bf16_f32 v125, v122, v123
	global_store_dwordx2 v196, v[124:125], s[44:45] offset:512
	v_mul_f32_e32 v108, 0xbfb8aa3b, v24
	v_exp_f32_e32 v109, v108
	s_nop 0
	v_add_f32_e32 v110, 1.0, v109
	v_div_scale_f32 v111, s[54:55], v110, v110, 1.0
	v_rcp_f32_e32 v112, v111
	v_div_scale_f32 v113, vcc, 1.0, v110, 1.0
	v_fma_f32 v115, -v111, v112, 1.0
	v_fmac_f32_e32 v112, v115, v112
	v_mul_f32_e32 v114, v113, v112
	v_fma_f32 v115, -v111, v114, v113
	v_fmac_f32_e32 v114, v115, v112
	v_fma_f32 v115, -v111, v114, v113
	v_div_fmas_f32 v115, v115, v112, v114
	v_div_fixup_f32 v115, v115, v110, 1.0
	v_mul_f32_e32 v120, v24, v115
	v_mul_f32_e32 v108, 0xbfb8aa3b, v25
	v_exp_f32_e32 v109, v108
	s_nop 0
	v_add_f32_e32 v110, 1.0, v109
	v_div_scale_f32 v111, s[54:55], v110, v110, 1.0
	v_rcp_f32_e32 v112, v111
	v_div_scale_f32 v113, vcc, 1.0, v110, 1.0
	v_fma_f32 v115, -v111, v112, 1.0
	v_fmac_f32_e32 v112, v115, v112
	v_mul_f32_e32 v114, v113, v112
	v_fma_f32 v115, -v111, v114, v113
	v_fmac_f32_e32 v114, v115, v112
	v_fma_f32 v115, -v111, v114, v113
	v_div_fmas_f32 v115, v115, v112, v114
	v_div_fixup_f32 v115, v115, v110, 1.0
	v_mul_f32_e32 v121, v25, v115
	v_mul_f32_e32 v108, 0xbfb8aa3b, v26
	v_exp_f32_e32 v109, v108
	s_nop 0
	v_add_f32_e32 v110, 1.0, v109
	v_div_scale_f32 v111, s[54:55], v110, v110, 1.0
	v_rcp_f32_e32 v112, v111
	v_div_scale_f32 v113, vcc, 1.0, v110, 1.0
	v_fma_f32 v115, -v111, v112, 1.0
	v_fmac_f32_e32 v112, v115, v112
	v_mul_f32_e32 v114, v113, v112
	v_fma_f32 v115, -v111, v114, v113
	v_fmac_f32_e32 v114, v115, v112
	v_fma_f32 v115, -v111, v114, v113
	v_div_fmas_f32 v115, v115, v112, v114
	v_div_fixup_f32 v115, v115, v110, 1.0
	v_mul_f32_e32 v122, v26, v115
	v_mul_f32_e32 v108, 0xbfb8aa3b, v27
	v_exp_f32_e32 v109, v108
	s_nop 0
	v_add_f32_e32 v110, 1.0, v109
	v_div_scale_f32 v111, s[54:55], v110, v110, 1.0
	v_rcp_f32_e32 v112, v111
	v_div_scale_f32 v113, vcc, 1.0, v110, 1.0
	v_fma_f32 v115, -v111, v112, 1.0
	v_fmac_f32_e32 v112, v115, v112
	v_mul_f32_e32 v114, v113, v112
	v_fma_f32 v115, -v111, v114, v113
	v_fmac_f32_e32 v114, v115, v112
	v_fma_f32 v115, -v111, v114, v113
	v_div_fmas_f32 v115, v115, v112, v114
	v_div_fixup_f32 v115, v115, v110, 1.0
	v_mul_f32_e32 v123, v27, v115
	v_cvt_pk_bf16_f32 v124, v120, v121
	v_cvt_pk_bf16_f32 v125, v122, v123
	global_store_dwordx2 v196, v[124:125], s[44:45] offset:1024
	v_add_f32_e32 v100, v28, v29
	v_add_f32_e32 v100, v100, v30
	v_add_f32_e32 v100, v100, v31
	v_add_f32_e32 v100, v100, v32
	v_add_f32_e32 v100, v100, v33
	v_add_f32_e32 v100, v100, v34
	v_add_f32_e32 v100, v100, v35
	v_add_f32_e32 v100, v100, v36
	v_add_f32_e32 v100, v100, v37
	v_add_f32_e32 v100, v100, v38
	v_add_f32_e32 v100, v100, v39
	s_nop 1
	v_add_f32_dpp v100, v100, v100 row_shr:1 row_mask:0xf bank_mask:0xf bound_ctrl:1
	s_nop 1
	v_add_f32_dpp v100, v100, v100 row_shr:2 row_mask:0xf bank_mask:0xf bound_ctrl:1
	s_nop 1
	v_add_f32_dpp v100, v100, v100 row_shr:4 row_mask:0xf bank_mask:0xf bound_ctrl:1
	s_nop 1
	v_add_f32_dpp v100, v100, v100 row_shr:8 row_mask:0xf bank_mask:0xf bound_ctrl:1
	s_nop 1
	v_add_f32_dpp v100, v100, v100 row_bcast:15 row_mask:0xa bank_mask:0xf
	s_nop 1
	v_add_f32_dpp v100, v100, v100 row_bcast:31 row_mask:0xc bank_mask:0xf
	s_nop 0
	v_readlane_b32 s53, v100, 63
	s_nop 1
	v_mov_b32_e32 v101, s53
	v_fmac_f32_e32 v28, 0xbaaaaaab, v101
	v_fmac_f32_e32 v29, 0xbaaaaaab, v101
	v_fmac_f32_e32 v30, 0xbaaaaaab, v101
	v_fmac_f32_e32 v31, 0xbaaaaaab, v101
	v_fmac_f32_e32 v32, 0xbaaaaaab, v101
	v_fmac_f32_e32 v33, 0xbaaaaaab, v101
	v_fmac_f32_e32 v34, 0xbaaaaaab, v101
	v_fmac_f32_e32 v35, 0xbaaaaaab, v101
	v_fmac_f32_e32 v36, 0xbaaaaaab, v101
	v_fmac_f32_e32 v37, 0xbaaaaaab, v101
	v_fmac_f32_e32 v38, 0xbaaaaaab, v101
	v_fmac_f32_e32 v39, 0xbaaaaaab, v101
	v_mul_f32_e32 v102, v28, v28
	v_fmac_f32_e32 v102, v29, v29
	v_fmac_f32_e32 v102, v30, v30
	v_fmac_f32_e32 v102, v31, v31
	v_fmac_f32_e32 v102, v32, v32
	v_fmac_f32_e32 v102, v33, v33
	v_fmac_f32_e32 v102, v34, v34
	v_fmac_f32_e32 v102, v35, v35
	v_fmac_f32_e32 v102, v36, v36
	v_fmac_f32_e32 v102, v37, v37
	v_fmac_f32_e32 v102, v38, v38
	v_fmac_f32_e32 v102, v39, v39
	s_nop 1
	v_add_f32_dpp v102, v102, v102 row_shr:1 row_mask:0xf bank_mask:0xf bound_ctrl:1
	s_nop 1
	v_add_f32_dpp v102, v102, v102 row_shr:2 row_mask:0xf bank_mask:0xf bound_ctrl:1
	s_nop 1
	v_add_f32_dpp v102, v102, v102 row_shr:4 row_mask:0xf bank_mask:0xf bound_ctrl:1
	s_nop 1
	v_add_f32_dpp v102, v102, v102 row_shr:8 row_mask:0xf bank_mask:0xf bound_ctrl:1
	s_nop 1
	v_add_f32_dpp v102, v102, v102 row_bcast:15 row_mask:0xa bank_mask:0xf
	s_nop 1
	v_add_f32_dpp v102, v102, v102 row_bcast:31 row_mask:0xc bank_mask:0xf
	s_nop 0
	v_readlane_b32 s53, v102, 63
	s_nop 1
	v_mov_b32_e32 v101, s53
	v_fmamk_f32 v101, v101, 0x3aaaaaab, v197
	v_rsq_f32_e32 v103, v101
	s_nop 0
	v_mul_f32_e32 v28, v28, v103
	v_mul_f32_e32 v29, v29, v103
	v_mul_f32_e32 v30, v30, v103
	v_mul_f32_e32 v31, v31, v103
	v_mul_f32_e32 v32, v32, v103
	v_mul_f32_e32 v33, v33, v103
	v_mul_f32_e32 v34, v34, v103
	v_mul_f32_e32 v35, v35, v103
	v_mul_f32_e32 v36, v36, v103
	v_mul_f32_e32 v37, v37, v103
	v_mul_f32_e32 v38, v38, v103
	v_mul_f32_e32 v39, v39, v103
	v_fma_f32 v28, v222, v28, v234
	v_fma_f32 v29, v223, v29, v235
	v_fma_f32 v30, v224, v30, v236
	v_fma_f32 v31, v225, v31, v237
	v_fma_f32 v32, v226, v32, v238
	v_fma_f32 v33, v227, v33, v239
	v_fma_f32 v34, v228, v34, v240
	v_fma_f32 v35, v229, v35, v241
	v_fma_f32 v36, v230, v36, v242
	v_fma_f32 v37, v231, v37, v243
	v_fma_f32 v38, v232, v38, v244
	v_fma_f32 v39, v233, v39, v245
	s_lshl_b32 s52, s41, 11
	s_add_i32 s52, s52, 4096
	v_add_u32_e32 v196, s52, v3
	v_mul_f32_e32 v108, 0xbfb8aa3b, v28
	v_exp_f32_e32 v109, v108
	s_nop 0
	v_add_f32_e32 v110, 1.0, v109
	v_div_scale_f32 v111, s[54:55], v110, v110, 1.0
	v_rcp_f32_e32 v112, v111
	v_div_scale_f32 v113, vcc, 1.0, v110, 1.0
	v_fma_f32 v115, -v111, v112, 1.0
	v_fmac_f32_e32 v112, v115, v112
	v_mul_f32_e32 v114, v113, v112
	v_fma_f32 v115, -v111, v114, v113
	v_fmac_f32_e32 v114, v115, v112
	v_fma_f32 v115, -v111, v114, v113
	v_div_fmas_f32 v115, v115, v112, v114
	v_div_fixup_f32 v115, v115, v110, 1.0
	v_mul_f32_e32 v120, v28, v115
	v_mul_f32_e32 v108, 0xbfb8aa3b, v29
	v_exp_f32_e32 v109, v108
	s_nop 0
	v_add_f32_e32 v110, 1.0, v109
	v_div_scale_f32 v111, s[54:55], v110, v110, 1.0
	v_rcp_f32_e32 v112, v111
	v_div_scale_f32 v113, vcc, 1.0, v110, 1.0
	v_fma_f32 v115, -v111, v112, 1.0
	v_fmac_f32_e32 v112, v115, v112
	v_mul_f32_e32 v114, v113, v112
	v_fma_f32 v115, -v111, v114, v113
	v_fmac_f32_e32 v114, v115, v112
	v_fma_f32 v115, -v111, v114, v113
	v_div_fmas_f32 v115, v115, v112, v114
	v_div_fixup_f32 v115, v115, v110, 1.0
	v_mul_f32_e32 v121, v29, v115
	v_mul_f32_e32 v108, 0xbfb8aa3b, v30
	v_exp_f32_e32 v109, v108
	s_nop 0
	v_add_f32_e32 v110, 1.0, v109
	v_div_scale_f32 v111, s[54:55], v110, v110, 1.0
	v_rcp_f32_e32 v112, v111
	v_div_scale_f32 v113, vcc, 1.0, v110, 1.0
	v_fma_f32 v115, -v111, v112, 1.0
	v_fmac_f32_e32 v112, v115, v112
	v_mul_f32_e32 v114, v113, v112
	v_fma_f32 v115, -v111, v114, v113
	v_fmac_f32_e32 v114, v115, v112
	v_fma_f32 v115, -v111, v114, v113
	v_div_fmas_f32 v115, v115, v112, v114
	v_div_fixup_f32 v115, v115, v110, 1.0
	v_mul_f32_e32 v122, v30, v115
	v_mul_f32_e32 v108, 0xbfb8aa3b, v31
	v_exp_f32_e32 v109, v108
	s_nop 0
	v_add_f32_e32 v110, 1.0, v109
	v_div_scale_f32 v111, s[54:55], v110, v110, 1.0
	v_rcp_f32_e32 v112, v111
	v_div_scale_f32 v113, vcc, 1.0, v110, 1.0
	v_fma_f32 v115, -v111, v112, 1.0
	v_fmac_f32_e32 v112, v115, v112
	v_mul_f32_e32 v114, v113, v112
	v_fma_f32 v115, -v111, v114, v113
	v_fmac_f32_e32 v114, v115, v112
	v_fma_f32 v115, -v111, v114, v113
	v_div_fmas_f32 v115, v115, v112, v114
	v_div_fixup_f32 v115, v115, v110, 1.0
	v_mul_f32_e32 v123, v31, v115
	v_cvt_pk_bf16_f32 v124, v120, v121
	v_cvt_pk_bf16_f32 v125, v122, v123
	global_store_dwordx2 v196, v[124:125], s[44:45]
	v_mul_f32_e32 v108, 0xbfb8aa3b, v32
	v_exp_f32_e32 v109, v108
	s_nop 0
	v_add_f32_e32 v110, 1.0, v109
	v_div_scale_f32 v111, s[54:55], v110, v110, 1.0
	v_rcp_f32_e32 v112, v111
	v_div_scale_f32 v113, vcc, 1.0, v110, 1.0
	v_fma_f32 v115, -v111, v112, 1.0
	v_fmac_f32_e32 v112, v115, v112
	v_mul_f32_e32 v114, v113, v112
	v_fma_f32 v115, -v111, v114, v113
	v_fmac_f32_e32 v114, v115, v112
	v_fma_f32 v115, -v111, v114, v113
	v_div_fmas_f32 v115, v115, v112, v114
	v_div_fixup_f32 v115, v115, v110, 1.0
	v_mul_f32_e32 v120, v32, v115
	v_mul_f32_e32 v108, 0xbfb8aa3b, v33
	v_exp_f32_e32 v109, v108
	s_nop 0
	v_add_f32_e32 v110, 1.0, v109
	v_div_scale_f32 v111, s[54:55], v110, v110, 1.0
	v_rcp_f32_e32 v112, v111
	v_div_scale_f32 v113, vcc, 1.0, v110, 1.0
	v_fma_f32 v115, -v111, v112, 1.0
	v_fmac_f32_e32 v112, v115, v112
	v_mul_f32_e32 v114, v113, v112
	v_fma_f32 v115, -v111, v114, v113
	v_fmac_f32_e32 v114, v115, v112
	v_fma_f32 v115, -v111, v114, v113
	v_div_fmas_f32 v115, v115, v112, v114
	v_div_fixup_f32 v115, v115, v110, 1.0
	v_mul_f32_e32 v121, v33, v115
	v_mul_f32_e32 v108, 0xbfb8aa3b, v34
	v_exp_f32_e32 v109, v108
	s_nop 0
	v_add_f32_e32 v110, 1.0, v109
	v_div_scale_f32 v111, s[54:55], v110, v110, 1.0
	v_rcp_f32_e32 v112, v111
	v_div_scale_f32 v113, vcc, 1.0, v110, 1.0
	v_fma_f32 v115, -v111, v112, 1.0
	v_fmac_f32_e32 v112, v115, v112
	v_mul_f32_e32 v114, v113, v112
	v_fma_f32 v115, -v111, v114, v113
	v_fmac_f32_e32 v114, v115, v112
	v_fma_f32 v115, -v111, v114, v113
	v_div_fmas_f32 v115, v115, v112, v114
	v_div_fixup_f32 v115, v115, v110, 1.0
	v_mul_f32_e32 v122, v34, v115
	v_mul_f32_e32 v108, 0xbfb8aa3b, v35
	v_exp_f32_e32 v109, v108
	s_nop 0
	v_add_f32_e32 v110, 1.0, v109
	v_div_scale_f32 v111, s[54:55], v110, v110, 1.0
	v_rcp_f32_e32 v112, v111
	v_div_scale_f32 v113, vcc, 1.0, v110, 1.0
	v_fma_f32 v115, -v111, v112, 1.0
	v_fmac_f32_e32 v112, v115, v112
	v_mul_f32_e32 v114, v113, v112
	v_fma_f32 v115, -v111, v114, v113
	v_fmac_f32_e32 v114, v115, v112
	v_fma_f32 v115, -v111, v114, v113
	v_div_fmas_f32 v115, v115, v112, v114
	v_div_fixup_f32 v115, v115, v110, 1.0
	v_mul_f32_e32 v123, v35, v115
	v_cvt_pk_bf16_f32 v124, v120, v121
	v_cvt_pk_bf16_f32 v125, v122, v123
	global_store_dwordx2 v196, v[124:125], s[44:45] offset:512
	v_mul_f32_e32 v108, 0xbfb8aa3b, v36
	v_exp_f32_e32 v109, v108
	s_nop 0
	v_add_f32_e32 v110, 1.0, v109
	v_div_scale_f32 v111, s[54:55], v110, v110, 1.0
	v_rcp_f32_e32 v112, v111
	v_div_scale_f32 v113, vcc, 1.0, v110, 1.0
	v_fma_f32 v115, -v111, v112, 1.0
	v_fmac_f32_e32 v112, v115, v112
	v_mul_f32_e32 v114, v113, v112
	v_fma_f32 v115, -v111, v114, v113
	v_fmac_f32_e32 v114, v115, v112
	v_fma_f32 v115, -v111, v114, v113
	v_div_fmas_f32 v115, v115, v112, v114
	v_div_fixup_f32 v115, v115, v110, 1.0
	v_mul_f32_e32 v120, v36, v115
	v_mul_f32_e32 v108, 0xbfb8aa3b, v37
	v_exp_f32_e32 v109, v108
	s_nop 0
	v_add_f32_e32 v110, 1.0, v109
	v_div_scale_f32 v111, s[54:55], v110, v110, 1.0
	v_rcp_f32_e32 v112, v111
	v_div_scale_f32 v113, vcc, 1.0, v110, 1.0
	v_fma_f32 v115, -v111, v112, 1.0
	v_fmac_f32_e32 v112, v115, v112
	v_mul_f32_e32 v114, v113, v112
	v_fma_f32 v115, -v111, v114, v113
	v_fmac_f32_e32 v114, v115, v112
	v_fma_f32 v115, -v111, v114, v113
	v_div_fmas_f32 v115, v115, v112, v114
	v_div_fixup_f32 v115, v115, v110, 1.0
	v_mul_f32_e32 v121, v37, v115
	v_mul_f32_e32 v108, 0xbfb8aa3b, v38
	v_exp_f32_e32 v109, v108
	s_nop 0
	v_add_f32_e32 v110, 1.0, v109
	v_div_scale_f32 v111, s[54:55], v110, v110, 1.0
	v_rcp_f32_e32 v112, v111
	v_div_scale_f32 v113, vcc, 1.0, v110, 1.0
	v_fma_f32 v115, -v111, v112, 1.0
	v_fmac_f32_e32 v112, v115, v112
	v_mul_f32_e32 v114, v113, v112
	v_fma_f32 v115, -v111, v114, v113
	v_fmac_f32_e32 v114, v115, v112
	v_fma_f32 v115, -v111, v114, v113
	v_div_fmas_f32 v115, v115, v112, v114
	v_div_fixup_f32 v115, v115, v110, 1.0
	v_mul_f32_e32 v122, v38, v115
	v_mul_f32_e32 v108, 0xbfb8aa3b, v39
	v_exp_f32_e32 v109, v108
	s_nop 0
	v_add_f32_e32 v110, 1.0, v109
	v_div_scale_f32 v111, s[54:55], v110, v110, 1.0
	v_rcp_f32_e32 v112, v111
	v_div_scale_f32 v113, vcc, 1.0, v110, 1.0
	v_fma_f32 v115, -v111, v112, 1.0
	v_fmac_f32_e32 v112, v115, v112
	v_mul_f32_e32 v114, v113, v112
	v_fma_f32 v115, -v111, v114, v113
	v_fmac_f32_e32 v114, v115, v112
	v_fma_f32 v115, -v111, v114, v113
	v_div_fmas_f32 v115, v115, v112, v114
	v_div_fixup_f32 v115, v115, v110, 1.0
	v_mul_f32_e32 v123, v39, v115
	v_cvt_pk_bf16_f32 v124, v120, v121
	v_cvt_pk_bf16_f32 v125, v122, v123
	global_store_dwordx2 v196, v[124:125], s[44:45] offset:1024
	v_add_f32_e32 v100, v40, v41
	v_add_f32_e32 v100, v100, v42
	v_add_f32_e32 v100, v100, v43
	v_add_f32_e32 v100, v100, v44
	v_add_f32_e32 v100, v100, v45
	v_add_f32_e32 v100, v100, v46
	v_add_f32_e32 v100, v100, v47
	v_add_f32_e32 v100, v100, v48
	v_add_f32_e32 v100, v100, v49
	v_add_f32_e32 v100, v100, v50
	v_add_f32_e32 v100, v100, v51
	s_nop 1
	v_add_f32_dpp v100, v100, v100 row_shr:1 row_mask:0xf bank_mask:0xf bound_ctrl:1
	s_nop 1
	v_add_f32_dpp v100, v100, v100 row_shr:2 row_mask:0xf bank_mask:0xf bound_ctrl:1
	s_nop 1
	v_add_f32_dpp v100, v100, v100 row_shr:4 row_mask:0xf bank_mask:0xf bound_ctrl:1
	s_nop 1
	v_add_f32_dpp v100, v100, v100 row_shr:8 row_mask:0xf bank_mask:0xf bound_ctrl:1
	s_nop 1
	v_add_f32_dpp v100, v100, v100 row_bcast:15 row_mask:0xa bank_mask:0xf
	s_nop 1
	v_add_f32_dpp v100, v100, v100 row_bcast:31 row_mask:0xc bank_mask:0xf
	s_nop 0
	v_readlane_b32 s53, v100, 63
	s_nop 1
	v_mov_b32_e32 v101, s53
	v_fmac_f32_e32 v40, 0xbaaaaaab, v101
	v_fmac_f32_e32 v41, 0xbaaaaaab, v101
	v_fmac_f32_e32 v42, 0xbaaaaaab, v101
	v_fmac_f32_e32 v43, 0xbaaaaaab, v101
	v_fmac_f32_e32 v44, 0xbaaaaaab, v101
	v_fmac_f32_e32 v45, 0xbaaaaaab, v101
	v_fmac_f32_e32 v46, 0xbaaaaaab, v101
	v_fmac_f32_e32 v47, 0xbaaaaaab, v101
	v_fmac_f32_e32 v48, 0xbaaaaaab, v101
	v_fmac_f32_e32 v49, 0xbaaaaaab, v101
	v_fmac_f32_e32 v50, 0xbaaaaaab, v101
	v_fmac_f32_e32 v51, 0xbaaaaaab, v101
	v_mul_f32_e32 v102, v40, v40
	v_fmac_f32_e32 v102, v41, v41
	v_fmac_f32_e32 v102, v42, v42
	v_fmac_f32_e32 v102, v43, v43
	v_fmac_f32_e32 v102, v44, v44
	v_fmac_f32_e32 v102, v45, v45
	v_fmac_f32_e32 v102, v46, v46
	v_fmac_f32_e32 v102, v47, v47
	v_fmac_f32_e32 v102, v48, v48
	v_fmac_f32_e32 v102, v49, v49
	v_fmac_f32_e32 v102, v50, v50
	v_fmac_f32_e32 v102, v51, v51
	s_nop 1
	v_add_f32_dpp v102, v102, v102 row_shr:1 row_mask:0xf bank_mask:0xf bound_ctrl:1
	s_nop 1
	v_add_f32_dpp v102, v102, v102 row_shr:2 row_mask:0xf bank_mask:0xf bound_ctrl:1
	s_nop 1
	v_add_f32_dpp v102, v102, v102 row_shr:4 row_mask:0xf bank_mask:0xf bound_ctrl:1
	s_nop 1
	v_add_f32_dpp v102, v102, v102 row_shr:8 row_mask:0xf bank_mask:0xf bound_ctrl:1
	s_nop 1
	v_add_f32_dpp v102, v102, v102 row_bcast:15 row_mask:0xa bank_mask:0xf
	s_nop 1
	v_add_f32_dpp v102, v102, v102 row_bcast:31 row_mask:0xc bank_mask:0xf
	s_nop 0
	v_readlane_b32 s53, v102, 63
	s_nop 1
	v_mov_b32_e32 v101, s53
	v_fmamk_f32 v101, v101, 0x3aaaaaab, v197
	v_rsq_f32_e32 v103, v101
	s_nop 0
	v_mul_f32_e32 v40, v40, v103
	v_mul_f32_e32 v41, v41, v103
	v_mul_f32_e32 v42, v42, v103
	v_mul_f32_e32 v43, v43, v103
	v_mul_f32_e32 v44, v44, v103
	v_mul_f32_e32 v45, v45, v103
	v_mul_f32_e32 v46, v46, v103
	v_mul_f32_e32 v47, v47, v103
	v_mul_f32_e32 v48, v48, v103
	v_mul_f32_e32 v49, v49, v103
	v_mul_f32_e32 v50, v50, v103
	v_mul_f32_e32 v51, v51, v103
	v_fma_f32 v40, v222, v40, v234
	v_fma_f32 v41, v223, v41, v235
	v_fma_f32 v42, v224, v42, v236
	v_fma_f32 v43, v225, v43, v237
	v_fma_f32 v44, v226, v44, v238
	v_fma_f32 v45, v227, v45, v239
	v_fma_f32 v46, v228, v46, v240
	v_fma_f32 v47, v229, v47, v241
	v_fma_f32 v48, v230, v48, v242
	v_fma_f32 v49, v231, v49, v243
	v_fma_f32 v50, v232, v50, v244
	v_fma_f32 v51, v233, v51, v245
	s_lshl_b32 s52, s41, 11
	s_add_i32 s52, s52, 6144
	v_add_u32_e32 v196, s52, v3
	v_mul_f32_e32 v108, 0xbfb8aa3b, v40
	v_exp_f32_e32 v109, v108
	s_nop 0
	v_add_f32_e32 v110, 1.0, v109
	v_div_scale_f32 v111, s[54:55], v110, v110, 1.0
	v_rcp_f32_e32 v112, v111
	v_div_scale_f32 v113, vcc, 1.0, v110, 1.0
	v_fma_f32 v115, -v111, v112, 1.0
	v_fmac_f32_e32 v112, v115, v112
	v_mul_f32_e32 v114, v113, v112
	v_fma_f32 v115, -v111, v114, v113
	v_fmac_f32_e32 v114, v115, v112
	v_fma_f32 v115, -v111, v114, v113
	v_div_fmas_f32 v115, v115, v112, v114
	v_div_fixup_f32 v115, v115, v110, 1.0
	v_mul_f32_e32 v120, v40, v115
	v_mul_f32_e32 v108, 0xbfb8aa3b, v41
	v_exp_f32_e32 v109, v108
	s_nop 0
	v_add_f32_e32 v110, 1.0, v109
	v_div_scale_f32 v111, s[54:55], v110, v110, 1.0
	v_rcp_f32_e32 v112, v111
	v_div_scale_f32 v113, vcc, 1.0, v110, 1.0
	v_fma_f32 v115, -v111, v112, 1.0
	v_fmac_f32_e32 v112, v115, v112
	v_mul_f32_e32 v114, v113, v112
	v_fma_f32 v115, -v111, v114, v113
	v_fmac_f32_e32 v114, v115, v112
	v_fma_f32 v115, -v111, v114, v113
	v_div_fmas_f32 v115, v115, v112, v114
	v_div_fixup_f32 v115, v115, v110, 1.0
	v_mul_f32_e32 v121, v41, v115
	v_mul_f32_e32 v108, 0xbfb8aa3b, v42
	v_exp_f32_e32 v109, v108
	s_nop 0
	v_add_f32_e32 v110, 1.0, v109
	v_div_scale_f32 v111, s[54:55], v110, v110, 1.0
	v_rcp_f32_e32 v112, v111
	v_div_scale_f32 v113, vcc, 1.0, v110, 1.0
	v_fma_f32 v115, -v111, v112, 1.0
	v_fmac_f32_e32 v112, v115, v112
	v_mul_f32_e32 v114, v113, v112
	v_fma_f32 v115, -v111, v114, v113
	v_fmac_f32_e32 v114, v115, v112
	v_fma_f32 v115, -v111, v114, v113
	v_div_fmas_f32 v115, v115, v112, v114
	v_div_fixup_f32 v115, v115, v110, 1.0
	v_mul_f32_e32 v122, v42, v115
	v_mul_f32_e32 v108, 0xbfb8aa3b, v43
	v_exp_f32_e32 v109, v108
	s_nop 0
	v_add_f32_e32 v110, 1.0, v109
	v_div_scale_f32 v111, s[54:55], v110, v110, 1.0
	v_rcp_f32_e32 v112, v111
	v_div_scale_f32 v113, vcc, 1.0, v110, 1.0
	v_fma_f32 v115, -v111, v112, 1.0
	v_fmac_f32_e32 v112, v115, v112
	v_mul_f32_e32 v114, v113, v112
	v_fma_f32 v115, -v111, v114, v113
	v_fmac_f32_e32 v114, v115, v112
	v_fma_f32 v115, -v111, v114, v113
	v_div_fmas_f32 v115, v115, v112, v114
	v_div_fixup_f32 v115, v115, v110, 1.0
	v_mul_f32_e32 v123, v43, v115
	v_cvt_pk_bf16_f32 v124, v120, v121
	v_cvt_pk_bf16_f32 v125, v122, v123
	global_store_dwordx2 v196, v[124:125], s[44:45]
	v_mul_f32_e32 v108, 0xbfb8aa3b, v44
	v_exp_f32_e32 v109, v108
	s_nop 0
	v_add_f32_e32 v110, 1.0, v109
	v_div_scale_f32 v111, s[54:55], v110, v110, 1.0
	v_rcp_f32_e32 v112, v111
	v_div_scale_f32 v113, vcc, 1.0, v110, 1.0
	v_fma_f32 v115, -v111, v112, 1.0
	v_fmac_f32_e32 v112, v115, v112
	v_mul_f32_e32 v114, v113, v112
	v_fma_f32 v115, -v111, v114, v113
	v_fmac_f32_e32 v114, v115, v112
	v_fma_f32 v115, -v111, v114, v113
	v_div_fmas_f32 v115, v115, v112, v114
	v_div_fixup_f32 v115, v115, v110, 1.0
	v_mul_f32_e32 v120, v44, v115
	v_mul_f32_e32 v108, 0xbfb8aa3b, v45
	v_exp_f32_e32 v109, v108
	s_nop 0
	v_add_f32_e32 v110, 1.0, v109
	v_div_scale_f32 v111, s[54:55], v110, v110, 1.0
	v_rcp_f32_e32 v112, v111
	v_div_scale_f32 v113, vcc, 1.0, v110, 1.0
	v_fma_f32 v115, -v111, v112, 1.0
	v_fmac_f32_e32 v112, v115, v112
	v_mul_f32_e32 v114, v113, v112
	v_fma_f32 v115, -v111, v114, v113
	v_fmac_f32_e32 v114, v115, v112
	v_fma_f32 v115, -v111, v114, v113
	v_div_fmas_f32 v115, v115, v112, v114
	v_div_fixup_f32 v115, v115, v110, 1.0
	v_mul_f32_e32 v121, v45, v115
	v_mul_f32_e32 v108, 0xbfb8aa3b, v46
	v_exp_f32_e32 v109, v108
	s_nop 0
	v_add_f32_e32 v110, 1.0, v109
	v_div_scale_f32 v111, s[54:55], v110, v110, 1.0
	v_rcp_f32_e32 v112, v111
	v_div_scale_f32 v113, vcc, 1.0, v110, 1.0
	v_fma_f32 v115, -v111, v112, 1.0
	v_fmac_f32_e32 v112, v115, v112
	v_mul_f32_e32 v114, v113, v112
	v_fma_f32 v115, -v111, v114, v113
	v_fmac_f32_e32 v114, v115, v112
	v_fma_f32 v115, -v111, v114, v113
	v_div_fmas_f32 v115, v115, v112, v114
	v_div_fixup_f32 v115, v115, v110, 1.0
	v_mul_f32_e32 v122, v46, v115
	v_mul_f32_e32 v108, 0xbfb8aa3b, v47
	v_exp_f32_e32 v109, v108
	s_nop 0
	v_add_f32_e32 v110, 1.0, v109
	v_div_scale_f32 v111, s[54:55], v110, v110, 1.0
	v_rcp_f32_e32 v112, v111
	v_div_scale_f32 v113, vcc, 1.0, v110, 1.0
	v_fma_f32 v115, -v111, v112, 1.0
	v_fmac_f32_e32 v112, v115, v112
	v_mul_f32_e32 v114, v113, v112
	v_fma_f32 v115, -v111, v114, v113
	v_fmac_f32_e32 v114, v115, v112
	v_fma_f32 v115, -v111, v114, v113
	v_div_fmas_f32 v115, v115, v112, v114
	v_div_fixup_f32 v115, v115, v110, 1.0
	v_mul_f32_e32 v123, v47, v115
	v_cvt_pk_bf16_f32 v124, v120, v121
	v_cvt_pk_bf16_f32 v125, v122, v123
	global_store_dwordx2 v196, v[124:125], s[44:45] offset:512
	v_mul_f32_e32 v108, 0xbfb8aa3b, v48
	v_exp_f32_e32 v109, v108
	s_nop 0
	v_add_f32_e32 v110, 1.0, v109
	v_div_scale_f32 v111, s[54:55], v110, v110, 1.0
	v_rcp_f32_e32 v112, v111
	v_div_scale_f32 v113, vcc, 1.0, v110, 1.0
	v_fma_f32 v115, -v111, v112, 1.0
	v_fmac_f32_e32 v112, v115, v112
	v_mul_f32_e32 v114, v113, v112
	v_fma_f32 v115, -v111, v114, v113
	v_fmac_f32_e32 v114, v115, v112
	v_fma_f32 v115, -v111, v114, v113
	v_div_fmas_f32 v115, v115, v112, v114
	v_div_fixup_f32 v115, v115, v110, 1.0
	v_mul_f32_e32 v120, v48, v115
	v_mul_f32_e32 v108, 0xbfb8aa3b, v49
	v_exp_f32_e32 v109, v108
	s_nop 0
	v_add_f32_e32 v110, 1.0, v109
	v_div_scale_f32 v111, s[54:55], v110, v110, 1.0
	v_rcp_f32_e32 v112, v111
	v_div_scale_f32 v113, vcc, 1.0, v110, 1.0
	v_fma_f32 v115, -v111, v112, 1.0
	v_fmac_f32_e32 v112, v115, v112
	v_mul_f32_e32 v114, v113, v112
	v_fma_f32 v115, -v111, v114, v113
	v_fmac_f32_e32 v114, v115, v112
	v_fma_f32 v115, -v111, v114, v113
	v_div_fmas_f32 v115, v115, v112, v114
	v_div_fixup_f32 v115, v115, v110, 1.0
	v_mul_f32_e32 v121, v49, v115
	v_mul_f32_e32 v108, 0xbfb8aa3b, v50
	v_exp_f32_e32 v109, v108
	s_nop 0
	v_add_f32_e32 v110, 1.0, v109
	v_div_scale_f32 v111, s[54:55], v110, v110, 1.0
	v_rcp_f32_e32 v112, v111
	v_div_scale_f32 v113, vcc, 1.0, v110, 1.0
	v_fma_f32 v115, -v111, v112, 1.0
	v_fmac_f32_e32 v112, v115, v112
	v_mul_f32_e32 v114, v113, v112
	v_fma_f32 v115, -v111, v114, v113
	v_fmac_f32_e32 v114, v115, v112
	v_fma_f32 v115, -v111, v114, v113
	v_div_fmas_f32 v115, v115, v112, v114
	v_div_fixup_f32 v115, v115, v110, 1.0
	v_mul_f32_e32 v122, v50, v115
	v_mul_f32_e32 v108, 0xbfb8aa3b, v51
	v_exp_f32_e32 v109, v108
	s_nop 0
	v_add_f32_e32 v110, 1.0, v109
	v_div_scale_f32 v111, s[54:55], v110, v110, 1.0
	v_rcp_f32_e32 v112, v111
	v_div_scale_f32 v113, vcc, 1.0, v110, 1.0
	v_fma_f32 v115, -v111, v112, 1.0
	v_fmac_f32_e32 v112, v115, v112
	v_mul_f32_e32 v114, v113, v112
	v_fma_f32 v115, -v111, v114, v113
	v_fmac_f32_e32 v114, v115, v112
	v_fma_f32 v115, -v111, v114, v113
	v_div_fmas_f32 v115, v115, v112, v114
	v_div_fixup_f32 v115, v115, v110, 1.0
	v_mul_f32_e32 v123, v51, v115
	v_cvt_pk_bf16_f32 v124, v120, v121
	v_cvt_pk_bf16_f32 v125, v122, v123
	global_store_dwordx2 v196, v[124:125], s[44:45] offset:1024
	v_add_f32_e32 v100, v52, v53
	v_add_f32_e32 v100, v100, v54
	v_add_f32_e32 v100, v100, v55
	v_add_f32_e32 v100, v100, v56
	v_add_f32_e32 v100, v100, v57
	v_add_f32_e32 v100, v100, v58
	v_add_f32_e32 v100, v100, v59
	v_add_f32_e32 v100, v100, v60
	v_add_f32_e32 v100, v100, v61
	v_add_f32_e32 v100, v100, v62
	v_add_f32_e32 v100, v100, v63
	s_nop 1
	v_add_f32_dpp v100, v100, v100 row_shr:1 row_mask:0xf bank_mask:0xf bound_ctrl:1
	s_nop 1
	v_add_f32_dpp v100, v100, v100 row_shr:2 row_mask:0xf bank_mask:0xf bound_ctrl:1
	s_nop 1
	v_add_f32_dpp v100, v100, v100 row_shr:4 row_mask:0xf bank_mask:0xf bound_ctrl:1
	s_nop 1
	v_add_f32_dpp v100, v100, v100 row_shr:8 row_mask:0xf bank_mask:0xf bound_ctrl:1
	s_nop 1
	v_add_f32_dpp v100, v100, v100 row_bcast:15 row_mask:0xa bank_mask:0xf
	s_nop 1
	v_add_f32_dpp v100, v100, v100 row_bcast:31 row_mask:0xc bank_mask:0xf
	s_nop 0
	v_readlane_b32 s53, v100, 63
	s_nop 1
	v_mov_b32_e32 v101, s53
	v_fmac_f32_e32 v52, 0xbaaaaaab, v101
	v_fmac_f32_e32 v53, 0xbaaaaaab, v101
	v_fmac_f32_e32 v54, 0xbaaaaaab, v101
	v_fmac_f32_e32 v55, 0xbaaaaaab, v101
	v_fmac_f32_e32 v56, 0xbaaaaaab, v101
	v_fmac_f32_e32 v57, 0xbaaaaaab, v101
	v_fmac_f32_e32 v58, 0xbaaaaaab, v101
	v_fmac_f32_e32 v59, 0xbaaaaaab, v101
	v_fmac_f32_e32 v60, 0xbaaaaaab, v101
	v_fmac_f32_e32 v61, 0xbaaaaaab, v101
	v_fmac_f32_e32 v62, 0xbaaaaaab, v101
	v_fmac_f32_e32 v63, 0xbaaaaaab, v101
	v_mul_f32_e32 v102, v52, v52
	v_fmac_f32_e32 v102, v53, v53
	v_fmac_f32_e32 v102, v54, v54
	v_fmac_f32_e32 v102, v55, v55
	v_fmac_f32_e32 v102, v56, v56
	v_fmac_f32_e32 v102, v57, v57
	v_fmac_f32_e32 v102, v58, v58
	v_fmac_f32_e32 v102, v59, v59
	v_fmac_f32_e32 v102, v60, v60
	v_fmac_f32_e32 v102, v61, v61
	v_fmac_f32_e32 v102, v62, v62
	v_fmac_f32_e32 v102, v63, v63
	s_nop 1
	v_add_f32_dpp v102, v102, v102 row_shr:1 row_mask:0xf bank_mask:0xf bound_ctrl:1
	s_nop 1
	v_add_f32_dpp v102, v102, v102 row_shr:2 row_mask:0xf bank_mask:0xf bound_ctrl:1
	s_nop 1
	v_add_f32_dpp v102, v102, v102 row_shr:4 row_mask:0xf bank_mask:0xf bound_ctrl:1
	s_nop 1
	v_add_f32_dpp v102, v102, v102 row_shr:8 row_mask:0xf bank_mask:0xf bound_ctrl:1
	s_nop 1
	v_add_f32_dpp v102, v102, v102 row_bcast:15 row_mask:0xa bank_mask:0xf
	s_nop 1
	v_add_f32_dpp v102, v102, v102 row_bcast:31 row_mask:0xc bank_mask:0xf
	s_nop 0
	v_readlane_b32 s53, v102, 63
	s_nop 1
	v_mov_b32_e32 v101, s53
	v_fmamk_f32 v101, v101, 0x3aaaaaab, v197
	v_rsq_f32_e32 v103, v101
	s_nop 0
	v_mul_f32_e32 v52, v52, v103
	v_mul_f32_e32 v53, v53, v103
	v_mul_f32_e32 v54, v54, v103
	v_mul_f32_e32 v55, v55, v103
	v_mul_f32_e32 v56, v56, v103
	v_mul_f32_e32 v57, v57, v103
	v_mul_f32_e32 v58, v58, v103
	v_mul_f32_e32 v59, v59, v103
	v_mul_f32_e32 v60, v60, v103
	v_mul_f32_e32 v61, v61, v103
	v_mul_f32_e32 v62, v62, v103
	v_mul_f32_e32 v63, v63, v103
	v_fma_f32 v52, v222, v52, v234
	v_fma_f32 v53, v223, v53, v235
	v_fma_f32 v54, v224, v54, v236
	v_fma_f32 v55, v225, v55, v237
	v_fma_f32 v56, v226, v56, v238
	v_fma_f32 v57, v227, v57, v239
	v_fma_f32 v58, v228, v58, v240
	v_fma_f32 v59, v229, v59, v241
	v_fma_f32 v60, v230, v60, v242
	v_fma_f32 v61, v231, v61, v243
	v_fma_f32 v62, v232, v62, v244
	v_fma_f32 v63, v233, v63, v245
	s_lshl_b32 s52, s41, 11
	s_add_i32 s52, s52, 8192
	v_add_u32_e32 v196, s52, v3
	v_mul_f32_e32 v108, 0xbfb8aa3b, v52
	v_exp_f32_e32 v109, v108
	s_nop 0
	v_add_f32_e32 v110, 1.0, v109
	v_div_scale_f32 v111, s[54:55], v110, v110, 1.0
	v_rcp_f32_e32 v112, v111
	v_div_scale_f32 v113, vcc, 1.0, v110, 1.0
	v_fma_f32 v115, -v111, v112, 1.0
	v_fmac_f32_e32 v112, v115, v112
	v_mul_f32_e32 v114, v113, v112
	v_fma_f32 v115, -v111, v114, v113
	v_fmac_f32_e32 v114, v115, v112
	v_fma_f32 v115, -v111, v114, v113
	v_div_fmas_f32 v115, v115, v112, v114
	v_div_fixup_f32 v115, v115, v110, 1.0
	v_mul_f32_e32 v120, v52, v115
	v_mul_f32_e32 v108, 0xbfb8aa3b, v53
	v_exp_f32_e32 v109, v108
	s_nop 0
	v_add_f32_e32 v110, 1.0, v109
	v_div_scale_f32 v111, s[54:55], v110, v110, 1.0
	v_rcp_f32_e32 v112, v111
	v_div_scale_f32 v113, vcc, 1.0, v110, 1.0
	v_fma_f32 v115, -v111, v112, 1.0
	v_fmac_f32_e32 v112, v115, v112
	v_mul_f32_e32 v114, v113, v112
	v_fma_f32 v115, -v111, v114, v113
	v_fmac_f32_e32 v114, v115, v112
	v_fma_f32 v115, -v111, v114, v113
	v_div_fmas_f32 v115, v115, v112, v114
	v_div_fixup_f32 v115, v115, v110, 1.0
	v_mul_f32_e32 v121, v53, v115
	v_mul_f32_e32 v108, 0xbfb8aa3b, v54
	v_exp_f32_e32 v109, v108
	s_nop 0
	v_add_f32_e32 v110, 1.0, v109
	v_div_scale_f32 v111, s[54:55], v110, v110, 1.0
	v_rcp_f32_e32 v112, v111
	v_div_scale_f32 v113, vcc, 1.0, v110, 1.0
	v_fma_f32 v115, -v111, v112, 1.0
	v_fmac_f32_e32 v112, v115, v112
	v_mul_f32_e32 v114, v113, v112
	v_fma_f32 v115, -v111, v114, v113
	v_fmac_f32_e32 v114, v115, v112
	v_fma_f32 v115, -v111, v114, v113
	v_div_fmas_f32 v115, v115, v112, v114
	v_div_fixup_f32 v115, v115, v110, 1.0
	v_mul_f32_e32 v122, v54, v115
	v_mul_f32_e32 v108, 0xbfb8aa3b, v55
	v_exp_f32_e32 v109, v108
	s_nop 0
	v_add_f32_e32 v110, 1.0, v109
	v_div_scale_f32 v111, s[54:55], v110, v110, 1.0
	v_rcp_f32_e32 v112, v111
	v_div_scale_f32 v113, vcc, 1.0, v110, 1.0
	v_fma_f32 v115, -v111, v112, 1.0
	v_fmac_f32_e32 v112, v115, v112
	v_mul_f32_e32 v114, v113, v112
	v_fma_f32 v115, -v111, v114, v113
	v_fmac_f32_e32 v114, v115, v112
	v_fma_f32 v115, -v111, v114, v113
	v_div_fmas_f32 v115, v115, v112, v114
	v_div_fixup_f32 v115, v115, v110, 1.0
	v_mul_f32_e32 v123, v55, v115
	v_cvt_pk_bf16_f32 v124, v120, v121
	v_cvt_pk_bf16_f32 v125, v122, v123
	global_store_dwordx2 v196, v[124:125], s[44:45]
	v_mul_f32_e32 v108, 0xbfb8aa3b, v56
	v_exp_f32_e32 v109, v108
	s_nop 0
	v_add_f32_e32 v110, 1.0, v109
	v_div_scale_f32 v111, s[54:55], v110, v110, 1.0
	v_rcp_f32_e32 v112, v111
	v_div_scale_f32 v113, vcc, 1.0, v110, 1.0
	v_fma_f32 v115, -v111, v112, 1.0
	v_fmac_f32_e32 v112, v115, v112
	v_mul_f32_e32 v114, v113, v112
	v_fma_f32 v115, -v111, v114, v113
	v_fmac_f32_e32 v114, v115, v112
	v_fma_f32 v115, -v111, v114, v113
	v_div_fmas_f32 v115, v115, v112, v114
	v_div_fixup_f32 v115, v115, v110, 1.0
	v_mul_f32_e32 v120, v56, v115
	v_mul_f32_e32 v108, 0xbfb8aa3b, v57
	v_exp_f32_e32 v109, v108
	s_nop 0
	v_add_f32_e32 v110, 1.0, v109
	v_div_scale_f32 v111, s[54:55], v110, v110, 1.0
	v_rcp_f32_e32 v112, v111
	v_div_scale_f32 v113, vcc, 1.0, v110, 1.0
	v_fma_f32 v115, -v111, v112, 1.0
	v_fmac_f32_e32 v112, v115, v112
	v_mul_f32_e32 v114, v113, v112
	v_fma_f32 v115, -v111, v114, v113
	v_fmac_f32_e32 v114, v115, v112
	v_fma_f32 v115, -v111, v114, v113
	v_div_fmas_f32 v115, v115, v112, v114
	v_div_fixup_f32 v115, v115, v110, 1.0
	v_mul_f32_e32 v121, v57, v115
	v_mul_f32_e32 v108, 0xbfb8aa3b, v58
	v_exp_f32_e32 v109, v108
	s_nop 0
	v_add_f32_e32 v110, 1.0, v109
	v_div_scale_f32 v111, s[54:55], v110, v110, 1.0
	v_rcp_f32_e32 v112, v111
	v_div_scale_f32 v113, vcc, 1.0, v110, 1.0
	v_fma_f32 v115, -v111, v112, 1.0
	v_fmac_f32_e32 v112, v115, v112
	v_mul_f32_e32 v114, v113, v112
	v_fma_f32 v115, -v111, v114, v113
	v_fmac_f32_e32 v114, v115, v112
	v_fma_f32 v115, -v111, v114, v113
	v_div_fmas_f32 v115, v115, v112, v114
	v_div_fixup_f32 v115, v115, v110, 1.0
	v_mul_f32_e32 v122, v58, v115
	v_mul_f32_e32 v108, 0xbfb8aa3b, v59
	v_exp_f32_e32 v109, v108
	s_nop 0
	v_add_f32_e32 v110, 1.0, v109
	v_div_scale_f32 v111, s[54:55], v110, v110, 1.0
	v_rcp_f32_e32 v112, v111
	v_div_scale_f32 v113, vcc, 1.0, v110, 1.0
	v_fma_f32 v115, -v111, v112, 1.0
	v_fmac_f32_e32 v112, v115, v112
	v_mul_f32_e32 v114, v113, v112
	v_fma_f32 v115, -v111, v114, v113
	v_fmac_f32_e32 v114, v115, v112
	v_fma_f32 v115, -v111, v114, v113
	v_div_fmas_f32 v115, v115, v112, v114
	v_div_fixup_f32 v115, v115, v110, 1.0
	v_mul_f32_e32 v123, v59, v115
	v_cvt_pk_bf16_f32 v124, v120, v121
	v_cvt_pk_bf16_f32 v125, v122, v123
	global_store_dwordx2 v196, v[124:125], s[44:45] offset:512
	v_mul_f32_e32 v108, 0xbfb8aa3b, v60
	v_exp_f32_e32 v109, v108
	s_nop 0
	v_add_f32_e32 v110, 1.0, v109
	v_div_scale_f32 v111, s[54:55], v110, v110, 1.0
	v_rcp_f32_e32 v112, v111
	v_div_scale_f32 v113, vcc, 1.0, v110, 1.0
	v_fma_f32 v115, -v111, v112, 1.0
	v_fmac_f32_e32 v112, v115, v112
	v_mul_f32_e32 v114, v113, v112
	v_fma_f32 v115, -v111, v114, v113
	v_fmac_f32_e32 v114, v115, v112
	v_fma_f32 v115, -v111, v114, v113
	v_div_fmas_f32 v115, v115, v112, v114
	v_div_fixup_f32 v115, v115, v110, 1.0
	v_mul_f32_e32 v120, v60, v115
	v_mul_f32_e32 v108, 0xbfb8aa3b, v61
	v_exp_f32_e32 v109, v108
	s_nop 0
	v_add_f32_e32 v110, 1.0, v109
	v_div_scale_f32 v111, s[54:55], v110, v110, 1.0
	v_rcp_f32_e32 v112, v111
	v_div_scale_f32 v113, vcc, 1.0, v110, 1.0
	v_fma_f32 v115, -v111, v112, 1.0
	v_fmac_f32_e32 v112, v115, v112
	v_mul_f32_e32 v114, v113, v112
	v_fma_f32 v115, -v111, v114, v113
	v_fmac_f32_e32 v114, v115, v112
	v_fma_f32 v115, -v111, v114, v113
	v_div_fmas_f32 v115, v115, v112, v114
	v_div_fixup_f32 v115, v115, v110, 1.0
	v_mul_f32_e32 v121, v61, v115
	v_mul_f32_e32 v108, 0xbfb8aa3b, v62
	v_exp_f32_e32 v109, v108
	s_nop 0
	v_add_f32_e32 v110, 1.0, v109
	v_div_scale_f32 v111, s[54:55], v110, v110, 1.0
	v_rcp_f32_e32 v112, v111
	v_div_scale_f32 v113, vcc, 1.0, v110, 1.0
	v_fma_f32 v115, -v111, v112, 1.0
	v_fmac_f32_e32 v112, v115, v112
	v_mul_f32_e32 v114, v113, v112
	v_fma_f32 v115, -v111, v114, v113
	v_fmac_f32_e32 v114, v115, v112
	v_fma_f32 v115, -v111, v114, v113
	v_div_fmas_f32 v115, v115, v112, v114
	v_div_fixup_f32 v115, v115, v110, 1.0
	v_mul_f32_e32 v122, v62, v115
	v_mul_f32_e32 v108, 0xbfb8aa3b, v63
	v_exp_f32_e32 v109, v108
	s_nop 0
	v_add_f32_e32 v110, 1.0, v109
	v_div_scale_f32 v111, s[54:55], v110, v110, 1.0
	v_rcp_f32_e32 v112, v111
	v_div_scale_f32 v113, vcc, 1.0, v110, 1.0
	v_fma_f32 v115, -v111, v112, 1.0
	v_fmac_f32_e32 v112, v115, v112
	v_mul_f32_e32 v114, v113, v112
	v_fma_f32 v115, -v111, v114, v113
	v_fmac_f32_e32 v114, v115, v112
	v_fma_f32 v115, -v111, v114, v113
	v_div_fmas_f32 v115, v115, v112, v114
	v_div_fixup_f32 v115, v115, v110, 1.0
	v_mul_f32_e32 v123, v63, v115
	v_cvt_pk_bf16_f32 v124, v120, v121
	v_cvt_pk_bf16_f32 v125, v122, v123
	global_store_dwordx2 v196, v[124:125], s[44:45] offset:1024
	v_add_f32_e32 v100, v64, v65
	v_add_f32_e32 v100, v100, v66
	v_add_f32_e32 v100, v100, v67
	v_add_f32_e32 v100, v100, v68
	v_add_f32_e32 v100, v100, v69
	v_add_f32_e32 v100, v100, v70
	v_add_f32_e32 v100, v100, v71
	v_add_f32_e32 v100, v100, v72
	v_add_f32_e32 v100, v100, v73
	v_add_f32_e32 v100, v100, v74
	v_add_f32_e32 v100, v100, v75
	s_nop 1
	v_add_f32_dpp v100, v100, v100 row_shr:1 row_mask:0xf bank_mask:0xf bound_ctrl:1
	s_nop 1
	v_add_f32_dpp v100, v100, v100 row_shr:2 row_mask:0xf bank_mask:0xf bound_ctrl:1
	s_nop 1
	v_add_f32_dpp v100, v100, v100 row_shr:4 row_mask:0xf bank_mask:0xf bound_ctrl:1
	s_nop 1
	v_add_f32_dpp v100, v100, v100 row_shr:8 row_mask:0xf bank_mask:0xf bound_ctrl:1
	s_nop 1
	v_add_f32_dpp v100, v100, v100 row_bcast:15 row_mask:0xa bank_mask:0xf
	s_nop 1
	v_add_f32_dpp v100, v100, v100 row_bcast:31 row_mask:0xc bank_mask:0xf
	s_nop 0
	v_readlane_b32 s53, v100, 63
	s_nop 1
	v_mov_b32_e32 v101, s53
	v_fmac_f32_e32 v64, 0xbaaaaaab, v101
	v_fmac_f32_e32 v65, 0xbaaaaaab, v101
	v_fmac_f32_e32 v66, 0xbaaaaaab, v101
	v_fmac_f32_e32 v67, 0xbaaaaaab, v101
	v_fmac_f32_e32 v68, 0xbaaaaaab, v101
	v_fmac_f32_e32 v69, 0xbaaaaaab, v101
	v_fmac_f32_e32 v70, 0xbaaaaaab, v101
	v_fmac_f32_e32 v71, 0xbaaaaaab, v101
	v_fmac_f32_e32 v72, 0xbaaaaaab, v101
	v_fmac_f32_e32 v73, 0xbaaaaaab, v101
	v_fmac_f32_e32 v74, 0xbaaaaaab, v101
	v_fmac_f32_e32 v75, 0xbaaaaaab, v101
	v_mul_f32_e32 v102, v64, v64
	v_fmac_f32_e32 v102, v65, v65
	v_fmac_f32_e32 v102, v66, v66
	v_fmac_f32_e32 v102, v67, v67
	v_fmac_f32_e32 v102, v68, v68
	v_fmac_f32_e32 v102, v69, v69
	v_fmac_f32_e32 v102, v70, v70
	v_fmac_f32_e32 v102, v71, v71
	v_fmac_f32_e32 v102, v72, v72
	v_fmac_f32_e32 v102, v73, v73
	v_fmac_f32_e32 v102, v74, v74
	v_fmac_f32_e32 v102, v75, v75
	s_nop 1
	v_add_f32_dpp v102, v102, v102 row_shr:1 row_mask:0xf bank_mask:0xf bound_ctrl:1
	s_nop 1
	v_add_f32_dpp v102, v102, v102 row_shr:2 row_mask:0xf bank_mask:0xf bound_ctrl:1
	s_nop 1
	v_add_f32_dpp v102, v102, v102 row_shr:4 row_mask:0xf bank_mask:0xf bound_ctrl:1
	s_nop 1
	v_add_f32_dpp v102, v102, v102 row_shr:8 row_mask:0xf bank_mask:0xf bound_ctrl:1
	s_nop 1
	v_add_f32_dpp v102, v102, v102 row_bcast:15 row_mask:0xa bank_mask:0xf
	s_nop 1
	v_add_f32_dpp v102, v102, v102 row_bcast:31 row_mask:0xc bank_mask:0xf
	s_nop 0
	v_readlane_b32 s53, v102, 63
	s_nop 1
	v_mov_b32_e32 v101, s53
	v_fmamk_f32 v101, v101, 0x3aaaaaab, v197
	v_rsq_f32_e32 v103, v101
	s_nop 0
	v_mul_f32_e32 v64, v64, v103
	v_mul_f32_e32 v65, v65, v103
	v_mul_f32_e32 v66, v66, v103
	v_mul_f32_e32 v67, v67, v103
	v_mul_f32_e32 v68, v68, v103
	v_mul_f32_e32 v69, v69, v103
	v_mul_f32_e32 v70, v70, v103
	v_mul_f32_e32 v71, v71, v103
	v_mul_f32_e32 v72, v72, v103
	v_mul_f32_e32 v73, v73, v103
	v_mul_f32_e32 v74, v74, v103
	v_mul_f32_e32 v75, v75, v103
	v_fma_f32 v64, v222, v64, v234
	v_fma_f32 v65, v223, v65, v235
	v_fma_f32 v66, v224, v66, v236
	v_fma_f32 v67, v225, v67, v237
	v_fma_f32 v68, v226, v68, v238
	v_fma_f32 v69, v227, v69, v239
	v_fma_f32 v70, v228, v70, v240
	v_fma_f32 v71, v229, v71, v241
	v_fma_f32 v72, v230, v72, v242
	v_fma_f32 v73, v231, v73, v243
	v_fma_f32 v74, v232, v74, v244
	v_fma_f32 v75, v233, v75, v245
	s_lshl_b32 s52, s41, 11
	s_add_i32 s52, s52, 10240
	v_add_u32_e32 v196, s52, v3
	v_mul_f32_e32 v108, 0xbfb8aa3b, v64
	v_exp_f32_e32 v109, v108
	s_nop 0
	v_add_f32_e32 v110, 1.0, v109
	v_div_scale_f32 v111, s[54:55], v110, v110, 1.0
	v_rcp_f32_e32 v112, v111
	v_div_scale_f32 v113, vcc, 1.0, v110, 1.0
	v_fma_f32 v115, -v111, v112, 1.0
	v_fmac_f32_e32 v112, v115, v112
	v_mul_f32_e32 v114, v113, v112
	v_fma_f32 v115, -v111, v114, v113
	v_fmac_f32_e32 v114, v115, v112
	v_fma_f32 v115, -v111, v114, v113
	v_div_fmas_f32 v115, v115, v112, v114
	v_div_fixup_f32 v115, v115, v110, 1.0
	v_mul_f32_e32 v120, v64, v115
	v_mul_f32_e32 v108, 0xbfb8aa3b, v65
	v_exp_f32_e32 v109, v108
	s_nop 0
	v_add_f32_e32 v110, 1.0, v109
	v_div_scale_f32 v111, s[54:55], v110, v110, 1.0
	v_rcp_f32_e32 v112, v111
	v_div_scale_f32 v113, vcc, 1.0, v110, 1.0
	v_fma_f32 v115, -v111, v112, 1.0
	v_fmac_f32_e32 v112, v115, v112
	v_mul_f32_e32 v114, v113, v112
	v_fma_f32 v115, -v111, v114, v113
	v_fmac_f32_e32 v114, v115, v112
	v_fma_f32 v115, -v111, v114, v113
	v_div_fmas_f32 v115, v115, v112, v114
	v_div_fixup_f32 v115, v115, v110, 1.0
	v_mul_f32_e32 v121, v65, v115
	v_mul_f32_e32 v108, 0xbfb8aa3b, v66
	v_exp_f32_e32 v109, v108
	s_nop 0
	v_add_f32_e32 v110, 1.0, v109
	v_div_scale_f32 v111, s[54:55], v110, v110, 1.0
	v_rcp_f32_e32 v112, v111
	v_div_scale_f32 v113, vcc, 1.0, v110, 1.0
	v_fma_f32 v115, -v111, v112, 1.0
	v_fmac_f32_e32 v112, v115, v112
	v_mul_f32_e32 v114, v113, v112
	v_fma_f32 v115, -v111, v114, v113
	v_fmac_f32_e32 v114, v115, v112
	v_fma_f32 v115, -v111, v114, v113
	v_div_fmas_f32 v115, v115, v112, v114
	v_div_fixup_f32 v115, v115, v110, 1.0
	v_mul_f32_e32 v122, v66, v115
	v_mul_f32_e32 v108, 0xbfb8aa3b, v67
	v_exp_f32_e32 v109, v108
	s_nop 0
	v_add_f32_e32 v110, 1.0, v109
	v_div_scale_f32 v111, s[54:55], v110, v110, 1.0
	v_rcp_f32_e32 v112, v111
	v_div_scale_f32 v113, vcc, 1.0, v110, 1.0
	v_fma_f32 v115, -v111, v112, 1.0
	v_fmac_f32_e32 v112, v115, v112
	v_mul_f32_e32 v114, v113, v112
	v_fma_f32 v115, -v111, v114, v113
	v_fmac_f32_e32 v114, v115, v112
	v_fma_f32 v115, -v111, v114, v113
	v_div_fmas_f32 v115, v115, v112, v114
	v_div_fixup_f32 v115, v115, v110, 1.0
	v_mul_f32_e32 v123, v67, v115
	v_cvt_pk_bf16_f32 v124, v120, v121
	v_cvt_pk_bf16_f32 v125, v122, v123
	global_store_dwordx2 v196, v[124:125], s[44:45]
	v_mul_f32_e32 v108, 0xbfb8aa3b, v68
	v_exp_f32_e32 v109, v108
	s_nop 0
	v_add_f32_e32 v110, 1.0, v109
	v_div_scale_f32 v111, s[54:55], v110, v110, 1.0
	v_rcp_f32_e32 v112, v111
	v_div_scale_f32 v113, vcc, 1.0, v110, 1.0
	v_fma_f32 v115, -v111, v112, 1.0
	v_fmac_f32_e32 v112, v115, v112
	v_mul_f32_e32 v114, v113, v112
	v_fma_f32 v115, -v111, v114, v113
	v_fmac_f32_e32 v114, v115, v112
	v_fma_f32 v115, -v111, v114, v113
	v_div_fmas_f32 v115, v115, v112, v114
	v_div_fixup_f32 v115, v115, v110, 1.0
	v_mul_f32_e32 v120, v68, v115
	v_mul_f32_e32 v108, 0xbfb8aa3b, v69
	v_exp_f32_e32 v109, v108
	s_nop 0
	v_add_f32_e32 v110, 1.0, v109
	v_div_scale_f32 v111, s[54:55], v110, v110, 1.0
	v_rcp_f32_e32 v112, v111
	v_div_scale_f32 v113, vcc, 1.0, v110, 1.0
	v_fma_f32 v115, -v111, v112, 1.0
	v_fmac_f32_e32 v112, v115, v112
	v_mul_f32_e32 v114, v113, v112
	v_fma_f32 v115, -v111, v114, v113
	v_fmac_f32_e32 v114, v115, v112
	v_fma_f32 v115, -v111, v114, v113
	v_div_fmas_f32 v115, v115, v112, v114
	v_div_fixup_f32 v115, v115, v110, 1.0
	v_mul_f32_e32 v121, v69, v115
	v_mul_f32_e32 v108, 0xbfb8aa3b, v70
	v_exp_f32_e32 v109, v108
	s_nop 0
	v_add_f32_e32 v110, 1.0, v109
	v_div_scale_f32 v111, s[54:55], v110, v110, 1.0
	v_rcp_f32_e32 v112, v111
	v_div_scale_f32 v113, vcc, 1.0, v110, 1.0
	v_fma_f32 v115, -v111, v112, 1.0
	v_fmac_f32_e32 v112, v115, v112
	v_mul_f32_e32 v114, v113, v112
	v_fma_f32 v115, -v111, v114, v113
	v_fmac_f32_e32 v114, v115, v112
	v_fma_f32 v115, -v111, v114, v113
	v_div_fmas_f32 v115, v115, v112, v114
	v_div_fixup_f32 v115, v115, v110, 1.0
	v_mul_f32_e32 v122, v70, v115
	v_mul_f32_e32 v108, 0xbfb8aa3b, v71
	v_exp_f32_e32 v109, v108
	s_nop 0
	v_add_f32_e32 v110, 1.0, v109
	v_div_scale_f32 v111, s[54:55], v110, v110, 1.0
	v_rcp_f32_e32 v112, v111
	v_div_scale_f32 v113, vcc, 1.0, v110, 1.0
	v_fma_f32 v115, -v111, v112, 1.0
	v_fmac_f32_e32 v112, v115, v112
	v_mul_f32_e32 v114, v113, v112
	v_fma_f32 v115, -v111, v114, v113
	v_fmac_f32_e32 v114, v115, v112
	v_fma_f32 v115, -v111, v114, v113
	v_div_fmas_f32 v115, v115, v112, v114
	v_div_fixup_f32 v115, v115, v110, 1.0
	v_mul_f32_e32 v123, v71, v115
	v_cvt_pk_bf16_f32 v124, v120, v121
	v_cvt_pk_bf16_f32 v125, v122, v123
	global_store_dwordx2 v196, v[124:125], s[44:45] offset:512
	v_mul_f32_e32 v108, 0xbfb8aa3b, v72
	v_exp_f32_e32 v109, v108
	s_nop 0
	v_add_f32_e32 v110, 1.0, v109
	v_div_scale_f32 v111, s[54:55], v110, v110, 1.0
	v_rcp_f32_e32 v112, v111
	v_div_scale_f32 v113, vcc, 1.0, v110, 1.0
	v_fma_f32 v115, -v111, v112, 1.0
	v_fmac_f32_e32 v112, v115, v112
	v_mul_f32_e32 v114, v113, v112
	v_fma_f32 v115, -v111, v114, v113
	v_fmac_f32_e32 v114, v115, v112
	v_fma_f32 v115, -v111, v114, v113
	v_div_fmas_f32 v115, v115, v112, v114
	v_div_fixup_f32 v115, v115, v110, 1.0
	v_mul_f32_e32 v120, v72, v115
	v_mul_f32_e32 v108, 0xbfb8aa3b, v73
	v_exp_f32_e32 v109, v108
	s_nop 0
	v_add_f32_e32 v110, 1.0, v109
	v_div_scale_f32 v111, s[54:55], v110, v110, 1.0
	v_rcp_f32_e32 v112, v111
	v_div_scale_f32 v113, vcc, 1.0, v110, 1.0
	v_fma_f32 v115, -v111, v112, 1.0
	v_fmac_f32_e32 v112, v115, v112
	v_mul_f32_e32 v114, v113, v112
	v_fma_f32 v115, -v111, v114, v113
	v_fmac_f32_e32 v114, v115, v112
	v_fma_f32 v115, -v111, v114, v113
	v_div_fmas_f32 v115, v115, v112, v114
	v_div_fixup_f32 v115, v115, v110, 1.0
	v_mul_f32_e32 v121, v73, v115
	v_mul_f32_e32 v108, 0xbfb8aa3b, v74
	v_exp_f32_e32 v109, v108
	s_nop 0
	v_add_f32_e32 v110, 1.0, v109
	v_div_scale_f32 v111, s[54:55], v110, v110, 1.0
	v_rcp_f32_e32 v112, v111
	v_div_scale_f32 v113, vcc, 1.0, v110, 1.0
	v_fma_f32 v115, -v111, v112, 1.0
	v_fmac_f32_e32 v112, v115, v112
	v_mul_f32_e32 v114, v113, v112
	v_fma_f32 v115, -v111, v114, v113
	v_fmac_f32_e32 v114, v115, v112
	v_fma_f32 v115, -v111, v114, v113
	v_div_fmas_f32 v115, v115, v112, v114
	v_div_fixup_f32 v115, v115, v110, 1.0
	v_mul_f32_e32 v122, v74, v115
	v_mul_f32_e32 v108, 0xbfb8aa3b, v75
	v_exp_f32_e32 v109, v108
	s_nop 0
	v_add_f32_e32 v110, 1.0, v109
	v_div_scale_f32 v111, s[54:55], v110, v110, 1.0
	v_rcp_f32_e32 v112, v111
	v_div_scale_f32 v113, vcc, 1.0, v110, 1.0
	v_fma_f32 v115, -v111, v112, 1.0
	v_fmac_f32_e32 v112, v115, v112
	v_mul_f32_e32 v114, v113, v112
	v_fma_f32 v115, -v111, v114, v113
	v_fmac_f32_e32 v114, v115, v112
	v_fma_f32 v115, -v111, v114, v113
	v_div_fmas_f32 v115, v115, v112, v114
	v_div_fixup_f32 v115, v115, v110, 1.0
	v_mul_f32_e32 v123, v75, v115
	v_cvt_pk_bf16_f32 v124, v120, v121
	v_cvt_pk_bf16_f32 v125, v122, v123
	global_store_dwordx2 v196, v[124:125], s[44:45] offset:1024
	v_add_f32_e32 v100, v76, v77
	v_add_f32_e32 v100, v100, v78
	v_add_f32_e32 v100, v100, v79
	v_add_f32_e32 v100, v100, v80
	v_add_f32_e32 v100, v100, v81
	v_add_f32_e32 v100, v100, v82
	v_add_f32_e32 v100, v100, v83
	v_add_f32_e32 v100, v100, v84
	v_add_f32_e32 v100, v100, v85
	v_add_f32_e32 v100, v100, v86
	v_add_f32_e32 v100, v100, v87
	s_nop 1
	v_add_f32_dpp v100, v100, v100 row_shr:1 row_mask:0xf bank_mask:0xf bound_ctrl:1
	s_nop 1
	v_add_f32_dpp v100, v100, v100 row_shr:2 row_mask:0xf bank_mask:0xf bound_ctrl:1
	s_nop 1
	v_add_f32_dpp v100, v100, v100 row_shr:4 row_mask:0xf bank_mask:0xf bound_ctrl:1
	s_nop 1
	v_add_f32_dpp v100, v100, v100 row_shr:8 row_mask:0xf bank_mask:0xf bound_ctrl:1
	s_nop 1
	v_add_f32_dpp v100, v100, v100 row_bcast:15 row_mask:0xa bank_mask:0xf
	s_nop 1
	v_add_f32_dpp v100, v100, v100 row_bcast:31 row_mask:0xc bank_mask:0xf
	s_nop 0
	v_readlane_b32 s53, v100, 63
	s_nop 1
	v_mov_b32_e32 v101, s53
	v_fmac_f32_e32 v76, 0xbaaaaaab, v101
	v_fmac_f32_e32 v77, 0xbaaaaaab, v101
	v_fmac_f32_e32 v78, 0xbaaaaaab, v101
	v_fmac_f32_e32 v79, 0xbaaaaaab, v101
	v_fmac_f32_e32 v80, 0xbaaaaaab, v101
	v_fmac_f32_e32 v81, 0xbaaaaaab, v101
	v_fmac_f32_e32 v82, 0xbaaaaaab, v101
	v_fmac_f32_e32 v83, 0xbaaaaaab, v101
	v_fmac_f32_e32 v84, 0xbaaaaaab, v101
	v_fmac_f32_e32 v85, 0xbaaaaaab, v101
	v_fmac_f32_e32 v86, 0xbaaaaaab, v101
	v_fmac_f32_e32 v87, 0xbaaaaaab, v101
	v_mul_f32_e32 v102, v76, v76
	v_fmac_f32_e32 v102, v77, v77
	v_fmac_f32_e32 v102, v78, v78
	v_fmac_f32_e32 v102, v79, v79
	v_fmac_f32_e32 v102, v80, v80
	v_fmac_f32_e32 v102, v81, v81
	v_fmac_f32_e32 v102, v82, v82
	v_fmac_f32_e32 v102, v83, v83
	v_fmac_f32_e32 v102, v84, v84
	v_fmac_f32_e32 v102, v85, v85
	v_fmac_f32_e32 v102, v86, v86
	v_fmac_f32_e32 v102, v87, v87
	s_nop 1
	v_add_f32_dpp v102, v102, v102 row_shr:1 row_mask:0xf bank_mask:0xf bound_ctrl:1
	s_nop 1
	v_add_f32_dpp v102, v102, v102 row_shr:2 row_mask:0xf bank_mask:0xf bound_ctrl:1
	s_nop 1
	v_add_f32_dpp v102, v102, v102 row_shr:4 row_mask:0xf bank_mask:0xf bound_ctrl:1
	s_nop 1
	v_add_f32_dpp v102, v102, v102 row_shr:8 row_mask:0xf bank_mask:0xf bound_ctrl:1
	s_nop 1
	v_add_f32_dpp v102, v102, v102 row_bcast:15 row_mask:0xa bank_mask:0xf
	s_nop 1
	v_add_f32_dpp v102, v102, v102 row_bcast:31 row_mask:0xc bank_mask:0xf
	s_nop 0
	v_readlane_b32 s53, v102, 63
	s_nop 1
	v_mov_b32_e32 v101, s53
	v_fmamk_f32 v101, v101, 0x3aaaaaab, v197
	v_rsq_f32_e32 v103, v101
	s_nop 0
	v_mul_f32_e32 v76, v76, v103
	v_mul_f32_e32 v77, v77, v103
	v_mul_f32_e32 v78, v78, v103
	v_mul_f32_e32 v79, v79, v103
	v_mul_f32_e32 v80, v80, v103
	v_mul_f32_e32 v81, v81, v103
	v_mul_f32_e32 v82, v82, v103
	v_mul_f32_e32 v83, v83, v103
	v_mul_f32_e32 v84, v84, v103
	v_mul_f32_e32 v85, v85, v103
	v_mul_f32_e32 v86, v86, v103
	v_mul_f32_e32 v87, v87, v103
	v_fma_f32 v76, v222, v76, v234
	v_fma_f32 v77, v223, v77, v235
	v_fma_f32 v78, v224, v78, v236
	v_fma_f32 v79, v225, v79, v237
	v_fma_f32 v80, v226, v80, v238
	v_fma_f32 v81, v227, v81, v239
	v_fma_f32 v82, v228, v82, v240
	v_fma_f32 v83, v229, v83, v241
	v_fma_f32 v84, v230, v84, v242
	v_fma_f32 v85, v231, v85, v243
	v_fma_f32 v86, v232, v86, v244
	v_fma_f32 v87, v233, v87, v245
	s_lshl_b32 s52, s41, 11
	s_add_i32 s52, s52, 12288
	v_add_u32_e32 v196, s52, v3
	v_mul_f32_e32 v108, 0xbfb8aa3b, v76
	v_exp_f32_e32 v109, v108
	s_nop 0
	v_add_f32_e32 v110, 1.0, v109
	v_div_scale_f32 v111, s[54:55], v110, v110, 1.0
	v_rcp_f32_e32 v112, v111
	v_div_scale_f32 v113, vcc, 1.0, v110, 1.0
	v_fma_f32 v115, -v111, v112, 1.0
	v_fmac_f32_e32 v112, v115, v112
	v_mul_f32_e32 v114, v113, v112
	v_fma_f32 v115, -v111, v114, v113
	v_fmac_f32_e32 v114, v115, v112
	v_fma_f32 v115, -v111, v114, v113
	v_div_fmas_f32 v115, v115, v112, v114
	v_div_fixup_f32 v115, v115, v110, 1.0
	v_mul_f32_e32 v120, v76, v115
	v_mul_f32_e32 v108, 0xbfb8aa3b, v77
	v_exp_f32_e32 v109, v108
	s_nop 0
	v_add_f32_e32 v110, 1.0, v109
	v_div_scale_f32 v111, s[54:55], v110, v110, 1.0
	v_rcp_f32_e32 v112, v111
	v_div_scale_f32 v113, vcc, 1.0, v110, 1.0
	v_fma_f32 v115, -v111, v112, 1.0
	v_fmac_f32_e32 v112, v115, v112
	v_mul_f32_e32 v114, v113, v112
	v_fma_f32 v115, -v111, v114, v113
	v_fmac_f32_e32 v114, v115, v112
	v_fma_f32 v115, -v111, v114, v113
	v_div_fmas_f32 v115, v115, v112, v114
	v_div_fixup_f32 v115, v115, v110, 1.0
	v_mul_f32_e32 v121, v77, v115
	v_mul_f32_e32 v108, 0xbfb8aa3b, v78
	v_exp_f32_e32 v109, v108
	s_nop 0
	v_add_f32_e32 v110, 1.0, v109
	v_div_scale_f32 v111, s[54:55], v110, v110, 1.0
	v_rcp_f32_e32 v112, v111
	v_div_scale_f32 v113, vcc, 1.0, v110, 1.0
	v_fma_f32 v115, -v111, v112, 1.0
	v_fmac_f32_e32 v112, v115, v112
	v_mul_f32_e32 v114, v113, v112
	v_fma_f32 v115, -v111, v114, v113
	v_fmac_f32_e32 v114, v115, v112
	v_fma_f32 v115, -v111, v114, v113
	v_div_fmas_f32 v115, v115, v112, v114
	v_div_fixup_f32 v115, v115, v110, 1.0
	v_mul_f32_e32 v122, v78, v115
	v_mul_f32_e32 v108, 0xbfb8aa3b, v79
	v_exp_f32_e32 v109, v108
	s_nop 0
	v_add_f32_e32 v110, 1.0, v109
	v_div_scale_f32 v111, s[54:55], v110, v110, 1.0
	v_rcp_f32_e32 v112, v111
	v_div_scale_f32 v113, vcc, 1.0, v110, 1.0
	v_fma_f32 v115, -v111, v112, 1.0
	v_fmac_f32_e32 v112, v115, v112
	v_mul_f32_e32 v114, v113, v112
	v_fma_f32 v115, -v111, v114, v113
	v_fmac_f32_e32 v114, v115, v112
	v_fma_f32 v115, -v111, v114, v113
	v_div_fmas_f32 v115, v115, v112, v114
	v_div_fixup_f32 v115, v115, v110, 1.0
	v_mul_f32_e32 v123, v79, v115
	v_cvt_pk_bf16_f32 v124, v120, v121
	v_cvt_pk_bf16_f32 v125, v122, v123
	global_store_dwordx2 v196, v[124:125], s[44:45]
	v_mul_f32_e32 v108, 0xbfb8aa3b, v80
	v_exp_f32_e32 v109, v108
	s_nop 0
	v_add_f32_e32 v110, 1.0, v109
	v_div_scale_f32 v111, s[54:55], v110, v110, 1.0
	v_rcp_f32_e32 v112, v111
	v_div_scale_f32 v113, vcc, 1.0, v110, 1.0
	v_fma_f32 v115, -v111, v112, 1.0
	v_fmac_f32_e32 v112, v115, v112
	v_mul_f32_e32 v114, v113, v112
	v_fma_f32 v115, -v111, v114, v113
	v_fmac_f32_e32 v114, v115, v112
	v_fma_f32 v115, -v111, v114, v113
	v_div_fmas_f32 v115, v115, v112, v114
	v_div_fixup_f32 v115, v115, v110, 1.0
	v_mul_f32_e32 v120, v80, v115
	v_mul_f32_e32 v108, 0xbfb8aa3b, v81
	v_exp_f32_e32 v109, v108
	s_nop 0
	v_add_f32_e32 v110, 1.0, v109
	v_div_scale_f32 v111, s[54:55], v110, v110, 1.0
	v_rcp_f32_e32 v112, v111
	v_div_scale_f32 v113, vcc, 1.0, v110, 1.0
	v_fma_f32 v115, -v111, v112, 1.0
	v_fmac_f32_e32 v112, v115, v112
	v_mul_f32_e32 v114, v113, v112
	v_fma_f32 v115, -v111, v114, v113
	v_fmac_f32_e32 v114, v115, v112
	v_fma_f32 v115, -v111, v114, v113
	v_div_fmas_f32 v115, v115, v112, v114
	v_div_fixup_f32 v115, v115, v110, 1.0
	v_mul_f32_e32 v121, v81, v115
	v_mul_f32_e32 v108, 0xbfb8aa3b, v82
	v_exp_f32_e32 v109, v108
	s_nop 0
	v_add_f32_e32 v110, 1.0, v109
	v_div_scale_f32 v111, s[54:55], v110, v110, 1.0
	v_rcp_f32_e32 v112, v111
	v_div_scale_f32 v113, vcc, 1.0, v110, 1.0
	v_fma_f32 v115, -v111, v112, 1.0
	v_fmac_f32_e32 v112, v115, v112
	v_mul_f32_e32 v114, v113, v112
	v_fma_f32 v115, -v111, v114, v113
	v_fmac_f32_e32 v114, v115, v112
	v_fma_f32 v115, -v111, v114, v113
	v_div_fmas_f32 v115, v115, v112, v114
	v_div_fixup_f32 v115, v115, v110, 1.0
	v_mul_f32_e32 v122, v82, v115
	v_mul_f32_e32 v108, 0xbfb8aa3b, v83
	v_exp_f32_e32 v109, v108
	s_nop 0
	v_add_f32_e32 v110, 1.0, v109
	v_div_scale_f32 v111, s[54:55], v110, v110, 1.0
	v_rcp_f32_e32 v112, v111
	v_div_scale_f32 v113, vcc, 1.0, v110, 1.0
	v_fma_f32 v115, -v111, v112, 1.0
	v_fmac_f32_e32 v112, v115, v112
	v_mul_f32_e32 v114, v113, v112
	v_fma_f32 v115, -v111, v114, v113
	v_fmac_f32_e32 v114, v115, v112
	v_fma_f32 v115, -v111, v114, v113
	v_div_fmas_f32 v115, v115, v112, v114
	v_div_fixup_f32 v115, v115, v110, 1.0
	v_mul_f32_e32 v123, v83, v115
	v_cvt_pk_bf16_f32 v124, v120, v121
	v_cvt_pk_bf16_f32 v125, v122, v123
	global_store_dwordx2 v196, v[124:125], s[44:45] offset:512
	v_mul_f32_e32 v108, 0xbfb8aa3b, v84
	v_exp_f32_e32 v109, v108
	s_nop 0
	v_add_f32_e32 v110, 1.0, v109
	v_div_scale_f32 v111, s[54:55], v110, v110, 1.0
	v_rcp_f32_e32 v112, v111
	v_div_scale_f32 v113, vcc, 1.0, v110, 1.0
	v_fma_f32 v115, -v111, v112, 1.0
	v_fmac_f32_e32 v112, v115, v112
	v_mul_f32_e32 v114, v113, v112
	v_fma_f32 v115, -v111, v114, v113
	v_fmac_f32_e32 v114, v115, v112
	v_fma_f32 v115, -v111, v114, v113
	v_div_fmas_f32 v115, v115, v112, v114
	v_div_fixup_f32 v115, v115, v110, 1.0
	v_mul_f32_e32 v120, v84, v115
	v_mul_f32_e32 v108, 0xbfb8aa3b, v85
	v_exp_f32_e32 v109, v108
	s_nop 0
	v_add_f32_e32 v110, 1.0, v109
	v_div_scale_f32 v111, s[54:55], v110, v110, 1.0
	v_rcp_f32_e32 v112, v111
	v_div_scale_f32 v113, vcc, 1.0, v110, 1.0
	v_fma_f32 v115, -v111, v112, 1.0
	v_fmac_f32_e32 v112, v115, v112
	v_mul_f32_e32 v114, v113, v112
	v_fma_f32 v115, -v111, v114, v113
	v_fmac_f32_e32 v114, v115, v112
	v_fma_f32 v115, -v111, v114, v113
	v_div_fmas_f32 v115, v115, v112, v114
	v_div_fixup_f32 v115, v115, v110, 1.0
	v_mul_f32_e32 v121, v85, v115
	v_mul_f32_e32 v108, 0xbfb8aa3b, v86
	v_exp_f32_e32 v109, v108
	s_nop 0
	v_add_f32_e32 v110, 1.0, v109
	v_div_scale_f32 v111, s[54:55], v110, v110, 1.0
	v_rcp_f32_e32 v112, v111
	v_div_scale_f32 v113, vcc, 1.0, v110, 1.0
	v_fma_f32 v115, -v111, v112, 1.0
	v_fmac_f32_e32 v112, v115, v112
	v_mul_f32_e32 v114, v113, v112
	v_fma_f32 v115, -v111, v114, v113
	v_fmac_f32_e32 v114, v115, v112
	v_fma_f32 v115, -v111, v114, v113
	v_div_fmas_f32 v115, v115, v112, v114
	v_div_fixup_f32 v115, v115, v110, 1.0
	v_mul_f32_e32 v122, v86, v115
	v_mul_f32_e32 v108, 0xbfb8aa3b, v87
	v_exp_f32_e32 v109, v108
	s_nop 0
	v_add_f32_e32 v110, 1.0, v109
	v_div_scale_f32 v111, s[54:55], v110, v110, 1.0
	v_rcp_f32_e32 v112, v111
	v_div_scale_f32 v113, vcc, 1.0, v110, 1.0
	v_fma_f32 v115, -v111, v112, 1.0
	v_fmac_f32_e32 v112, v115, v112
	v_mul_f32_e32 v114, v113, v112
	v_fma_f32 v115, -v111, v114, v113
	v_fmac_f32_e32 v114, v115, v112
	v_fma_f32 v115, -v111, v114, v113
	v_div_fmas_f32 v115, v115, v112, v114
	v_div_fixup_f32 v115, v115, v110, 1.0
	v_mul_f32_e32 v123, v87, v115
	v_cvt_pk_bf16_f32 v124, v120, v121
	v_cvt_pk_bf16_f32 v125, v122, v123
	global_store_dwordx2 v196, v[124:125], s[44:45] offset:1024
	v_add_f32_e32 v100, v88, v89
	v_add_f32_e32 v100, v100, v90
	v_add_f32_e32 v100, v100, v91
	v_add_f32_e32 v100, v100, v92
	v_add_f32_e32 v100, v100, v93
	v_add_f32_e32 v100, v100, v94
	v_add_f32_e32 v100, v100, v95
	v_add_f32_e32 v100, v100, v96
	v_add_f32_e32 v100, v100, v97
	v_add_f32_e32 v100, v100, v98
	v_add_f32_e32 v100, v100, v99
	s_nop 1
	v_add_f32_dpp v100, v100, v100 row_shr:1 row_mask:0xf bank_mask:0xf bound_ctrl:1
	s_nop 1
	v_add_f32_dpp v100, v100, v100 row_shr:2 row_mask:0xf bank_mask:0xf bound_ctrl:1
	s_nop 1
	v_add_f32_dpp v100, v100, v100 row_shr:4 row_mask:0xf bank_mask:0xf bound_ctrl:1
	s_nop 1
	v_add_f32_dpp v100, v100, v100 row_shr:8 row_mask:0xf bank_mask:0xf bound_ctrl:1
	s_nop 1
	v_add_f32_dpp v100, v100, v100 row_bcast:15 row_mask:0xa bank_mask:0xf
	s_nop 1
	v_add_f32_dpp v100, v100, v100 row_bcast:31 row_mask:0xc bank_mask:0xf
	s_nop 0
	v_readlane_b32 s53, v100, 63
	s_nop 1
	v_mov_b32_e32 v101, s53
	v_fmac_f32_e32 v88, 0xbaaaaaab, v101
	v_fmac_f32_e32 v89, 0xbaaaaaab, v101
	v_fmac_f32_e32 v90, 0xbaaaaaab, v101
	v_fmac_f32_e32 v91, 0xbaaaaaab, v101
	v_fmac_f32_e32 v92, 0xbaaaaaab, v101
	v_fmac_f32_e32 v93, 0xbaaaaaab, v101
	v_fmac_f32_e32 v94, 0xbaaaaaab, v101
	v_fmac_f32_e32 v95, 0xbaaaaaab, v101
	v_fmac_f32_e32 v96, 0xbaaaaaab, v101
	v_fmac_f32_e32 v97, 0xbaaaaaab, v101
	v_fmac_f32_e32 v98, 0xbaaaaaab, v101
	v_fmac_f32_e32 v99, 0xbaaaaaab, v101
	v_mul_f32_e32 v102, v88, v88
	v_fmac_f32_e32 v102, v89, v89
	v_fmac_f32_e32 v102, v90, v90
	v_fmac_f32_e32 v102, v91, v91
	v_fmac_f32_e32 v102, v92, v92
	v_fmac_f32_e32 v102, v93, v93
	v_fmac_f32_e32 v102, v94, v94
	v_fmac_f32_e32 v102, v95, v95
	v_fmac_f32_e32 v102, v96, v96
	v_fmac_f32_e32 v102, v97, v97
	v_fmac_f32_e32 v102, v98, v98
	v_fmac_f32_e32 v102, v99, v99
	s_nop 1
	v_add_f32_dpp v102, v102, v102 row_shr:1 row_mask:0xf bank_mask:0xf bound_ctrl:1
	s_nop 1
	v_add_f32_dpp v102, v102, v102 row_shr:2 row_mask:0xf bank_mask:0xf bound_ctrl:1
	s_nop 1
	v_add_f32_dpp v102, v102, v102 row_shr:4 row_mask:0xf bank_mask:0xf bound_ctrl:1
	s_nop 1
	v_add_f32_dpp v102, v102, v102 row_shr:8 row_mask:0xf bank_mask:0xf bound_ctrl:1
	s_nop 1
	v_add_f32_dpp v102, v102, v102 row_bcast:15 row_mask:0xa bank_mask:0xf
	s_nop 1
	v_add_f32_dpp v102, v102, v102 row_bcast:31 row_mask:0xc bank_mask:0xf
	s_nop 0
	v_readlane_b32 s53, v102, 63
	s_nop 1
	v_mov_b32_e32 v101, s53
	v_fmamk_f32 v101, v101, 0x3aaaaaab, v197
	v_rsq_f32_e32 v103, v101
	s_nop 0
	v_mul_f32_e32 v88, v88, v103
	v_mul_f32_e32 v89, v89, v103
	v_mul_f32_e32 v90, v90, v103
	v_mul_f32_e32 v91, v91, v103
	v_mul_f32_e32 v92, v92, v103
	v_mul_f32_e32 v93, v93, v103
	v_mul_f32_e32 v94, v94, v103
	v_mul_f32_e32 v95, v95, v103
	v_mul_f32_e32 v96, v96, v103
	v_mul_f32_e32 v97, v97, v103
	v_mul_f32_e32 v98, v98, v103
	v_mul_f32_e32 v99, v99, v103
	v_fma_f32 v88, v222, v88, v234
	v_fma_f32 v89, v223, v89, v235
	v_fma_f32 v90, v224, v90, v236
	v_fma_f32 v91, v225, v91, v237
	v_fma_f32 v92, v226, v92, v238
	v_fma_f32 v93, v227, v93, v239
	v_fma_f32 v94, v228, v94, v240
	v_fma_f32 v95, v229, v95, v241
	v_fma_f32 v96, v230, v96, v242
	v_fma_f32 v97, v231, v97, v243
	v_fma_f32 v98, v232, v98, v244
	v_fma_f32 v99, v233, v99, v245
	s_lshl_b32 s52, s41, 11
	s_add_i32 s52, s52, 14336
	v_add_u32_e32 v196, s52, v3
	v_mul_f32_e32 v108, 0xbfb8aa3b, v88
	v_exp_f32_e32 v109, v108
	s_nop 0
	v_add_f32_e32 v110, 1.0, v109
	v_div_scale_f32 v111, s[54:55], v110, v110, 1.0
	v_rcp_f32_e32 v112, v111
	v_div_scale_f32 v113, vcc, 1.0, v110, 1.0
	v_fma_f32 v115, -v111, v112, 1.0
	v_fmac_f32_e32 v112, v115, v112
	v_mul_f32_e32 v114, v113, v112
	v_fma_f32 v115, -v111, v114, v113
	v_fmac_f32_e32 v114, v115, v112
	v_fma_f32 v115, -v111, v114, v113
	v_div_fmas_f32 v115, v115, v112, v114
	v_div_fixup_f32 v115, v115, v110, 1.0
	v_mul_f32_e32 v120, v88, v115
	v_mul_f32_e32 v108, 0xbfb8aa3b, v89
	v_exp_f32_e32 v109, v108
	s_nop 0
	v_add_f32_e32 v110, 1.0, v109
	v_div_scale_f32 v111, s[54:55], v110, v110, 1.0
	v_rcp_f32_e32 v112, v111
	v_div_scale_f32 v113, vcc, 1.0, v110, 1.0
	v_fma_f32 v115, -v111, v112, 1.0
	v_fmac_f32_e32 v112, v115, v112
	v_mul_f32_e32 v114, v113, v112
	v_fma_f32 v115, -v111, v114, v113
	v_fmac_f32_e32 v114, v115, v112
	v_fma_f32 v115, -v111, v114, v113
	v_div_fmas_f32 v115, v115, v112, v114
	v_div_fixup_f32 v115, v115, v110, 1.0
	v_mul_f32_e32 v121, v89, v115
	v_mul_f32_e32 v108, 0xbfb8aa3b, v90
	v_exp_f32_e32 v109, v108
	s_nop 0
	v_add_f32_e32 v110, 1.0, v109
	v_div_scale_f32 v111, s[54:55], v110, v110, 1.0
	v_rcp_f32_e32 v112, v111
	v_div_scale_f32 v113, vcc, 1.0, v110, 1.0
	v_fma_f32 v115, -v111, v112, 1.0
	v_fmac_f32_e32 v112, v115, v112
	v_mul_f32_e32 v114, v113, v112
	v_fma_f32 v115, -v111, v114, v113
	v_fmac_f32_e32 v114, v115, v112
	v_fma_f32 v115, -v111, v114, v113
	v_div_fmas_f32 v115, v115, v112, v114
	v_div_fixup_f32 v115, v115, v110, 1.0
	v_mul_f32_e32 v122, v90, v115
	v_mul_f32_e32 v108, 0xbfb8aa3b, v91
	v_exp_f32_e32 v109, v108
	s_nop 0
	v_add_f32_e32 v110, 1.0, v109
	v_div_scale_f32 v111, s[54:55], v110, v110, 1.0
	v_rcp_f32_e32 v112, v111
	v_div_scale_f32 v113, vcc, 1.0, v110, 1.0
	v_fma_f32 v115, -v111, v112, 1.0
	v_fmac_f32_e32 v112, v115, v112
	v_mul_f32_e32 v114, v113, v112
	v_fma_f32 v115, -v111, v114, v113
	v_fmac_f32_e32 v114, v115, v112
	v_fma_f32 v115, -v111, v114, v113
	v_div_fmas_f32 v115, v115, v112, v114
	v_div_fixup_f32 v115, v115, v110, 1.0
	v_mul_f32_e32 v123, v91, v115
	v_cvt_pk_bf16_f32 v124, v120, v121
	v_cvt_pk_bf16_f32 v125, v122, v123
	global_store_dwordx2 v196, v[124:125], s[44:45]
	v_mul_f32_e32 v108, 0xbfb8aa3b, v92
	v_exp_f32_e32 v109, v108
	s_nop 0
	v_add_f32_e32 v110, 1.0, v109
	v_div_scale_f32 v111, s[54:55], v110, v110, 1.0
	v_rcp_f32_e32 v112, v111
	v_div_scale_f32 v113, vcc, 1.0, v110, 1.0
	v_fma_f32 v115, -v111, v112, 1.0
	v_fmac_f32_e32 v112, v115, v112
	v_mul_f32_e32 v114, v113, v112
	v_fma_f32 v115, -v111, v114, v113
	v_fmac_f32_e32 v114, v115, v112
	v_fma_f32 v115, -v111, v114, v113
	v_div_fmas_f32 v115, v115, v112, v114
	v_div_fixup_f32 v115, v115, v110, 1.0
	v_mul_f32_e32 v120, v92, v115
	v_mul_f32_e32 v108, 0xbfb8aa3b, v93
	v_exp_f32_e32 v109, v108
	s_nop 0
	v_add_f32_e32 v110, 1.0, v109
	v_div_scale_f32 v111, s[54:55], v110, v110, 1.0
	v_rcp_f32_e32 v112, v111
	v_div_scale_f32 v113, vcc, 1.0, v110, 1.0
	v_fma_f32 v115, -v111, v112, 1.0
	v_fmac_f32_e32 v112, v115, v112
	v_mul_f32_e32 v114, v113, v112
	v_fma_f32 v115, -v111, v114, v113
	v_fmac_f32_e32 v114, v115, v112
	v_fma_f32 v115, -v111, v114, v113
	v_div_fmas_f32 v115, v115, v112, v114
	v_div_fixup_f32 v115, v115, v110, 1.0
	v_mul_f32_e32 v121, v93, v115
	v_mul_f32_e32 v108, 0xbfb8aa3b, v94
	v_exp_f32_e32 v109, v108
	s_nop 0
	v_add_f32_e32 v110, 1.0, v109
	v_div_scale_f32 v111, s[54:55], v110, v110, 1.0
	v_rcp_f32_e32 v112, v111
	v_div_scale_f32 v113, vcc, 1.0, v110, 1.0
	v_fma_f32 v115, -v111, v112, 1.0
	v_fmac_f32_e32 v112, v115, v112
	v_mul_f32_e32 v114, v113, v112
	v_fma_f32 v115, -v111, v114, v113
	v_fmac_f32_e32 v114, v115, v112
	v_fma_f32 v115, -v111, v114, v113
	v_div_fmas_f32 v115, v115, v112, v114
	v_div_fixup_f32 v115, v115, v110, 1.0
	v_mul_f32_e32 v122, v94, v115
	v_mul_f32_e32 v108, 0xbfb8aa3b, v95
	v_exp_f32_e32 v109, v108
	s_nop 0
	v_add_f32_e32 v110, 1.0, v109
	v_div_scale_f32 v111, s[54:55], v110, v110, 1.0
	v_rcp_f32_e32 v112, v111
	v_div_scale_f32 v113, vcc, 1.0, v110, 1.0
	v_fma_f32 v115, -v111, v112, 1.0
	v_fmac_f32_e32 v112, v115, v112
	v_mul_f32_e32 v114, v113, v112
	v_fma_f32 v115, -v111, v114, v113
	v_fmac_f32_e32 v114, v115, v112
	v_fma_f32 v115, -v111, v114, v113
	v_div_fmas_f32 v115, v115, v112, v114
	v_div_fixup_f32 v115, v115, v110, 1.0
	v_mul_f32_e32 v123, v95, v115
	v_cvt_pk_bf16_f32 v124, v120, v121
	v_cvt_pk_bf16_f32 v125, v122, v123
	global_store_dwordx2 v196, v[124:125], s[44:45] offset:512
	v_mul_f32_e32 v108, 0xbfb8aa3b, v96
	v_exp_f32_e32 v109, v108
	s_nop 0
	v_add_f32_e32 v110, 1.0, v109
	v_div_scale_f32 v111, s[54:55], v110, v110, 1.0
	v_rcp_f32_e32 v112, v111
	v_div_scale_f32 v113, vcc, 1.0, v110, 1.0
	v_fma_f32 v115, -v111, v112, 1.0
	v_fmac_f32_e32 v112, v115, v112
	v_mul_f32_e32 v114, v113, v112
	v_fma_f32 v115, -v111, v114, v113
	v_fmac_f32_e32 v114, v115, v112
	v_fma_f32 v115, -v111, v114, v113
	v_div_fmas_f32 v115, v115, v112, v114
	v_div_fixup_f32 v115, v115, v110, 1.0
	v_mul_f32_e32 v120, v96, v115
	v_mul_f32_e32 v108, 0xbfb8aa3b, v97
	v_exp_f32_e32 v109, v108
	s_nop 0
	v_add_f32_e32 v110, 1.0, v109
	v_div_scale_f32 v111, s[54:55], v110, v110, 1.0
	v_rcp_f32_e32 v112, v111
	v_div_scale_f32 v113, vcc, 1.0, v110, 1.0
	v_fma_f32 v115, -v111, v112, 1.0
	v_fmac_f32_e32 v112, v115, v112
	v_mul_f32_e32 v114, v113, v112
	v_fma_f32 v115, -v111, v114, v113
	v_fmac_f32_e32 v114, v115, v112
	v_fma_f32 v115, -v111, v114, v113
	v_div_fmas_f32 v115, v115, v112, v114
	v_div_fixup_f32 v115, v115, v110, 1.0
	v_mul_f32_e32 v121, v97, v115
	v_mul_f32_e32 v108, 0xbfb8aa3b, v98
	v_exp_f32_e32 v109, v108
	s_nop 0
	v_add_f32_e32 v110, 1.0, v109
	v_div_scale_f32 v111, s[54:55], v110, v110, 1.0
	v_rcp_f32_e32 v112, v111
	v_div_scale_f32 v113, vcc, 1.0, v110, 1.0
	v_fma_f32 v115, -v111, v112, 1.0
	v_fmac_f32_e32 v112, v115, v112
	v_mul_f32_e32 v114, v113, v112
	v_fma_f32 v115, -v111, v114, v113
	v_fmac_f32_e32 v114, v115, v112
	v_fma_f32 v115, -v111, v114, v113
	v_div_fmas_f32 v115, v115, v112, v114
	v_div_fixup_f32 v115, v115, v110, 1.0
	v_mul_f32_e32 v122, v98, v115
	v_mul_f32_e32 v108, 0xbfb8aa3b, v99
	v_exp_f32_e32 v109, v108
	s_nop 0
	v_add_f32_e32 v110, 1.0, v109
	v_div_scale_f32 v111, s[54:55], v110, v110, 1.0
	v_rcp_f32_e32 v112, v111
	v_div_scale_f32 v113, vcc, 1.0, v110, 1.0
	v_fma_f32 v115, -v111, v112, 1.0
	v_fmac_f32_e32 v112, v115, v112
	v_mul_f32_e32 v114, v113, v112
	v_fma_f32 v115, -v111, v114, v113
	v_fmac_f32_e32 v114, v115, v112
	v_fma_f32 v115, -v111, v114, v113
	v_div_fmas_f32 v115, v115, v112, v114
	v_div_fixup_f32 v115, v115, v110, 1.0
	v_mul_f32_e32 v123, v99, v115
	v_cvt_pk_bf16_f32 v124, v120, v121
	v_cvt_pk_bf16_f32 v125, v122, v123
	global_store_dwordx2 v196, v[124:125], s[44:45] offset:1024
	s_waitcnt vmcnt(0)
